# MLA: V^T tile rows of 144 B with each lane half's two 4-key groups adjacent -> one ds_read_b128 per V fragment instead of two ds_read_b64
# speedup vs baseline: 1.0193x; 1.0037x over previous
.LBB0_1885:
	s_or_b64 exec, exec, s[0:1]
	v_readlane_b32 s0, v250, 2
	v_readlane_b32 s1, v250, 3
	v_readlane_b32 s86, v250, 1
	s_andn2_b64 vcc, exec, s[0:1]
	s_waitcnt vmcnt(0) lgkmcnt(0)
	s_barrier
	s_cbranch_vccnz .LBB0_1920
	v_and_b32_e32 v234, 31, v0
	v_bfe_u32 v235, v0, 5, 1
	v_mul_u32_u24_e32 v220, 0xd0, v234
	v_lshl_add_u32 v220, v235, 4, v220
	v_mul_u32_u24_e32 v221, 0x90, v234
	v_lshl_add_u32 v221, v235, 4, v221
	v_add_u32_e32 v221, 0xd000, v221
	v_lshl_or_b32 v1, s87, 5, v234
	v_mul_u32_u24_e32 v237, 0xc0, v1
	v_lshl_add_u32 v237, v235, 4, v237
	v_lshlrev_b32_e32 v236, 10, v1
	v_lshl_add_u32 v236, v235, 3, v236
	v_lshlrev_b32_e32 v226, 4, v0
	v_add_u32_e32 v227, 0x2000, v226
	v_add_u32_e32 v228, 0x4000, v226
	v_lshrrev_b32_e32 v234, 3, v0
	v_and_b32_e32 v235, 7, v0
	v_mul_u32_u24_e32 v229, 0x2200, v234
	v_lshl_add_u32 v229, v235, 4, v229
	v_mul_u32_u24_e32 v225, 0x90, v234
	v_lshrrev_b32_e32 v1, 1, v235
	v_lshl_add_u32 v225, v1, 5, v225
	v_and_b32_e32 v1, 1, v235
	v_lshl_add_u32 v225, v1, 3, v225
	v_add_u32_e32 v225, 0xd000, v225
	s_mov_b32 s17, 0xaaab
	s_movk_i32 s18, 0xd0
	v_mov_b32_e32 v234, v0
	v_mul_lo_u32 v235, v234, s17
	v_lshrrev_b32_e32 v235, 19, v235
	v_mul_u32_u24_e32 v1, 12, v235
	v_sub_u32_e32 v234, v234, v1
	v_lshrrev_b32_e32 v1, 6, v235
	v_and_b32_e32 v235, 63, v235
	v_mul_u32_u24_e32 v1, 0x3400, v1
	v_mad_u32_u24 v1, v235, s18, v1
	v_lshl_add_u32 v222, v234, 4, v1
	v_add_u32_e32 v234, 512, v0
	v_mul_lo_u32 v235, v234, s17
	v_lshrrev_b32_e32 v235, 19, v235
	v_mul_u32_u24_e32 v1, 12, v235
	v_sub_u32_e32 v234, v234, v1
	v_lshrrev_b32_e32 v1, 6, v235
	v_and_b32_e32 v235, 63, v235
	v_mul_u32_u24_e32 v1, 0x3400, v1
	v_mad_u32_u24 v1, v235, s18, v1
	v_lshl_add_u32 v223, v234, 4, v1
	v_add_u32_e32 v234, 1024, v0
	v_mul_lo_u32 v235, v234, s17
	v_lshrrev_b32_e32 v235, 19, v235
	v_mul_u32_u24_e32 v1, 12, v235
	v_sub_u32_e32 v234, v234, v1
	v_lshrrev_b32_e32 v1, 6, v235
	v_and_b32_e32 v235, 63, v235
	v_mul_u32_u24_e32 v1, 0x3400, v1
	v_mad_u32_u24 v1, v235, s18, v1
	v_lshl_add_u32 v224, v234, 4, v1
	v_mov_b32_e32 v234, 0
	v_mov_b32_e32 v235, 0x186a0
	ds_write_b32 v235, v234
.Lmla_restart:
	s_lshr_b32 s17, s2, 4
	s_and_b32 s18, s2, 15
	s_mul_i32 s19, s17, 0xcc000
	s_add_u32 s4, s78, s19
	s_addc_u32 s5, s79, 0
	s_mul_i32 s19, s17, 0x88000
	s_add_u32 s19, s19, 0x1a00000
	s_add_u32 s10, s78, s19
	s_addc_u32 s11, s79, 0
	s_lshl_b32 s19, s17, 12
	s_lshl_b32 s20, s18, 8
	s_add_u32 s19, s19, s20
	s_mul_i32 s19, s19, 0xc0
	s_add_u32 s19, s19, 0x1400000
	s_add_u32 s12, s80, s19
	s_addc_u32 s13, s81, 0
	s_lshr_b32 s19, s17, 3
	s_lshl_b32 s19, s19, 12
	s_add_u32 s19, s19, s20
	s_lshl_b32 s19, s19, 10
	s_and_b32 s21, s17, 7
	s_lshl_b32 s21, s21, 7
	s_add_u32 s19, s19, s21
	s_add_u32 s19, s19, 0x7900000
	s_add_u32 s14, s80, s19
	s_addc_u32 s15, s81, 0
	global_load_dwordx4 v[98:101], v237, s[12:13] offset:0
	global_load_dwordx4 v[102:105], v237, s[12:13] offset:32
	global_load_dwordx4 v[106:109], v237, s[12:13] offset:64
	global_load_dwordx4 v[110:113], v237, s[12:13] offset:96
	global_load_dwordx4 v[114:117], v237, s[12:13] offset:128
	global_load_dwordx4 v[118:121], v237, s[12:13] offset:160
	global_load_dwordx4 v[34:37], v226, s[4:5]
	global_load_dwordx4 v[38:41], v227, s[4:5]
	global_load_dwordx4 v[42:45], v228, s[4:5]
	global_load_dwordx4 v[46:49], v229, s[10:11]
	s_add_u32 s4, s4, 0x6000
	s_addc_u32 s5, s5, 0
	global_load_dwordx4 v[50:53], v226, s[4:5]
	global_load_dwordx4 v[54:57], v227, s[4:5]
	global_load_dwordx4 v[58:61], v228, s[4:5]
	global_load_dwordx4 v[62:65], v229, s[10:11] offset:128
	global_load_dwordx4 v[216:219], v229, s[10:11] offset:256
	s_add_u32 s4, s4, 0x6000
	s_addc_u32 s5, s5, 0
	s_add_u32 s10, s10, 0x180
	s_addc_u32 s11, s11, 0
	v_mov_b32_e32 v2, 0
	v_mov_b32_e32 v3, 0
	v_mov_b32_e32 v4, 0
	v_mov_b32_e32 v5, 0
	v_mov_b32_e32 v6, 0
	v_mov_b32_e32 v7, 0
	v_mov_b32_e32 v8, 0
	v_mov_b32_e32 v9, 0
	v_mov_b32_e32 v10, 0
	v_mov_b32_e32 v11, 0
	v_mov_b32_e32 v12, 0
	v_mov_b32_e32 v13, 0
	v_mov_b32_e32 v14, 0
	v_mov_b32_e32 v15, 0
	v_mov_b32_e32 v16, 0
	v_mov_b32_e32 v17, 0
	v_mov_b32_e32 v18, 0
	v_mov_b32_e32 v19, 0
	v_mov_b32_e32 v20, 0
	v_mov_b32_e32 v21, 0
	v_mov_b32_e32 v22, 0
	v_mov_b32_e32 v23, 0
	v_mov_b32_e32 v24, 0
	v_mov_b32_e32 v25, 0
	v_mov_b32_e32 v26, 0
	v_mov_b32_e32 v27, 0
	v_mov_b32_e32 v28, 0
	v_mov_b32_e32 v29, 0
	v_mov_b32_e32 v30, 0
	v_mov_b32_e32 v31, 0
	v_mov_b32_e32 v32, 0
	v_mov_b32_e32 v33, 0
	v_mov_b32_e32 v122, 0
	v_mov_b32_e32 v123, 0
	v_mov_b32_e32 v124, 0
	v_mov_b32_e32 v125, 0
	v_mov_b32_e32 v126, 0
	v_mov_b32_e32 v127, 0
	v_mov_b32_e32 v128, 0
	v_mov_b32_e32 v129, 0
	v_mov_b32_e32 v130, 0
	v_mov_b32_e32 v131, 0
	v_mov_b32_e32 v132, 0
	v_mov_b32_e32 v133, 0
	v_mov_b32_e32 v134, 0
	v_mov_b32_e32 v135, 0
	v_mov_b32_e32 v136, 0
	v_mov_b32_e32 v137, 0
	v_mov_b32_e32 v230, 0
	v_mov_b32_e32 v231, 0
	v_mov_b32_e32 v232, 0
	s_waitcnt vmcnt(5)
	ds_write_b128 v222, v[34:37]
	ds_write_b128 v223, v[38:41]
	ds_write_b128 v224, v[42:45]
	ds_write_b64 v225, v[46:47]
	ds_write_b64 v225, v[48:49] offset:16
	s_waitcnt vmcnt(1)
	ds_write_b128 v222, v[50:53] offset:26624
	ds_write_b128 v223, v[54:57] offset:26624
	ds_write_b128 v224, v[58:61] offset:26624
	ds_write_b64 v225, v[62:63] offset:9216
	ds_write_b64 v225, v[64:65] offset:9232
	s_waitcnt lgkmcnt(0)
	s_barrier

.Lmla_loop:
	v_exp_f32_e32 v34, v34
	v_exp_f32_e32 v35, v35
	v_exp_f32_e32 v36, v36
	s_waitcnt lgkmcnt(4)
	v_mfma_f32_32x32x16_bf16 v[66:81], v[138:141], v[98:101], v[122:137]
	ds_read_b128 v[138:141], v220 offset:13408
	v_exp_f32_e32 v37, v37
	v_add_f32_e32 v231, v231, v34
	v_add_f32_e32 v232, v232, v35
	v_exp_f32_e32 v38, v38
	v_mfma_f32_32x32x16_bf16 v[82:97], v[142:145], v[98:101], v[122:137]
	ds_read_b128 v[142:145], v220 offset:20064
	v_exp_f32_e32 v39, v39
	v_add_f32_e32 v231, v231, v36
	v_add_f32_e32 v232, v232, v37
	s_waitcnt lgkmcnt(4)
	v_mfma_f32_32x32x16_bf16 v[66:81], v[146:149], v[102:105], v[66:81]
	ds_read_b128 v[146:149], v220 offset:13440
	global_load_dwordx4 v[200:203], v226, s[4:5]
	global_load_dwordx4 v[204:207], v227, s[4:5]
	global_load_dwordx4 v[208:211], v228, s[4:5]
	s_add_u32 s4, s4, 0x6000
	s_addc_u32 s5, s5, 0
	global_load_dwordx4 v[212:215], v229, s[10:11]
	s_add_u32 s10, s10, 0x80
	s_addc_u32 s11, s11, 0
	v_exp_f32_e32 v40, v40
	v_exp_f32_e32 v41, v41
	v_add_f32_e32 v231, v231, v38
	v_add_f32_e32 v232, v232, v39
	v_mfma_f32_32x32x16_bf16 v[82:97], v[150:153], v[102:105], v[82:97]
	ds_read_b128 v[150:153], v220 offset:20096
	v_add_f32_e32 v231, v231, v40
	v_add_f32_e32 v232, v232, v41
	v_cvt_pk_bf16_f32 v34, v34, v35
	v_cvt_pk_bf16_f32 v35, v36, v37
	v_cvt_pk_bf16_f32 v36, v38, v39
	s_waitcnt lgkmcnt(4)
	v_mfma_f32_32x32x16_bf16 v[66:81], v[154:157], v[106:109], v[66:81]
	ds_read_b128 v[154:157], v220 offset:13472
	v_cvt_pk_bf16_f32 v37, v40, v41
	v_exp_f32_e32 v42, v42
	v_exp_f32_e32 v43, v43
	v_mfma_f32_32x32x16_bf16 v[82:97], v[158:161], v[106:109], v[82:97]
	ds_read_b128 v[158:161], v220 offset:20128
	v_exp_f32_e32 v44, v44
	v_exp_f32_e32 v45, v45
	v_add_f32_e32 v231, v231, v42
	v_add_f32_e32 v232, v232, v43
	s_waitcnt lgkmcnt(4)
	v_mfma_f32_32x32x16_bf16 v[66:81], v[138:141], v[110:113], v[66:81]
	ds_read_b128 v[162:165], v221 offset:0
	v_exp_f32_e32 v46, v46
	v_exp_f32_e32 v47, v47
	v_add_f32_e32 v231, v231, v44
	v_mfma_f32_32x32x16_bf16 v[82:97], v[142:145], v[110:113], v[82:97]
	ds_read_b128 v[166:169], v221 offset:4608
	v_add_f32_e32 v232, v232, v45
	v_exp_f32_e32 v48, v48
	v_exp_f32_e32 v49, v49
	s_waitcnt lgkmcnt(4)
	v_mfma_f32_32x32x16_bf16 v[66:81], v[146:149], v[114:117], v[66:81]
	ds_read_b128 v[170:173], v221 offset:32
	v_add_f32_e32 v231, v231, v46
	v_add_f32_e32 v232, v232, v47
	v_add_f32_e32 v231, v231, v48
	v_add_f32_e32 v232, v232, v49
	v_cvt_pk_bf16_f32 v42, v42, v43
	v_cvt_pk_bf16_f32 v43, v44, v45
	v_mfma_f32_32x32x16_bf16 v[82:97], v[150:153], v[114:117], v[82:97]
	ds_read_b128 v[174:177], v221 offset:4640
	v_cvt_pk_bf16_f32 v44, v46, v47
	v_cvt_pk_bf16_f32 v45, v48, v49
	v_exp_f32_e32 v50, v50
	v_exp_f32_e32 v51, v51
	s_waitcnt lgkmcnt(4)
	v_mfma_f32_32x32x16_bf16 v[66:81], v[154:157], v[118:121], v[66:81]
	ds_read_b128 v[180:183], v221 offset:64
	v_exp_f32_e32 v52, v52
	v_exp_f32_e32 v53, v53
	v_mfma_f32_32x32x16_bf16 v[82:97], v[158:161], v[118:121], v[82:97]
	ds_read_b128 v[184:187], v221 offset:4672
	v_add_f32_e32 v231, v231, v50
	v_add_f32_e32 v232, v232, v51
	v_exp_f32_e32 v54, v54
	v_exp_f32_e32 v55, v55
	s_waitcnt lgkmcnt(4)
	v_mfma_f32_32x32x16_bf16 v[2:17], v[162:165], v[34:37], v[2:17]
	ds_read_b128 v[188:191], v221 offset:96
	v_add_f32_e32 v231, v231, v52
	v_add_f32_e32 v232, v232, v53
	v_exp_f32_e32 v56, v56
	v_exp_f32_e32 v57, v57
	v_mfma_f32_32x32x16_bf16 v[18:33], v[166:169], v[34:37], v[18:33]
	ds_read_b128 v[192:195], v221 offset:4704
	v_add_f32_e32 v231, v231, v54
	v_add_f32_e32 v232, v232, v55
	v_add_f32_e32 v231, v231, v56
	v_add_f32_e32 v232, v232, v57
	s_waitcnt lgkmcnt(4)
	v_mfma_f32_32x32x16_bf16 v[2:17], v[170:173], v[42:45], v[2:17]
	v_cvt_pk_bf16_f32 v50, v50, v51
	v_cvt_pk_bf16_f32 v51, v52, v53
	v_cvt_pk_bf16_f32 v52, v54, v55
	v_cvt_pk_bf16_f32 v53, v56, v57
	v_exp_f32_e32 v58, v58
	v_mfma_f32_32x32x16_bf16 v[18:33], v[174:177], v[42:45], v[18:33]
	s_waitcnt vmcnt(4)
	ds_write_b64 v225, v[216:217] offset:18432
	ds_write_b64 v225, v[218:219] offset:18448
	v_exp_f32_e32 v59, v59
	v_exp_f32_e32 v60, v60
	v_exp_f32_e32 v61, v61
	s_waitcnt lgkmcnt(4)
	v_mfma_f32_32x32x16_bf16 v[2:17], v[180:183], v[50:53], v[2:17]
	v_add_f32_e32 v231, v231, v58
	v_add_f32_e32 v232, v232, v59
	v_exp_f32_e32 v62, v62
	v_mfma_f32_32x32x16_bf16 v[18:33], v[184:187], v[50:53], v[18:33]
	v_exp_f32_e32 v63, v63
	v_add_f32_e32 v231, v231, v60
	v_add_f32_e32 v232, v232, v61
	v_exp_f32_e32 v64, v64
	v_exp_f32_e32 v65, v65
	v_add_f32_e32 v231, v231, v62
	v_add_f32_e32 v232, v232, v63
	v_add_f32_e32 v231, v231, v64
	v_add_f32_e32 v232, v232, v65
	v_cvt_pk_bf16_f32 v58, v58, v59
	v_cvt_pk_bf16_f32 v59, v60, v61
	v_cvt_pk_bf16_f32 v60, v62, v63
	v_cvt_pk_bf16_f32 v61, v64, v65
	s_waitcnt lgkmcnt(2)
	s_nop 0
	v_mfma_f32_32x32x16_bf16 v[2:17], v[188:191], v[58:61], v[2:17]
	v_mfma_f32_32x32x16_bf16 v[18:33], v[192:195], v[58:61], v[18:33]
	ds_read_b128 v[138:141], v220 offset:26624
	ds_read_b128 v[142:145], v220 offset:33280
	ds_read_b128 v[146:149], v220 offset:26656
	ds_read_b128 v[150:153], v220 offset:33312
	ds_read_b128 v[154:157], v220 offset:26688
	ds_read_b128 v[158:161], v220 offset:33344
	s_waitcnt lgkmcnt(6)
	s_barrier
	v_exp_f32_e32 v66, v66
	v_exp_f32_e32 v67, v67
	v_exp_f32_e32 v68, v68
	s_waitcnt lgkmcnt(4)
	v_mfma_f32_32x32x16_bf16 v[34:49], v[138:141], v[98:101], v[122:137]
	ds_read_b128 v[138:141], v220 offset:26720
	v_exp_f32_e32 v69, v69
	v_add_f32_e32 v231, v231, v66
	v_add_f32_e32 v232, v232, v67
	v_exp_f32_e32 v70, v70
	v_mfma_f32_32x32x16_bf16 v[50:65], v[142:145], v[98:101], v[122:137]
	ds_read_b128 v[142:145], v220 offset:33376
	v_exp_f32_e32 v71, v71
	v_add_f32_e32 v231, v231, v68
	v_add_f32_e32 v232, v232, v69
	s_waitcnt lgkmcnt(4)
	v_mfma_f32_32x32x16_bf16 v[34:49], v[146:149], v[102:105], v[34:49]
	ds_read_b128 v[146:149], v220 offset:26752
	global_load_dwordx4 v[216:219], v229, s[10:11]
	s_add_u32 s10, s10, 0x80
	s_addc_u32 s11, s11, 0
	v_exp_f32_e32 v72, v72
	v_exp_f32_e32 v73, v73
	v_add_f32_e32 v231, v231, v70
	v_add_f32_e32 v232, v232, v71
	v_mfma_f32_32x32x16_bf16 v[50:65], v[150:153], v[102:105], v[50:65]
	ds_read_b128 v[150:153], v220 offset:33408
	v_add_f32_e32 v231, v231, v72
	v_add_f32_e32 v232, v232, v73
	v_cvt_pk_bf16_f32 v66, v66, v67
	v_cvt_pk_bf16_f32 v67, v68, v69
	v_cvt_pk_bf16_f32 v68, v70, v71
	s_waitcnt lgkmcnt(4)
	v_mfma_f32_32x32x16_bf16 v[34:49], v[154:157], v[106:109], v[34:49]
	ds_read_b128 v[154:157], v220 offset:26784
	v_cvt_pk_bf16_f32 v69, v72, v73
	v_exp_f32_e32 v74, v74
	v_exp_f32_e32 v75, v75
	v_mfma_f32_32x32x16_bf16 v[50:65], v[158:161], v[106:109], v[50:65]
	ds_read_b128 v[158:161], v220 offset:33440
	v_exp_f32_e32 v76, v76
	v_exp_f32_e32 v77, v77
	v_add_f32_e32 v231, v231, v74
	v_add_f32_e32 v232, v232, v75
	s_waitcnt lgkmcnt(4)
	v_mfma_f32_32x32x16_bf16 v[34:49], v[138:141], v[110:113], v[34:49]
	ds_read_b128 v[162:165], v221 offset:9216
	v_exp_f32_e32 v78, v78
	v_exp_f32_e32 v79, v79
	v_add_f32_e32 v231, v231, v76
	v_mfma_f32_32x32x16_bf16 v[50:65], v[142:145], v[110:113], v[50:65]
	ds_read_b128 v[166:169], v221 offset:13824
	v_add_f32_e32 v232, v232, v77
	v_exp_f32_e32 v80, v80
	v_exp_f32_e32 v81, v81
	s_waitcnt lgkmcnt(4)
	v_mfma_f32_32x32x16_bf16 v[34:49], v[146:149], v[114:117], v[34:49]
	ds_read_b128 v[170:173], v221 offset:9248
	v_add_f32_e32 v231, v231, v78
	v_add_f32_e32 v232, v232, v79
	v_add_f32_e32 v231, v231, v80
	v_add_f32_e32 v232, v232, v81
	v_cvt_pk_bf16_f32 v74, v74, v75
	v_cvt_pk_bf16_f32 v75, v76, v77
	v_mfma_f32_32x32x16_bf16 v[50:65], v[150:153], v[114:117], v[50:65]
	ds_read_b128 v[174:177], v221 offset:13856
	v_cvt_pk_bf16_f32 v76, v78, v79
	v_cvt_pk_bf16_f32 v77, v80, v81
	v_exp_f32_e32 v82, v82
	v_exp_f32_e32 v83, v83
	s_waitcnt lgkmcnt(4)
	v_mfma_f32_32x32x16_bf16 v[34:49], v[154:157], v[118:121], v[34:49]
	ds_read_b128 v[180:183], v221 offset:9280
	v_exp_f32_e32 v84, v84
	v_exp_f32_e32 v85, v85
	v_mfma_f32_32x32x16_bf16 v[50:65], v[158:161], v[118:121], v[50:65]
	ds_read_b128 v[184:187], v221 offset:13888
	v_add_f32_e32 v231, v231, v82
	v_add_f32_e32 v232, v232, v83
	v_exp_f32_e32 v86, v86
	v_exp_f32_e32 v87, v87
	s_waitcnt lgkmcnt(4)
	v_mfma_f32_32x32x16_bf16 v[2:17], v[162:165], v[66:69], v[2:17]
	ds_read_b128 v[188:191], v221 offset:9312
	v_add_f32_e32 v231, v231, v84
	v_add_f32_e32 v232, v232, v85
	v_exp_f32_e32 v88, v88
	v_exp_f32_e32 v89, v89
	v_mfma_f32_32x32x16_bf16 v[18:33], v[166:169], v[66:69], v[18:33]
	ds_read_b128 v[192:195], v221 offset:13920
	v_add_f32_e32 v231, v231, v86
	v_add_f32_e32 v232, v232, v87
	v_add_f32_e32 v231, v231, v88
	v_add_f32_e32 v232, v232, v89
	s_waitcnt lgkmcnt(4)
	v_mfma_f32_32x32x16_bf16 v[2:17], v[170:173], v[74:77], v[2:17]
	v_cvt_pk_bf16_f32 v82, v82, v83
	v_cvt_pk_bf16_f32 v83, v84, v85
	v_cvt_pk_bf16_f32 v84, v86, v87
	v_cvt_pk_bf16_f32 v85, v88, v89
	v_exp_f32_e32 v90, v90
	v_mfma_f32_32x32x16_bf16 v[18:33], v[174:177], v[74:77], v[18:33]
	s_waitcnt vmcnt(1)
	ds_write_b128 v222, v[200:203] offset:0
	ds_write_b128 v223, v[204:207] offset:0
	ds_write_b128 v224, v[208:211] offset:0
	ds_write_b64 v225, v[212:213] offset:27648
	ds_write_b64 v225, v[214:215] offset:27664
	v_exp_f32_e32 v91, v91
	v_exp_f32_e32 v92, v92
	v_exp_f32_e32 v93, v93
	s_waitcnt lgkmcnt(7)
	v_mfma_f32_32x32x16_bf16 v[2:17], v[180:183], v[82:85], v[2:17]
	v_add_f32_e32 v231, v231, v90
	v_add_f32_e32 v232, v232, v91
	v_exp_f32_e32 v94, v94
	v_mfma_f32_32x32x16_bf16 v[18:33], v[184:187], v[82:85], v[18:33]
	v_exp_f32_e32 v95, v95
	v_add_f32_e32 v231, v231, v92
	v_add_f32_e32 v232, v232, v93
	v_exp_f32_e32 v96, v96
	v_exp_f32_e32 v97, v97
	v_add_f32_e32 v231, v231, v94
	v_add_f32_e32 v232, v232, v95
	v_add_f32_e32 v231, v231, v96
	v_add_f32_e32 v232, v232, v97
	v_cvt_pk_bf16_f32 v90, v90, v91
	v_cvt_pk_bf16_f32 v91, v92, v93
	v_cvt_pk_bf16_f32 v92, v94, v95
	v_cvt_pk_bf16_f32 v93, v96, v97
	s_waitcnt lgkmcnt(5)
	s_nop 0
	v_mfma_f32_32x32x16_bf16 v[2:17], v[188:191], v[90:93], v[2:17]
	v_mfma_f32_32x32x16_bf16 v[18:33], v[192:195], v[90:93], v[18:33]
	ds_read_b128 v[138:141], v220 offset:39936
	ds_read_b128 v[142:145], v220 offset:46592
	ds_read_b128 v[146:149], v220 offset:39968
	ds_read_b128 v[150:153], v220 offset:46624
	ds_read_b128 v[154:157], v220 offset:40000
	ds_read_b128 v[158:161], v220 offset:46656
	s_waitcnt lgkmcnt(6)
	s_barrier
	v_exp_f32_e32 v34, v34
	v_exp_f32_e32 v35, v35
	v_exp_f32_e32 v36, v36
	s_waitcnt lgkmcnt(4)
	v_mfma_f32_32x32x16_bf16 v[66:81], v[138:141], v[98:101], v[122:137]
	ds_read_b128 v[138:141], v220 offset:40032
	v_exp_f32_e32 v37, v37
	v_add_f32_e32 v231, v231, v34
	v_add_f32_e32 v232, v232, v35
	v_exp_f32_e32 v38, v38
	v_mfma_f32_32x32x16_bf16 v[82:97], v[142:145], v[98:101], v[122:137]
	ds_read_b128 v[142:145], v220 offset:46688
	v_exp_f32_e32 v39, v39
	v_add_f32_e32 v231, v231, v36
	v_add_f32_e32 v232, v232, v37
	s_waitcnt lgkmcnt(4)
	v_mfma_f32_32x32x16_bf16 v[66:81], v[146:149], v[102:105], v[66:81]
	ds_read_b128 v[146:149], v220 offset:40064
	global_load_dwordx4 v[200:203], v226, s[4:5]
	global_load_dwordx4 v[204:207], v227, s[4:5]
	global_load_dwordx4 v[208:211], v228, s[4:5]
	s_add_u32 s4, s4, 0x6000
	s_addc_u32 s5, s5, 0
	global_load_dwordx4 v[212:215], v229, s[10:11]
	s_add_u32 s10, s10, 0x80
	s_addc_u32 s11, s11, 0
	v_exp_f32_e32 v40, v40
	v_exp_f32_e32 v41, v41
	v_add_f32_e32 v231, v231, v38
	v_add_f32_e32 v232, v232, v39
	v_mfma_f32_32x32x16_bf16 v[82:97], v[150:153], v[102:105], v[82:97]
	ds_read_b128 v[150:153], v220 offset:46720
	v_add_f32_e32 v231, v231, v40
	v_add_f32_e32 v232, v232, v41
	v_cvt_pk_bf16_f32 v34, v34, v35
	v_cvt_pk_bf16_f32 v35, v36, v37
	v_cvt_pk_bf16_f32 v36, v38, v39
	s_waitcnt lgkmcnt(4)
	v_mfma_f32_32x32x16_bf16 v[66:81], v[154:157], v[106:109], v[66:81]
	ds_read_b128 v[154:157], v220 offset:40096
	v_cvt_pk_bf16_f32 v37, v40, v41
	v_exp_f32_e32 v42, v42
	v_exp_f32_e32 v43, v43
	v_mfma_f32_32x32x16_bf16 v[82:97], v[158:161], v[106:109], v[82:97]
	ds_read_b128 v[158:161], v220 offset:46752
	v_exp_f32_e32 v44, v44
	v_exp_f32_e32 v45, v45
	v_add_f32_e32 v231, v231, v42
	v_add_f32_e32 v232, v232, v43
	s_waitcnt lgkmcnt(4)
	v_mfma_f32_32x32x16_bf16 v[66:81], v[138:141], v[110:113], v[66:81]
	ds_read_b128 v[162:165], v221 offset:18432
	v_exp_f32_e32 v46, v46
	v_exp_f32_e32 v47, v47
	v_add_f32_e32 v231, v231, v44
	v_mfma_f32_32x32x16_bf16 v[82:97], v[142:145], v[110:113], v[82:97]
	ds_read_b128 v[166:169], v221 offset:23040
	v_add_f32_e32 v232, v232, v45
	v_exp_f32_e32 v48, v48
	v_exp_f32_e32 v49, v49
	s_waitcnt lgkmcnt(4)
	v_mfma_f32_32x32x16_bf16 v[66:81], v[146:149], v[114:117], v[66:81]
	ds_read_b128 v[170:173], v221 offset:18464
	v_add_f32_e32 v231, v231, v46
	v_add_f32_e32 v232, v232, v47
	v_add_f32_e32 v231, v231, v48
	v_add_f32_e32 v232, v232, v49
	v_cvt_pk_bf16_f32 v42, v42, v43
	v_cvt_pk_bf16_f32 v43, v44, v45
	v_mfma_f32_32x32x16_bf16 v[82:97], v[150:153], v[114:117], v[82:97]
	ds_read_b128 v[174:177], v221 offset:23072
	v_cvt_pk_bf16_f32 v44, v46, v47
	v_cvt_pk_bf16_f32 v45, v48, v49
	v_exp_f32_e32 v50, v50
	v_exp_f32_e32 v51, v51
	s_waitcnt lgkmcnt(4)
	v_mfma_f32_32x32x16_bf16 v[66:81], v[154:157], v[118:121], v[66:81]
	ds_read_b128 v[180:183], v221 offset:18496
	v_exp_f32_e32 v52, v52
	v_exp_f32_e32 v53, v53
	v_mfma_f32_32x32x16_bf16 v[82:97], v[158:161], v[118:121], v[82:97]
	ds_read_b128 v[184:187], v221 offset:23104
	v_add_f32_e32 v231, v231, v50
	v_add_f32_e32 v232, v232, v51
	v_exp_f32_e32 v54, v54
	v_exp_f32_e32 v55, v55
	s_waitcnt lgkmcnt(4)
	v_mfma_f32_32x32x16_bf16 v[2:17], v[162:165], v[34:37], v[2:17]
	ds_read_b128 v[188:191], v221 offset:18528
	v_add_f32_e32 v231, v231, v52
	v_add_f32_e32 v232, v232, v53
	v_exp_f32_e32 v56, v56
	v_exp_f32_e32 v57, v57
	v_mfma_f32_32x32x16_bf16 v[18:33], v[166:169], v[34:37], v[18:33]
	ds_read_b128 v[192:195], v221 offset:23136
	v_add_f32_e32 v231, v231, v54
	v_add_f32_e32 v232, v232, v55
	v_add_f32_e32 v231, v231, v56
	v_add_f32_e32 v232, v232, v57
	s_waitcnt lgkmcnt(4)
	v_mfma_f32_32x32x16_bf16 v[2:17], v[170:173], v[42:45], v[2:17]
	v_cvt_pk_bf16_f32 v50, v50, v51
	v_cvt_pk_bf16_f32 v51, v52, v53
	v_cvt_pk_bf16_f32 v52, v54, v55
	v_cvt_pk_bf16_f32 v53, v56, v57
	v_exp_f32_e32 v58, v58
	v_mfma_f32_32x32x16_bf16 v[18:33], v[174:177], v[42:45], v[18:33]
	s_waitcnt vmcnt(4)
	ds_write_b64 v225, v[216:217] offset:0
	ds_write_b64 v225, v[218:219] offset:16
	v_exp_f32_e32 v59, v59
	v_exp_f32_e32 v60, v60
	v_exp_f32_e32 v61, v61
	s_waitcnt lgkmcnt(4)
	v_mfma_f32_32x32x16_bf16 v[2:17], v[180:183], v[50:53], v[2:17]
	v_add_f32_e32 v231, v231, v58
	v_add_f32_e32 v232, v232, v59
	v_exp_f32_e32 v62, v62
	v_mfma_f32_32x32x16_bf16 v[18:33], v[184:187], v[50:53], v[18:33]
	v_exp_f32_e32 v63, v63
	v_add_f32_e32 v231, v231, v60
	v_add_f32_e32 v232, v232, v61
	v_exp_f32_e32 v64, v64
	v_exp_f32_e32 v65, v65
	v_add_f32_e32 v231, v231, v62
	v_add_f32_e32 v232, v232, v63
	v_add_f32_e32 v231, v231, v64
	v_add_f32_e32 v232, v232, v65
	v_cvt_pk_bf16_f32 v58, v58, v59
	v_cvt_pk_bf16_f32 v59, v60, v61
	v_cvt_pk_bf16_f32 v60, v62, v63
	v_cvt_pk_bf16_f32 v61, v64, v65
	s_waitcnt lgkmcnt(2)
	s_nop 0
	v_mfma_f32_32x32x16_bf16 v[2:17], v[188:191], v[58:61], v[2:17]
	v_mfma_f32_32x32x16_bf16 v[18:33], v[192:195], v[58:61], v[18:33]
	ds_read_b128 v[138:141], v220 offset:0
	ds_read_b128 v[142:145], v220 offset:6656
	ds_read_b128 v[146:149], v220 offset:32
	ds_read_b128 v[150:153], v220 offset:6688
	ds_read_b128 v[154:157], v220 offset:64
	ds_read_b128 v[158:161], v220 offset:6720
	s_waitcnt lgkmcnt(6)
	s_barrier
	v_exp_f32_e32 v66, v66
	v_exp_f32_e32 v67, v67
	v_exp_f32_e32 v68, v68
	s_waitcnt lgkmcnt(4)
	v_mfma_f32_32x32x16_bf16 v[34:49], v[138:141], v[98:101], v[122:137]
	ds_read_b128 v[138:141], v220 offset:96
	v_exp_f32_e32 v69, v69
	v_add_f32_e32 v231, v231, v66
	v_add_f32_e32 v232, v232, v67
	v_exp_f32_e32 v70, v70
	v_mfma_f32_32x32x16_bf16 v[50:65], v[142:145], v[98:101], v[122:137]
	ds_read_b128 v[142:145], v220 offset:6752
	v_exp_f32_e32 v71, v71
	v_add_f32_e32 v231, v231, v68
	v_add_f32_e32 v232, v232, v69
	s_waitcnt lgkmcnt(4)
	v_mfma_f32_32x32x16_bf16 v[34:49], v[146:149], v[102:105], v[34:49]
	ds_read_b128 v[146:149], v220 offset:128
	global_load_dwordx4 v[216:219], v229, s[10:11]
	s_add_u32 s10, s10, 0x80
	s_addc_u32 s11, s11, 0
	v_exp_f32_e32 v72, v72
	v_exp_f32_e32 v73, v73
	v_add_f32_e32 v231, v231, v70
	v_add_f32_e32 v232, v232, v71
	v_mfma_f32_32x32x16_bf16 v[50:65], v[150:153], v[102:105], v[50:65]
	ds_read_b128 v[150:153], v220 offset:6784
	v_add_f32_e32 v231, v231, v72
	v_add_f32_e32 v232, v232, v73
	v_cvt_pk_bf16_f32 v66, v66, v67
	v_cvt_pk_bf16_f32 v67, v68, v69
	v_cvt_pk_bf16_f32 v68, v70, v71
	s_waitcnt lgkmcnt(4)
	v_mfma_f32_32x32x16_bf16 v[34:49], v[154:157], v[106:109], v[34:49]
	ds_read_b128 v[154:157], v220 offset:160
	v_cvt_pk_bf16_f32 v69, v72, v73
	v_exp_f32_e32 v74, v74
	v_exp_f32_e32 v75, v75
	v_mfma_f32_32x32x16_bf16 v[50:65], v[158:161], v[106:109], v[50:65]
	ds_read_b128 v[158:161], v220 offset:6816
	v_exp_f32_e32 v76, v76
	v_exp_f32_e32 v77, v77
	v_add_f32_e32 v231, v231, v74
	v_add_f32_e32 v232, v232, v75
	s_waitcnt lgkmcnt(4)
	v_mfma_f32_32x32x16_bf16 v[34:49], v[138:141], v[110:113], v[34:49]
	ds_read_b128 v[162:165], v221 offset:27648
	v_exp_f32_e32 v78, v78
	v_exp_f32_e32 v79, v79
	v_add_f32_e32 v231, v231, v76
	v_mfma_f32_32x32x16_bf16 v[50:65], v[142:145], v[110:113], v[50:65]
	ds_read_b128 v[166:169], v221 offset:32256
	v_add_f32_e32 v232, v232, v77
	v_exp_f32_e32 v80, v80
	v_exp_f32_e32 v81, v81
	s_waitcnt lgkmcnt(4)
	v_mfma_f32_32x32x16_bf16 v[34:49], v[146:149], v[114:117], v[34:49]
	ds_read_b128 v[170:173], v221 offset:27680
	v_add_f32_e32 v231, v231, v78
	v_add_f32_e32 v232, v232, v79
	v_add_f32_e32 v231, v231, v80
	v_add_f32_e32 v232, v232, v81
	v_cvt_pk_bf16_f32 v74, v74, v75
	v_cvt_pk_bf16_f32 v75, v76, v77
	v_mfma_f32_32x32x16_bf16 v[50:65], v[150:153], v[114:117], v[50:65]
	ds_read_b128 v[174:177], v221 offset:32288
	v_cvt_pk_bf16_f32 v76, v78, v79
	v_cvt_pk_bf16_f32 v77, v80, v81
	v_exp_f32_e32 v82, v82
	v_exp_f32_e32 v83, v83
	s_waitcnt lgkmcnt(4)
	v_mfma_f32_32x32x16_bf16 v[34:49], v[154:157], v[118:121], v[34:49]
	ds_read_b128 v[180:183], v221 offset:27712
	v_exp_f32_e32 v84, v84
	v_exp_f32_e32 v85, v85
	v_mfma_f32_32x32x16_bf16 v[50:65], v[158:161], v[118:121], v[50:65]
	ds_read_b128 v[184:187], v221 offset:32320
	v_add_f32_e32 v231, v231, v82
	v_add_f32_e32 v232, v232, v83
	v_exp_f32_e32 v86, v86
	v_exp_f32_e32 v87, v87
	s_waitcnt lgkmcnt(4)
	v_mfma_f32_32x32x16_bf16 v[2:17], v[162:165], v[66:69], v[2:17]
	ds_read_b128 v[188:191], v221 offset:27744
	v_add_f32_e32 v231, v231, v84
	v_add_f32_e32 v232, v232, v85
	v_exp_f32_e32 v88, v88
	v_exp_f32_e32 v89, v89
	v_mfma_f32_32x32x16_bf16 v[18:33], v[166:169], v[66:69], v[18:33]
	ds_read_b128 v[192:195], v221 offset:32352
	v_add_f32_e32 v231, v231, v86
	v_add_f32_e32 v232, v232, v87
	v_add_f32_e32 v231, v231, v88
	v_add_f32_e32 v232, v232, v89
	s_waitcnt lgkmcnt(4)
	v_mfma_f32_32x32x16_bf16 v[2:17], v[170:173], v[74:77], v[2:17]
	v_cvt_pk_bf16_f32 v82, v82, v83
	v_cvt_pk_bf16_f32 v83, v84, v85
	v_cvt_pk_bf16_f32 v84, v86, v87
	v_cvt_pk_bf16_f32 v85, v88, v89
	v_exp_f32_e32 v90, v90
	v_mfma_f32_32x32x16_bf16 v[18:33], v[174:177], v[74:77], v[18:33]
	s_waitcnt vmcnt(1)
	ds_write_b128 v222, v[200:203] offset:26624
	ds_write_b128 v223, v[204:207] offset:26624
	ds_write_b128 v224, v[208:211] offset:26624
	ds_write_b64 v225, v[212:213] offset:9216
	ds_write_b64 v225, v[214:215] offset:9232
	v_exp_f32_e32 v91, v91
	v_exp_f32_e32 v92, v92
	v_exp_f32_e32 v93, v93
	s_waitcnt lgkmcnt(7)
	v_mfma_f32_32x32x16_bf16 v[2:17], v[180:183], v[82:85], v[2:17]
	v_add_f32_e32 v231, v231, v90
	v_add_f32_e32 v232, v232, v91
	v_exp_f32_e32 v94, v94
	v_mfma_f32_32x32x16_bf16 v[18:33], v[184:187], v[82:85], v[18:33]
	v_exp_f32_e32 v95, v95
	v_add_f32_e32 v231, v231, v92
	v_add_f32_e32 v232, v232, v93
	v_exp_f32_e32 v96, v96
	v_exp_f32_e32 v97, v97
	v_add_f32_e32 v231, v231, v94
	v_add_f32_e32 v232, v232, v95
	v_add_f32_e32 v231, v231, v96
	v_add_f32_e32 v232, v232, v97
	v_cvt_pk_bf16_f32 v90, v90, v91
	v_cvt_pk_bf16_f32 v91, v92, v93
	v_cvt_pk_bf16_f32 v92, v94, v95
	v_cvt_pk_bf16_f32 v93, v96, v97
	s_waitcnt lgkmcnt(5)
	s_nop 0
	v_mfma_f32_32x32x16_bf16 v[2:17], v[188:191], v[90:93], v[2:17]
	v_mfma_f32_32x32x16_bf16 v[18:33], v[192:195], v[90:93], v[18:33]
	ds_read_b128 v[138:141], v220 offset:13312
	ds_read_b128 v[142:145], v220 offset:19968
	ds_read_b128 v[146:149], v220 offset:13344
	ds_read_b128 v[150:153], v220 offset:20000
	ds_read_b128 v[154:157], v220 offset:13376
	ds_read_b128 v[158:161], v220 offset:20032
	s_waitcnt lgkmcnt(6)
	s_barrier
	s_add_i32 s16, s16, -1
	s_cmp_lg_u32 s16, 0
	s_cbranch_scc1 .Lmla_loop
	v_exp_f32_e32 v34, v34
	v_exp_f32_e32 v35, v35
	v_exp_f32_e32 v36, v36
	s_waitcnt lgkmcnt(4)
	v_mfma_f32_32x32x16_bf16 v[66:81], v[138:141], v[98:101], v[122:137]
	ds_read_b128 v[138:141], v220 offset:13408
	v_exp_f32_e32 v37, v37
	v_add_f32_e32 v231, v231, v34
	v_add_f32_e32 v232, v232, v35
	v_exp_f32_e32 v38, v38
	v_mfma_f32_32x32x16_bf16 v[82:97], v[142:145], v[98:101], v[122:137]
	ds_read_b128 v[142:145], v220 offset:20064
	v_exp_f32_e32 v39, v39
	v_add_f32_e32 v231, v231, v36
	v_add_f32_e32 v232, v232, v37
	s_waitcnt lgkmcnt(4)
	v_mfma_f32_32x32x16_bf16 v[66:81], v[146:149], v[102:105], v[66:81]
	ds_read_b128 v[146:149], v220 offset:13440
	global_load_dwordx4 v[212:215], v229, s[10:11]
	s_add_u32 s10, s10, 0x80
	s_addc_u32 s11, s11, 0
	v_exp_f32_e32 v40, v40
	v_exp_f32_e32 v41, v41
	v_add_f32_e32 v231, v231, v38
	v_add_f32_e32 v232, v232, v39
	v_mfma_f32_32x32x16_bf16 v[82:97], v[150:153], v[102:105], v[82:97]
	ds_read_b128 v[150:153], v220 offset:20096
	v_add_f32_e32 v231, v231, v40
	v_add_f32_e32 v232, v232, v41
	v_cvt_pk_bf16_f32 v34, v34, v35
	v_cvt_pk_bf16_f32 v35, v36, v37
	v_cvt_pk_bf16_f32 v36, v38, v39
	s_waitcnt lgkmcnt(4)
	v_mfma_f32_32x32x16_bf16 v[66:81], v[154:157], v[106:109], v[66:81]
	ds_read_b128 v[154:157], v220 offset:13472
	v_cvt_pk_bf16_f32 v37, v40, v41
	v_exp_f32_e32 v42, v42
	v_exp_f32_e32 v43, v43
	v_mfma_f32_32x32x16_bf16 v[82:97], v[158:161], v[106:109], v[82:97]
	ds_read_b128 v[158:161], v220 offset:20128
	v_exp_f32_e32 v44, v44
	v_exp_f32_e32 v45, v45
	v_add_f32_e32 v231, v231, v42
	v_add_f32_e32 v232, v232, v43
	s_waitcnt lgkmcnt(4)
	v_mfma_f32_32x32x16_bf16 v[66:81], v[138:141], v[110:113], v[66:81]
	ds_read_b128 v[162:165], v221 offset:0
	v_exp_f32_e32 v46, v46
	v_exp_f32_e32 v47, v47
	v_add_f32_e32 v231, v231, v44
	v_mfma_f32_32x32x16_bf16 v[82:97], v[142:145], v[110:113], v[82:97]
	ds_read_b128 v[166:169], v221 offset:4608
	v_add_f32_e32 v232, v232, v45
	v_exp_f32_e32 v48, v48
	v_exp_f32_e32 v49, v49
	s_waitcnt lgkmcnt(4)
	v_mfma_f32_32x32x16_bf16 v[66:81], v[146:149], v[114:117], v[66:81]
	ds_read_b128 v[170:173], v221 offset:32
	v_add_f32_e32 v231, v231, v46
	v_add_f32_e32 v232, v232, v47
	v_add_f32_e32 v231, v231, v48
	v_add_f32_e32 v232, v232, v49
	v_cvt_pk_bf16_f32 v42, v42, v43
	v_cvt_pk_bf16_f32 v43, v44, v45
	v_mfma_f32_32x32x16_bf16 v[82:97], v[150:153], v[114:117], v[82:97]
	ds_read_b128 v[174:177], v221 offset:4640
	v_cvt_pk_bf16_f32 v44, v46, v47
	v_cvt_pk_bf16_f32 v45, v48, v49
	v_exp_f32_e32 v50, v50
	v_exp_f32_e32 v51, v51
	s_waitcnt lgkmcnt(4)
	v_mfma_f32_32x32x16_bf16 v[66:81], v[154:157], v[118:121], v[66:81]
	ds_read_b128 v[180:183], v221 offset:64
	v_exp_f32_e32 v52, v52
	v_exp_f32_e32 v53, v53
	v_mfma_f32_32x32x16_bf16 v[82:97], v[158:161], v[118:121], v[82:97]
	ds_read_b128 v[184:187], v221 offset:4672
	v_add_f32_e32 v231, v231, v50
	v_add_f32_e32 v232, v232, v51
	v_exp_f32_e32 v54, v54
	v_exp_f32_e32 v55, v55
	s_waitcnt lgkmcnt(4)
	v_mfma_f32_32x32x16_bf16 v[2:17], v[162:165], v[34:37], v[2:17]
	ds_read_b128 v[188:191], v221 offset:96
	v_add_f32_e32 v231, v231, v52
	v_add_f32_e32 v232, v232, v53
	v_exp_f32_e32 v56, v56
	v_exp_f32_e32 v57, v57
	v_mfma_f32_32x32x16_bf16 v[18:33], v[166:169], v[34:37], v[18:33]
	ds_read_b128 v[192:195], v221 offset:4704
	v_add_f32_e32 v231, v231, v54
	v_add_f32_e32 v232, v232, v55
	v_add_f32_e32 v231, v231, v56
	v_add_f32_e32 v232, v232, v57
	s_waitcnt lgkmcnt(4)
	v_mfma_f32_32x32x16_bf16 v[2:17], v[170:173], v[42:45], v[2:17]
	v_cvt_pk_bf16_f32 v50, v50, v51
	v_cvt_pk_bf16_f32 v51, v52, v53
	v_cvt_pk_bf16_f32 v52, v54, v55
	v_cvt_pk_bf16_f32 v53, v56, v57
	v_exp_f32_e32 v58, v58
	v_mfma_f32_32x32x16_bf16 v[18:33], v[174:177], v[42:45], v[18:33]
	s_waitcnt vmcnt(1)
	ds_write_b64 v225, v[216:217] offset:18432
	ds_write_b64 v225, v[218:219] offset:18448
	v_exp_f32_e32 v59, v59
	v_exp_f32_e32 v60, v60
	v_exp_f32_e32 v61, v61
	s_waitcnt lgkmcnt(4)
	v_mfma_f32_32x32x16_bf16 v[2:17], v[180:183], v[50:53], v[2:17]
	v_add_f32_e32 v231, v231, v58
	v_add_f32_e32 v232, v232, v59
	v_exp_f32_e32 v62, v62
	v_mfma_f32_32x32x16_bf16 v[18:33], v[184:187], v[50:53], v[18:33]
	v_exp_f32_e32 v63, v63
	v_add_f32_e32 v231, v231, v60
	v_add_f32_e32 v232, v232, v61
	v_exp_f32_e32 v64, v64
	v_exp_f32_e32 v65, v65
	v_add_f32_e32 v231, v231, v62
	v_add_f32_e32 v232, v232, v63
	v_add_f32_e32 v231, v231, v64
	v_add_f32_e32 v232, v232, v65
	v_cvt_pk_bf16_f32 v58, v58, v59
	v_cvt_pk_bf16_f32 v59, v60, v61
	v_cvt_pk_bf16_f32 v60, v62, v63
	v_cvt_pk_bf16_f32 v61, v64, v65
	s_waitcnt lgkmcnt(2)
	s_nop 0
	v_mfma_f32_32x32x16_bf16 v[2:17], v[188:191], v[58:61], v[2:17]
	v_mfma_f32_32x32x16_bf16 v[18:33], v[192:195], v[58:61], v[18:33]
	ds_read_b128 v[138:141], v220 offset:26624
	ds_read_b128 v[142:145], v220 offset:33280
	ds_read_b128 v[146:149], v220 offset:26656
	ds_read_b128 v[150:153], v220 offset:33312
	ds_read_b128 v[154:157], v220 offset:26688
	ds_read_b128 v[158:161], v220 offset:33344
	s_waitcnt lgkmcnt(6)
	s_barrier
	v_exp_f32_e32 v66, v66
	v_exp_f32_e32 v67, v67
	v_exp_f32_e32 v68, v68
	s_waitcnt lgkmcnt(4)
	v_mfma_f32_32x32x16_bf16 v[34:49], v[138:141], v[98:101], v[122:137]
	ds_read_b128 v[138:141], v220 offset:26720
	v_exp_f32_e32 v69, v69
	v_add_f32_e32 v231, v231, v66
	v_add_f32_e32 v232, v232, v67
	v_exp_f32_e32 v70, v70
	v_mfma_f32_32x32x16_bf16 v[50:65], v[142:145], v[98:101], v[122:137]
	ds_read_b128 v[142:145], v220 offset:33376
	v_exp_f32_e32 v71, v71
	v_add_f32_e32 v231, v231, v68
	v_add_f32_e32 v232, v232, v69
	s_waitcnt lgkmcnt(4)
	v_mfma_f32_32x32x16_bf16 v[34:49], v[146:149], v[102:105], v[34:49]
	ds_read_b128 v[146:149], v220 offset:26752
	v_exp_f32_e32 v72, v72
	v_exp_f32_e32 v73, v73
	v_add_f32_e32 v231, v231, v70
	v_add_f32_e32 v232, v232, v71
	v_mfma_f32_32x32x16_bf16 v[50:65], v[150:153], v[102:105], v[50:65]
	ds_read_b128 v[150:153], v220 offset:33408
	v_add_f32_e32 v231, v231, v72
	v_add_f32_e32 v232, v232, v73
	v_cvt_pk_bf16_f32 v66, v66, v67
	v_cvt_pk_bf16_f32 v67, v68, v69
	v_cvt_pk_bf16_f32 v68, v70, v71
	s_waitcnt lgkmcnt(4)
	v_mfma_f32_32x32x16_bf16 v[34:49], v[154:157], v[106:109], v[34:49]
	ds_read_b128 v[154:157], v220 offset:26784
	v_cvt_pk_bf16_f32 v69, v72, v73
	v_exp_f32_e32 v74, v74
	v_exp_f32_e32 v75, v75
	v_mfma_f32_32x32x16_bf16 v[50:65], v[158:161], v[106:109], v[50:65]
	ds_read_b128 v[158:161], v220 offset:33440
	v_exp_f32_e32 v76, v76
	v_exp_f32_e32 v77, v77
	v_add_f32_e32 v231, v231, v74
	v_add_f32_e32 v232, v232, v75
	s_waitcnt lgkmcnt(4)
	v_mfma_f32_32x32x16_bf16 v[34:49], v[138:141], v[110:113], v[34:49]
	ds_read_b128 v[162:165], v221 offset:9216
	v_exp_f32_e32 v78, v78
	v_exp_f32_e32 v79, v79
	v_add_f32_e32 v231, v231, v76
	v_mfma_f32_32x32x16_bf16 v[50:65], v[142:145], v[110:113], v[50:65]
	ds_read_b128 v[166:169], v221 offset:13824
	v_add_f32_e32 v232, v232, v77
	v_exp_f32_e32 v80, v80
	v_exp_f32_e32 v81, v81
	s_waitcnt lgkmcnt(4)
	v_mfma_f32_32x32x16_bf16 v[34:49], v[146:149], v[114:117], v[34:49]
	ds_read_b128 v[170:173], v221 offset:9248
	v_add_f32_e32 v231, v231, v78
	v_add_f32_e32 v232, v232, v79
	v_add_f32_e32 v231, v231, v80
	v_add_f32_e32 v232, v232, v81
	v_cvt_pk_bf16_f32 v74, v74, v75
	v_cvt_pk_bf16_f32 v75, v76, v77
	v_mfma_f32_32x32x16_bf16 v[50:65], v[150:153], v[114:117], v[50:65]
	ds_read_b128 v[174:177], v221 offset:13856
	v_cvt_pk_bf16_f32 v76, v78, v79
	v_cvt_pk_bf16_f32 v77, v80, v81
	v_exp_f32_e32 v82, v82
	v_exp_f32_e32 v83, v83
	s_waitcnt lgkmcnt(4)
	v_mfma_f32_32x32x16_bf16 v[34:49], v[154:157], v[118:121], v[34:49]
	ds_read_b128 v[180:183], v221 offset:9280
	v_exp_f32_e32 v84, v84
	v_exp_f32_e32 v85, v85
	v_mfma_f32_32x32x16_bf16 v[50:65], v[158:161], v[118:121], v[50:65]
	ds_read_b128 v[184:187], v221 offset:13888
	v_add_f32_e32 v231, v231, v82
	v_add_f32_e32 v232, v232, v83
	v_exp_f32_e32 v86, v86
	v_exp_f32_e32 v87, v87
	s_waitcnt lgkmcnt(4)
	v_mfma_f32_32x32x16_bf16 v[2:17], v[162:165], v[66:69], v[2:17]
	ds_read_b128 v[188:191], v221 offset:9312
	v_add_f32_e32 v231, v231, v84
	v_add_f32_e32 v232, v232, v85
	v_exp_f32_e32 v88, v88
	v_exp_f32_e32 v89, v89
	v_mfma_f32_32x32x16_bf16 v[18:33], v[166:169], v[66:69], v[18:33]
	ds_read_b128 v[192:195], v221 offset:13920
	v_add_f32_e32 v231, v231, v86
	v_add_f32_e32 v232, v232, v87
	v_add_f32_e32 v231, v231, v88
	v_add_f32_e32 v232, v232, v89
	s_waitcnt lgkmcnt(4)
	v_mfma_f32_32x32x16_bf16 v[2:17], v[170:173], v[74:77], v[2:17]
	v_cvt_pk_bf16_f32 v82, v82, v83
	v_cvt_pk_bf16_f32 v83, v84, v85
	v_cvt_pk_bf16_f32 v84, v86, v87
	v_cvt_pk_bf16_f32 v85, v88, v89
	v_exp_f32_e32 v90, v90
	v_mfma_f32_32x32x16_bf16 v[18:33], v[174:177], v[74:77], v[18:33]
	s_waitcnt vmcnt(0)
	ds_write_b64 v225, v[212:213] offset:27648
	ds_write_b64 v225, v[214:215] offset:27664
	v_exp_f32_e32 v91, v91
	v_exp_f32_e32 v92, v92
	v_exp_f32_e32 v93, v93
	s_waitcnt lgkmcnt(4)
	v_mfma_f32_32x32x16_bf16 v[2:17], v[180:183], v[82:85], v[2:17]
	v_add_f32_e32 v231, v231, v90
	v_add_f32_e32 v232, v232, v91
	v_exp_f32_e32 v94, v94
	v_mfma_f32_32x32x16_bf16 v[18:33], v[184:187], v[82:85], v[18:33]
	v_exp_f32_e32 v95, v95
	v_add_f32_e32 v231, v231, v92
	v_add_f32_e32 v232, v232, v93
	v_exp_f32_e32 v96, v96
	v_exp_f32_e32 v97, v97
	v_add_f32_e32 v231, v231, v94
	v_add_f32_e32 v232, v232, v95
	v_add_f32_e32 v231, v231, v96
	v_add_f32_e32 v232, v232, v97
	v_cvt_pk_bf16_f32 v90, v90, v91
	v_cvt_pk_bf16_f32 v91, v92, v93
	v_cvt_pk_bf16_f32 v92, v94, v95
	v_cvt_pk_bf16_f32 v93, v96, v97
	s_waitcnt lgkmcnt(2)
	s_nop 0
	v_mfma_f32_32x32x16_bf16 v[2:17], v[188:191], v[90:93], v[2:17]
	v_mfma_f32_32x32x16_bf16 v[18:33], v[192:195], v[90:93], v[18:33]
	ds_read_b128 v[138:141], v220 offset:39936
	ds_read_b128 v[142:145], v220 offset:46592
	ds_read_b128 v[146:149], v220 offset:39968
	ds_read_b128 v[150:153], v220 offset:46624
	ds_read_b128 v[154:157], v220 offset:40000
	ds_read_b128 v[158:161], v220 offset:46656
	s_waitcnt lgkmcnt(6)
	s_barrier
	global_load_dwordx2 v[200:201], v236, s[14:15] offset:0
	global_load_dwordx2 v[202:203], v236, s[14:15] offset:16
	global_load_dwordx2 v[204:205], v236, s[14:15] offset:32
	global_load_dwordx2 v[206:207], v236, s[14:15] offset:48
	global_load_dwordx2 v[208:209], v236, s[14:15] offset:64
	global_load_dwordx2 v[210:211], v236, s[14:15] offset:80
	global_load_dwordx2 v[212:213], v236, s[14:15] offset:96
	global_load_dwordx2 v[214:215], v236, s[14:15] offset:112
	v_exp_f32_e32 v34, v34
	v_exp_f32_e32 v35, v35
	v_exp_f32_e32 v36, v36
	s_waitcnt lgkmcnt(4)
	v_mfma_f32_32x32x16_bf16 v[66:81], v[138:141], v[98:101], v[122:137]
	ds_read_b128 v[138:141], v220 offset:40032
	v_exp_f32_e32 v37, v37
	v_add_f32_e32 v231, v231, v34
	v_add_f32_e32 v232, v232, v35
	v_exp_f32_e32 v38, v38
	v_mfma_f32_32x32x16_bf16 v[82:97], v[142:145], v[98:101], v[122:137]
	ds_read_b128 v[142:145], v220 offset:46688
	v_exp_f32_e32 v39, v39
	v_add_f32_e32 v231, v231, v36
	v_add_f32_e32 v232, v232, v37
	s_waitcnt lgkmcnt(4)
	v_mfma_f32_32x32x16_bf16 v[66:81], v[146:149], v[102:105], v[66:81]
	ds_read_b128 v[146:149], v220 offset:40064
	v_exp_f32_e32 v40, v40
	v_exp_f32_e32 v41, v41
	v_add_f32_e32 v231, v231, v38
	v_add_f32_e32 v232, v232, v39
	v_mfma_f32_32x32x16_bf16 v[82:97], v[150:153], v[102:105], v[82:97]
	ds_read_b128 v[150:153], v220 offset:46720
	v_add_f32_e32 v231, v231, v40
	v_add_f32_e32 v232, v232, v41
	v_cvt_pk_bf16_f32 v34, v34, v35
	v_cvt_pk_bf16_f32 v35, v36, v37
	v_cvt_pk_bf16_f32 v36, v38, v39
	s_waitcnt lgkmcnt(4)
	v_mfma_f32_32x32x16_bf16 v[66:81], v[154:157], v[106:109], v[66:81]
	ds_read_b128 v[154:157], v220 offset:40096
	v_cvt_pk_bf16_f32 v37, v40, v41
	v_exp_f32_e32 v42, v42
	v_exp_f32_e32 v43, v43
	v_mfma_f32_32x32x16_bf16 v[82:97], v[158:161], v[106:109], v[82:97]
	ds_read_b128 v[158:161], v220 offset:46752
	v_exp_f32_e32 v44, v44
	v_exp_f32_e32 v45, v45
	v_add_f32_e32 v231, v231, v42
	v_add_f32_e32 v232, v232, v43
	s_waitcnt lgkmcnt(4)
	v_mfma_f32_32x32x16_bf16 v[66:81], v[138:141], v[110:113], v[66:81]
	ds_read_b128 v[162:165], v221 offset:18432
	v_exp_f32_e32 v46, v46
	v_exp_f32_e32 v47, v47
	v_add_f32_e32 v231, v231, v44
	v_mfma_f32_32x32x16_bf16 v[82:97], v[142:145], v[110:113], v[82:97]
	ds_read_b128 v[166:169], v221 offset:23040
	v_add_f32_e32 v232, v232, v45
	v_exp_f32_e32 v48, v48
	v_exp_f32_e32 v49, v49
	s_waitcnt lgkmcnt(4)
	v_mfma_f32_32x32x16_bf16 v[66:81], v[146:149], v[114:117], v[66:81]
	ds_read_b128 v[170:173], v221 offset:18464
	v_add_f32_e32 v231, v231, v46
	v_add_f32_e32 v232, v232, v47
	v_add_f32_e32 v231, v231, v48
	v_add_f32_e32 v232, v232, v49
	v_cvt_pk_bf16_f32 v42, v42, v43
	v_cvt_pk_bf16_f32 v43, v44, v45
	v_mfma_f32_32x32x16_bf16 v[82:97], v[150:153], v[114:117], v[82:97]
	ds_read_b128 v[174:177], v221 offset:23072
	v_cvt_pk_bf16_f32 v44, v46, v47
	v_cvt_pk_bf16_f32 v45, v48, v49
	v_exp_f32_e32 v50, v50
	v_exp_f32_e32 v51, v51
	s_waitcnt lgkmcnt(4)
	v_mfma_f32_32x32x16_bf16 v[66:81], v[154:157], v[118:121], v[66:81]
	ds_read_b128 v[180:183], v221 offset:18496
	v_exp_f32_e32 v52, v52
	v_exp_f32_e32 v53, v53
	v_mfma_f32_32x32x16_bf16 v[82:97], v[158:161], v[118:121], v[82:97]
	ds_read_b128 v[184:187], v221 offset:23104
	v_add_f32_e32 v231, v231, v50
	v_add_f32_e32 v232, v232, v51
	v_exp_f32_e32 v54, v54
	v_exp_f32_e32 v55, v55
	s_waitcnt lgkmcnt(4)
	v_mfma_f32_32x32x16_bf16 v[2:17], v[162:165], v[34:37], v[2:17]
	ds_read_b128 v[188:191], v221 offset:18528
	v_add_f32_e32 v231, v231, v52
	v_add_f32_e32 v232, v232, v53
	v_exp_f32_e32 v56, v56
	v_exp_f32_e32 v57, v57
	v_mfma_f32_32x32x16_bf16 v[18:33], v[166:169], v[34:37], v[18:33]
	ds_read_b128 v[192:195], v221 offset:23136
	v_add_f32_e32 v231, v231, v54
	v_add_f32_e32 v232, v232, v55
	v_add_f32_e32 v231, v231, v56
	v_add_f32_e32 v232, v232, v57
	s_waitcnt lgkmcnt(4)
	v_mfma_f32_32x32x16_bf16 v[2:17], v[170:173], v[42:45], v[2:17]
	v_cvt_pk_bf16_f32 v50, v50, v51
	v_cvt_pk_bf16_f32 v51, v52, v53
	v_cvt_pk_bf16_f32 v52, v54, v55
	v_cvt_pk_bf16_f32 v53, v56, v57
	v_exp_f32_e32 v58, v58
	v_mfma_f32_32x32x16_bf16 v[18:33], v[174:177], v[42:45], v[18:33]
	v_exp_f32_e32 v59, v59
	v_exp_f32_e32 v60, v60
	v_exp_f32_e32 v61, v61
	s_waitcnt lgkmcnt(2)
	v_mfma_f32_32x32x16_bf16 v[2:17], v[180:183], v[50:53], v[2:17]
	v_add_f32_e32 v231, v231, v58
	v_add_f32_e32 v232, v232, v59
	v_exp_f32_e32 v62, v62
	v_mfma_f32_32x32x16_bf16 v[18:33], v[184:187], v[50:53], v[18:33]
	v_exp_f32_e32 v63, v63
	v_add_f32_e32 v231, v231, v60
	v_add_f32_e32 v232, v232, v61
	v_exp_f32_e32 v64, v64
	v_exp_f32_e32 v65, v65
	v_add_f32_e32 v231, v231, v62
	v_add_f32_e32 v232, v232, v63
	v_add_f32_e32 v231, v231, v64
	v_add_f32_e32 v232, v232, v65
	v_cvt_pk_bf16_f32 v58, v58, v59
	v_cvt_pk_bf16_f32 v59, v60, v61
	v_cvt_pk_bf16_f32 v60, v62, v63
	v_cvt_pk_bf16_f32 v61, v64, v65
	s_waitcnt lgkmcnt(0)
	s_nop 0
	v_mfma_f32_32x32x16_bf16 v[2:17], v[188:191], v[58:61], v[2:17]
	v_mfma_f32_32x32x16_bf16 v[18:33], v[192:195], v[58:61], v[18:33]
	s_waitcnt lgkmcnt(0)
	s_barrier
	s_mov_b64 s[24:25], s[14:15]
	s_add_i32 s2, s2, s88
	s_cmpk_lt_i32 s2, 0x200
	s_cbranch_scc0 .Lmla_nopf
	s_lshr_b32 s17, s2, 4
	s_and_b32 s18, s2, 15
	s_mul_i32 s19, s17, 0xcc000
	s_add_u32 s4, s78, s19
	s_addc_u32 s5, s79, 0
	s_mul_i32 s19, s17, 0x88000
	s_add_u32 s19, s19, 0x1a00000
	s_add_u32 s10, s78, s19
	s_addc_u32 s11, s79, 0
	s_lshl_b32 s19, s17, 12
	s_lshl_b32 s20, s18, 8
	s_add_u32 s19, s19, s20
	s_mul_i32 s19, s19, 0xc0
	s_add_u32 s19, s19, 0x1400000
	s_add_u32 s12, s80, s19
	s_addc_u32 s13, s81, 0
	s_lshr_b32 s19, s17, 3
	s_lshl_b32 s19, s19, 12
	s_add_u32 s19, s19, s20
	s_lshl_b32 s19, s19, 10
	s_and_b32 s21, s17, 7
	s_lshl_b32 s21, s21, 7
	s_add_u32 s19, s19, s21
	s_add_u32 s19, s19, 0x7900000
	s_add_u32 s14, s80, s19
	s_addc_u32 s15, s81, 0
	global_load_dwordx4 v[98:101], v237, s[12:13] offset:0
	global_load_dwordx4 v[102:105], v237, s[12:13] offset:32
	global_load_dwordx4 v[106:109], v237, s[12:13] offset:64
	global_load_dwordx4 v[110:113], v237, s[12:13] offset:96
	global_load_dwordx4 v[114:117], v237, s[12:13] offset:128
	global_load_dwordx4 v[118:121], v237, s[12:13] offset:160
	global_load_dwordx4 v[34:37], v226, s[4:5]
	global_load_dwordx4 v[38:41], v227, s[4:5]
	global_load_dwordx4 v[42:45], v228, s[4:5]
	global_load_dwordx4 v[46:49], v229, s[10:11]
	s_add_u32 s4, s4, 0x6000
	s_addc_u32 s5, s5, 0
	global_load_dwordx4 v[50:53], v226, s[4:5]
	global_load_dwordx4 v[54:57], v227, s[4:5]
	global_load_dwordx4 v[58:61], v228, s[4:5]
	global_load_dwordx4 v[62:65], v229, s[10:11] offset:128
	global_load_dwordx4 v[216:219], v229, s[10:11] offset:256
	s_add_u32 s4, s4, 0x6000
	s_addc_u32 s5, s5, 0
	s_add_u32 s10, s10, 0x180
	s_addc_u32 s11, s11, 0
.Lmla_nopf:
	ds_read_b128 v[162:165], v221 offset:27648
	ds_read_b128 v[166:169], v221 offset:32256
	ds_read_b128 v[170:173], v221 offset:27680
	v_exp_f32_e32 v66, v66
	v_exp_f32_e32 v67, v67
	v_exp_f32_e32 v68, v68
	v_exp_f32_e32 v69, v69
	v_add_f32_e32 v231, v231, v66
	v_add_f32_e32 v232, v232, v67
	v_exp_f32_e32 v70, v70
	v_exp_f32_e32 v71, v71
	v_add_f32_e32 v231, v231, v68
	v_add_f32_e32 v232, v232, v69
	v_exp_f32_e32 v72, v72
	v_exp_f32_e32 v73, v73
	v_add_f32_e32 v231, v231, v70
	v_add_f32_e32 v232, v232, v71
	v_add_f32_e32 v231, v231, v72
	v_add_f32_e32 v232, v232, v73
	v_cvt_pk_bf16_f32 v66, v66, v67
	v_cvt_pk_bf16_f32 v67, v68, v69
	v_cvt_pk_bf16_f32 v68, v70, v71
	v_cvt_pk_bf16_f32 v69, v72, v73
	s_waitcnt lgkmcnt(1)
	s_nop 0
	v_mfma_f32_32x32x16_bf16 v[2:17], v[162:165], v[66:69], v[2:17]
	ds_read_b128 v[174:177], v221 offset:32288
	v_mfma_f32_32x32x16_bf16 v[18:33], v[166:169], v[66:69], v[18:33]
	ds_read_b128 v[180:183], v221 offset:27712
	v_exp_f32_e32 v74, v74
	v_exp_f32_e32 v75, v75
	v_exp_f32_e32 v76, v76
	v_exp_f32_e32 v77, v77
	v_add_f32_e32 v231, v231, v74
	v_add_f32_e32 v232, v232, v75
	v_exp_f32_e32 v78, v78
	v_exp_f32_e32 v79, v79
	v_add_f32_e32 v231, v231, v76
	v_add_f32_e32 v232, v232, v77
	v_exp_f32_e32 v80, v80
	v_exp_f32_e32 v81, v81
	v_add_f32_e32 v231, v231, v78
	v_add_f32_e32 v232, v232, v79
	v_add_f32_e32 v231, v231, v80
	v_add_f32_e32 v232, v232, v81
	v_cvt_pk_bf16_f32 v74, v74, v75
	v_cvt_pk_bf16_f32 v75, v76, v77
	v_cvt_pk_bf16_f32 v76, v78, v79
	v_cvt_pk_bf16_f32 v77, v80, v81
	s_waitcnt lgkmcnt(1)
	s_nop 0
	v_mfma_f32_32x32x16_bf16 v[2:17], v[170:173], v[74:77], v[2:17]
	ds_read_b128 v[184:187], v221 offset:32320
	v_mfma_f32_32x32x16_bf16 v[18:33], v[174:177], v[74:77], v[18:33]
	ds_read_b128 v[188:191], v221 offset:27744
	v_exp_f32_e32 v82, v82
	v_exp_f32_e32 v83, v83
	v_exp_f32_e32 v84, v84
	v_exp_f32_e32 v85, v85
	v_add_f32_e32 v231, v231, v82
	v_add_f32_e32 v232, v232, v83
	v_exp_f32_e32 v86, v86
	v_exp_f32_e32 v87, v87
	v_add_f32_e32 v231, v231, v84
	v_add_f32_e32 v232, v232, v85
	v_exp_f32_e32 v88, v88
	v_exp_f32_e32 v89, v89
	v_add_f32_e32 v231, v231, v86
	v_add_f32_e32 v232, v232, v87
	v_add_f32_e32 v231, v231, v88
	v_add_f32_e32 v232, v232, v89
	v_cvt_pk_bf16_f32 v82, v82, v83
	v_cvt_pk_bf16_f32 v83, v84, v85
	v_cvt_pk_bf16_f32 v84, v86, v87
	v_cvt_pk_bf16_f32 v85, v88, v89
	s_waitcnt lgkmcnt(1)
	s_nop 0
	v_mfma_f32_32x32x16_bf16 v[2:17], v[180:183], v[82:85], v[2:17]
	ds_read_b128 v[192:195], v221 offset:32352
	v_mfma_f32_32x32x16_bf16 v[18:33], v[184:187], v[82:85], v[18:33]
	v_exp_f32_e32 v90, v90
	v_exp_f32_e32 v91, v91
	v_exp_f32_e32 v92, v92
	v_exp_f32_e32 v93, v93
	v_add_f32_e32 v231, v231, v90
	v_add_f32_e32 v232, v232, v91
	v_exp_f32_e32 v94, v94
	v_exp_f32_e32 v95, v95
	v_add_f32_e32 v231, v231, v92
	v_add_f32_e32 v232, v232, v93
	v_exp_f32_e32 v96, v96
	v_exp_f32_e32 v97, v97
	v_add_f32_e32 v231, v231, v94
	v_add_f32_e32 v232, v232, v95
	v_add_f32_e32 v231, v231, v96
	v_add_f32_e32 v232, v232, v97
	v_cvt_pk_bf16_f32 v90, v90, v91
	v_cvt_pk_bf16_f32 v91, v92, v93
	v_cvt_pk_bf16_f32 v92, v94, v95
	v_cvt_pk_bf16_f32 v93, v96, v97
	s_waitcnt lgkmcnt(0)
	s_nop 0
	v_mfma_f32_32x32x16_bf16 v[2:17], v[188:191], v[90:93], v[2:17]
	v_mfma_f32_32x32x16_bf16 v[18:33], v[192:195], v[90:93], v[18:33]
	s_waitcnt lgkmcnt(0)
	s_barrier
	v_add_f32_e32 v231, v231, v232
	v_mov_b32_e32 v235, v231
	s_nop 1
	v_permlane32_swap_b32_e32 v231, v235
	v_add_f32_e32 v234, v231, v235
	v_mov_b32_e32 v233, v234
	v_div_scale_f32 v235, s[22:23], v234, v234, 1.0
	v_rcp_f32_e32 v179, v235
	v_div_scale_f32 v196, vcc, 1.0, v234, 1.0
	v_fma_f32 v197, -v235, v179, 1.0
	v_fmac_f32_e32 v179, v197, v179
	v_mul_f32_e32 v197, v196, v179
	v_fma_f32 v199, -v235, v197, v196
	v_fmac_f32_e32 v197, v199, v179
	v_fma_f32 v235, -v235, v197, v196
	v_div_fmas_f32 v235, v235, v179, v197
	v_div_fixup_f32 v234, v235, v234, 1.0
	s_nop 15
	v_mul_f32_e32 v2, v2, v234
	v_mul_f32_e32 v3, v3, v234
	v_mul_f32_e32 v4, v4, v234
	v_mul_f32_e32 v5, v5, v234
	v_mul_f32_e32 v6, v6, v234
	v_mul_f32_e32 v7, v7, v234
	v_mul_f32_e32 v8, v8, v234
	v_mul_f32_e32 v9, v9, v234
	v_mul_f32_e32 v10, v10, v234
	v_mul_f32_e32 v11, v11, v234
	v_mul_f32_e32 v12, v12, v234
	v_mul_f32_e32 v13, v13, v234
	v_mul_f32_e32 v14, v14, v234
	v_mul_f32_e32 v15, v15, v234
	v_mul_f32_e32 v16, v16, v234
	v_mul_f32_e32 v17, v17, v234
	v_mul_f32_e32 v18, v18, v234
	v_mul_f32_e32 v19, v19, v234
	v_mul_f32_e32 v20, v20, v234
	v_mul_f32_e32 v21, v21, v234
	v_mul_f32_e32 v22, v22, v234
	v_mul_f32_e32 v23, v23, v234
	v_mul_f32_e32 v24, v24, v234
	v_mul_f32_e32 v25, v25, v234
	v_mul_f32_e32 v26, v26, v234
	v_mul_f32_e32 v27, v27, v234
	v_mul_f32_e32 v28, v28, v234
	v_mul_f32_e32 v29, v29, v234
	v_mul_f32_e32 v30, v30, v234
	v_mul_f32_e32 v31, v31, v234
	v_mul_f32_e32 v32, v32, v234
	v_mul_f32_e32 v33, v33, v234
	v_mov_b32_e32 v235, 0
	v_fmac_f32_e32 v235, 0, v2
	v_fmac_f32_e32 v235, 0, v3
	v_fmac_f32_e32 v235, 0, v4
	v_fmac_f32_e32 v235, 0, v5
	v_fmac_f32_e32 v235, 0, v6
	v_fmac_f32_e32 v235, 0, v7
	v_fmac_f32_e32 v235, 0, v8
	v_fmac_f32_e32 v235, 0, v9
	v_fmac_f32_e32 v235, 0, v10
	v_fmac_f32_e32 v235, 0, v11
	v_fmac_f32_e32 v235, 0, v12
	v_fmac_f32_e32 v235, 0, v13
	v_fmac_f32_e32 v235, 0, v14
	v_fmac_f32_e32 v235, 0, v15
	v_fmac_f32_e32 v235, 0, v16
	v_fmac_f32_e32 v235, 0, v17
	v_fmac_f32_e32 v235, 0, v18
	v_fmac_f32_e32 v235, 0, v19
	v_fmac_f32_e32 v235, 0, v20
	v_fmac_f32_e32 v235, 0, v21
	v_fmac_f32_e32 v235, 0, v22
	v_fmac_f32_e32 v235, 0, v23
	v_fmac_f32_e32 v235, 0, v24
	v_fmac_f32_e32 v235, 0, v25
	v_fmac_f32_e32 v235, 0, v26
	v_fmac_f32_e32 v235, 0, v27
	v_fmac_f32_e32 v235, 0, v28
	v_fmac_f32_e32 v235, 0, v29
	v_fmac_f32_e32 v235, 0, v30
	v_fmac_f32_e32 v235, 0, v31
	v_fmac_f32_e32 v235, 0, v32
	v_fmac_f32_e32 v235, 0, v33
	v_fmac_f32_e32 v235, 0, v233
	v_cmp_u_f32_e32 vcc, v235, v235
	s_cmp_lg_u64 vcc, 0
	s_cselect_b32 s26, 1, 0
	v_mov_b32_e32 v179, 0x186a0
	v_mov_b32_e32 v196, s26
	ds_or_b32 v179, v196
	s_waitcnt lgkmcnt(0)
	s_barrier
	ds_read_b32 v196, v179
	s_waitcnt lgkmcnt(0)
	v_readfirstlane_b32 s26, v196
	s_barrier
	v_mov_b32_e32 v196, 0
	ds_write_b32 v179, v196
	s_cmp_lg_u32 s26, 0
	s_cbranch_scc1 .Lmla_redo
	s_cmpk_lt_i32 s2, 0x200
	s_cbranch_scc1 .Lmla_zw15
	s_waitcnt vmcnt(0)
	s_branch .Lmla_zw

.Lmla_zw:
	v_lshlrev_b32_e32 v179, 16, v200
	v_and_b32_e32 v196, 0xffff0000, v200
	v_lshlrev_b32_e32 v197, 16, v201
	v_and_b32_e32 v199, 0xffff0000, v201
	v_mul_f32_e32 v2, v2, v179
	v_mul_f32_e32 v3, v3, v196
	v_mul_f32_e32 v4, v4, v197
	v_mul_f32_e32 v5, v5, v199
	v_cvt_pk_bf16_f32 v200, v2, v3
	v_cvt_pk_bf16_f32 v201, v4, v5
	global_store_dwordx2 v236, v[200:201], s[24:25] offset:0
	v_lshlrev_b32_e32 v179, 16, v202
	v_and_b32_e32 v196, 0xffff0000, v202
	v_lshlrev_b32_e32 v197, 16, v203
	v_and_b32_e32 v199, 0xffff0000, v203
	v_mul_f32_e32 v6, v6, v179
	v_mul_f32_e32 v7, v7, v196
	v_mul_f32_e32 v8, v8, v197
	v_mul_f32_e32 v9, v9, v199
	v_cvt_pk_bf16_f32 v202, v6, v7
	v_cvt_pk_bf16_f32 v203, v8, v9
	global_store_dwordx2 v236, v[202:203], s[24:25] offset:16
	v_lshlrev_b32_e32 v179, 16, v204
	v_and_b32_e32 v196, 0xffff0000, v204
	v_lshlrev_b32_e32 v197, 16, v205
	v_and_b32_e32 v199, 0xffff0000, v205
	v_mul_f32_e32 v10, v10, v179
	v_mul_f32_e32 v11, v11, v196
	v_mul_f32_e32 v12, v12, v197
	v_mul_f32_e32 v13, v13, v199
	v_cvt_pk_bf16_f32 v204, v10, v11
	v_cvt_pk_bf16_f32 v205, v12, v13
	global_store_dwordx2 v236, v[204:205], s[24:25] offset:32
	v_lshlrev_b32_e32 v179, 16, v206
	v_and_b32_e32 v196, 0xffff0000, v206
	v_lshlrev_b32_e32 v197, 16, v207
	v_and_b32_e32 v199, 0xffff0000, v207
	v_mul_f32_e32 v14, v14, v179
	v_mul_f32_e32 v15, v15, v196
	v_mul_f32_e32 v16, v16, v197
	v_mul_f32_e32 v17, v17, v199
	v_cvt_pk_bf16_f32 v206, v14, v15
	v_cvt_pk_bf16_f32 v207, v16, v17
	global_store_dwordx2 v236, v[206:207], s[24:25] offset:48
	v_lshlrev_b32_e32 v179, 16, v208
	v_and_b32_e32 v196, 0xffff0000, v208
	v_lshlrev_b32_e32 v197, 16, v209
	v_and_b32_e32 v199, 0xffff0000, v209
	v_mul_f32_e32 v18, v18, v179
	v_mul_f32_e32 v19, v19, v196
	v_mul_f32_e32 v20, v20, v197
	v_mul_f32_e32 v21, v21, v199
	v_cvt_pk_bf16_f32 v208, v18, v19
	v_cvt_pk_bf16_f32 v209, v20, v21
	global_store_dwordx2 v236, v[208:209], s[24:25] offset:64
	v_lshlrev_b32_e32 v179, 16, v210
	v_and_b32_e32 v196, 0xffff0000, v210
	v_lshlrev_b32_e32 v197, 16, v211
	v_and_b32_e32 v199, 0xffff0000, v211
	v_mul_f32_e32 v22, v22, v179
	v_mul_f32_e32 v23, v23, v196
	v_mul_f32_e32 v24, v24, v197
	v_mul_f32_e32 v25, v25, v199
	v_cvt_pk_bf16_f32 v210, v22, v23
	v_cvt_pk_bf16_f32 v211, v24, v25
	global_store_dwordx2 v236, v[210:211], s[24:25] offset:80
	v_lshlrev_b32_e32 v179, 16, v212
	v_and_b32_e32 v196, 0xffff0000, v212
	v_lshlrev_b32_e32 v197, 16, v213
	v_and_b32_e32 v199, 0xffff0000, v213
	v_mul_f32_e32 v26, v26, v179
	v_mul_f32_e32 v27, v27, v196
	v_mul_f32_e32 v28, v28, v197
	v_mul_f32_e32 v29, v29, v199
	v_cvt_pk_bf16_f32 v212, v26, v27
	v_cvt_pk_bf16_f32 v213, v28, v29
	global_store_dwordx2 v236, v[212:213], s[24:25] offset:96
	v_lshlrev_b32_e32 v179, 16, v214
	v_and_b32_e32 v196, 0xffff0000, v214
	v_lshlrev_b32_e32 v197, 16, v215
	v_and_b32_e32 v199, 0xffff0000, v215
	v_mul_f32_e32 v30, v30, v179
	v_mul_f32_e32 v31, v31, v196
	v_mul_f32_e32 v32, v32, v197
	v_mul_f32_e32 v33, v33, v199
	v_cvt_pk_bf16_f32 v214, v30, v31
	v_cvt_pk_bf16_f32 v215, v32, v33
	global_store_dwordx2 v236, v[214:215], s[24:25] offset:112
	s_cmpk_lt_i32 s2, 0x200
	s_cbranch_scc0 .Lmla_exit
	v_mov_b32_e32 v2, 0
	v_mov_b32_e32 v3, 0
	v_mov_b32_e32 v4, 0
	v_mov_b32_e32 v5, 0
	v_mov_b32_e32 v6, 0
	v_mov_b32_e32 v7, 0
	v_mov_b32_e32 v8, 0
	v_mov_b32_e32 v9, 0
	v_mov_b32_e32 v10, 0
	v_mov_b32_e32 v11, 0
	v_mov_b32_e32 v12, 0
	v_mov_b32_e32 v13, 0
	v_mov_b32_e32 v14, 0
	v_mov_b32_e32 v15, 0
	v_mov_b32_e32 v16, 0
	v_mov_b32_e32 v17, 0
	v_mov_b32_e32 v18, 0
	v_mov_b32_e32 v19, 0
	v_mov_b32_e32 v20, 0
	v_mov_b32_e32 v21, 0
	v_mov_b32_e32 v22, 0
	v_mov_b32_e32 v23, 0
	v_mov_b32_e32 v24, 0
	v_mov_b32_e32 v25, 0
	v_mov_b32_e32 v26, 0
	v_mov_b32_e32 v27, 0
	v_mov_b32_e32 v28, 0
	v_mov_b32_e32 v29, 0
	v_mov_b32_e32 v30, 0
	v_mov_b32_e32 v31, 0
	v_mov_b32_e32 v32, 0
	v_mov_b32_e32 v33, 0
	v_mov_b32_e32 v122, 0
	v_mov_b32_e32 v123, 0
	v_mov_b32_e32 v124, 0
	v_mov_b32_e32 v125, 0
	v_mov_b32_e32 v126, 0
	v_mov_b32_e32 v127, 0
	v_mov_b32_e32 v128, 0
	v_mov_b32_e32 v129, 0
	v_mov_b32_e32 v130, 0
	v_mov_b32_e32 v131, 0
	v_mov_b32_e32 v132, 0
	v_mov_b32_e32 v133, 0
	v_mov_b32_e32 v134, 0
	v_mov_b32_e32 v135, 0
	v_mov_b32_e32 v136, 0
	v_mov_b32_e32 v137, 0
	v_mov_b32_e32 v230, 0
	v_mov_b32_e32 v231, 0
	v_mov_b32_e32 v232, 0
	s_waitcnt vmcnt(13)
	ds_write_b128 v222, v[34:37]
	ds_write_b128 v223, v[38:41]
	ds_write_b128 v224, v[42:45]
	ds_write_b64 v225, v[46:47]
	ds_write_b64 v225, v[48:49] offset:16
	s_waitcnt vmcnt(9)
	ds_write_b128 v222, v[50:53] offset:26624
	ds_write_b128 v223, v[54:57] offset:26624
	ds_write_b128 v224, v[58:61] offset:26624
	ds_write_b64 v225, v[62:63] offset:9216
	ds_write_b64 v225, v[64:65] offset:9232
	s_waitcnt lgkmcnt(0)
	s_barrier
	s_branch .Lmla_body
.Lmla_redo:
	s_sub_i32 s2, s2, s88
	s_waitcnt vmcnt(0)
	s_lshr_b32 s17, s2, 4
	s_and_b32 s18, s2, 15
	s_mul_i32 s19, s17, 0xcc000
	s_add_u32 s4, s78, s19
	s_addc_u32 s5, s79, 0
	s_mul_i32 s19, s17, 0x88000
	s_add_u32 s19, s19, 0x1a00000
	s_add_u32 s10, s78, s19
	s_addc_u32 s11, s79, 0
	s_lshl_b32 s19, s17, 12
	s_lshl_b32 s20, s18, 8
	s_add_u32 s19, s19, s20
	s_mul_i32 s19, s19, 0xc0
	s_add_u32 s19, s19, 0x1400000
	s_add_u32 s12, s80, s19
	s_addc_u32 s13, s81, 0
	s_lshr_b32 s19, s17, 3
	s_lshl_b32 s19, s19, 12
	s_add_u32 s19, s19, s20
	s_lshl_b32 s19, s19, 10
	s_and_b32 s21, s17, 7
	s_lshl_b32 s21, s21, 7
	s_add_u32 s19, s19, s21
	s_add_u32 s19, s19, 0x7900000
	s_add_u32 s14, s80, s19
	s_addc_u32 s15, s81, 0
	global_load_dwordx4 v[98:101], v237, s[12:13] offset:0
	global_load_dwordx4 v[102:105], v237, s[12:13] offset:32
	global_load_dwordx4 v[106:109], v237, s[12:13] offset:64
	global_load_dwordx4 v[110:113], v237, s[12:13] offset:96
	global_load_dwordx4 v[114:117], v237, s[12:13] offset:128
	global_load_dwordx4 v[118:121], v237, s[12:13] offset:160
	global_load_dwordx4 v[200:203], v226, s[4:5]
	global_load_dwordx4 v[204:207], v227, s[4:5]
	global_load_dwordx4 v[208:211], v228, s[4:5]
	global_load_dwordx4 v[66:69], v229, s[10:11]
	s_add_u32 s4, s4, 0x6000
	s_addc_u32 s5, s5, 0
	global_load_dwordx4 v[70:73], v226, s[4:5]
	global_load_dwordx4 v[74:77], v227, s[4:5]
	global_load_dwordx4 v[78:81], v228, s[4:5]
	global_load_dwordx4 v[82:85], v229, s[10:11] offset:128
	global_load_dwordx4 v[216:219], v229, s[10:11] offset:256
	s_add_u32 s4, s4, 0x6000
	s_addc_u32 s5, s5, 0
	s_add_u32 s10, s10, 0x180
	s_addc_u32 s11, s11, 0
	v_mov_b32_e32 v2, 0
	v_mov_b32_e32 v3, 0
	v_mov_b32_e32 v4, 0
	v_mov_b32_e32 v5, 0
	v_mov_b32_e32 v6, 0
	v_mov_b32_e32 v7, 0
	v_mov_b32_e32 v8, 0
	v_mov_b32_e32 v9, 0
	v_mov_b32_e32 v10, 0
	v_mov_b32_e32 v11, 0
	v_mov_b32_e32 v12, 0
	v_mov_b32_e32 v13, 0
	v_mov_b32_e32 v14, 0
	v_mov_b32_e32 v15, 0
	v_mov_b32_e32 v16, 0
	v_mov_b32_e32 v17, 0
	v_mov_b32_e32 v18, 0
	v_mov_b32_e32 v19, 0
	v_mov_b32_e32 v20, 0
	v_mov_b32_e32 v21, 0
	v_mov_b32_e32 v22, 0
	v_mov_b32_e32 v23, 0
	v_mov_b32_e32 v24, 0
	v_mov_b32_e32 v25, 0
	v_mov_b32_e32 v26, 0
	v_mov_b32_e32 v27, 0
	v_mov_b32_e32 v28, 0
	v_mov_b32_e32 v29, 0
	v_mov_b32_e32 v30, 0
	v_mov_b32_e32 v31, 0
	v_mov_b32_e32 v32, 0
	v_mov_b32_e32 v33, 0
	v_mov_b32_e32 v122, 0
	v_mov_b32_e32 v123, 0
	v_mov_b32_e32 v124, 0
	v_mov_b32_e32 v125, 0
	v_mov_b32_e32 v126, 0
	v_mov_b32_e32 v127, 0
	v_mov_b32_e32 v128, 0
	v_mov_b32_e32 v129, 0
	v_mov_b32_e32 v130, 0
	v_mov_b32_e32 v131, 0
	v_mov_b32_e32 v132, 0
	v_mov_b32_e32 v133, 0
	v_mov_b32_e32 v134, 0
	v_mov_b32_e32 v135, 0
	v_mov_b32_e32 v136, 0
	v_mov_b32_e32 v137, 0
	v_mov_b32_e32 v230, 0
	v_mov_b32_e32 v231, 0
	v_mov_b32_e32 v232, 0
	s_waitcnt vmcnt(5)
	ds_write_b128 v222, v[200:203]
	ds_write_b128 v223, v[204:207]
	ds_write_b128 v224, v[208:211]
	ds_write_b64 v225, v[66:67]
	ds_write_b64 v225, v[68:69] offset:16
	s_waitcnt vmcnt(1)
	ds_write_b128 v222, v[70:73] offset:26624
	ds_write_b128 v223, v[74:77] offset:26624
	ds_write_b128 v224, v[78:81] offset:26624
	ds_write_b64 v225, v[82:83] offset:9216
	ds_write_b64 v225, v[84:85] offset:9232
	s_waitcnt lgkmcnt(0)
	s_barrier
	ds_read_b128 v[138:141], v220 offset:0
	ds_read_b128 v[142:145], v220 offset:6656
	ds_read_b128 v[146:149], v220 offset:32
	ds_read_b128 v[150:153], v220 offset:6688
	ds_read_b128 v[154:157], v220 offset:64
	ds_read_b128 v[158:161], v220 offset:6720
	ds_read_b128 v[66:69], v220 offset:96
	ds_read_b128 v[70:73], v220 offset:6752
	ds_read_b128 v[74:77], v220 offset:128
	ds_read_b128 v[78:81], v220 offset:6784
	ds_read_b128 v[82:85], v220 offset:160
	ds_read_b128 v[86:89], v220 offset:6816
	s_waitcnt lgkmcnt(11)
	v_mfma_f32_32x32x16_bf16 v[34:49], v[138:141], v[98:101], v[122:137]
	s_waitcnt lgkmcnt(10)
	v_mfma_f32_32x32x16_bf16 v[50:65], v[142:145], v[98:101], v[122:137]
	s_waitcnt lgkmcnt(9)
	v_mfma_f32_32x32x16_bf16 v[34:49], v[146:149], v[102:105], v[34:49]
	s_waitcnt lgkmcnt(8)
	v_mfma_f32_32x32x16_bf16 v[50:65], v[150:153], v[102:105], v[50:65]
	s_waitcnt lgkmcnt(7)
	v_mfma_f32_32x32x16_bf16 v[34:49], v[154:157], v[106:109], v[34:49]
	s_waitcnt lgkmcnt(6)
	v_mfma_f32_32x32x16_bf16 v[50:65], v[158:161], v[106:109], v[50:65]
	s_waitcnt lgkmcnt(5)
	v_mfma_f32_32x32x16_bf16 v[34:49], v[66:69], v[110:113], v[34:49]
	s_waitcnt lgkmcnt(4)
	v_mfma_f32_32x32x16_bf16 v[50:65], v[70:73], v[110:113], v[50:65]
	s_waitcnt lgkmcnt(3)
	v_mfma_f32_32x32x16_bf16 v[34:49], v[74:77], v[114:117], v[34:49]
	s_waitcnt lgkmcnt(2)
	v_mfma_f32_32x32x16_bf16 v[50:65], v[78:81], v[114:117], v[50:65]
	s_waitcnt lgkmcnt(1)
	v_mfma_f32_32x32x16_bf16 v[34:49], v[82:85], v[118:121], v[34:49]
	s_waitcnt lgkmcnt(0)
	v_mfma_f32_32x32x16_bf16 v[50:65], v[86:89], v[118:121], v[50:65]
	s_nop 15
	v_max3_f32 v234, v34, v35, v36
	v_max3_f32 v235, v50, v51, v52
	v_max3_f32 v234, v234, v37, v38
	v_max3_f32 v235, v235, v53, v54
	v_max3_f32 v234, v234, v39, v40
	v_max3_f32 v235, v235, v55, v56
	v_max3_f32 v234, v234, v41, v42
	v_max3_f32 v235, v235, v57, v58
	v_max3_f32 v234, v234, v43, v44
	v_max3_f32 v235, v235, v59, v60
	v_max3_f32 v234, v234, v45, v46
	v_max3_f32 v235, v235, v61, v62
	v_max3_f32 v234, v234, v47, v48
	v_max3_f32 v235, v235, v63, v64
	v_max3_f32 v234, v234, v49, v65
	v_max_f32_e32 v234, v234, v235
	v_mov_b32_e32 v235, v234
	s_nop 1
	v_permlane32_swap_b32_e32 v234, v235
	v_max_f32_e32 v233, v234, v235
	s_nop 15
	v_add_f32_e32 v230, v230, v233
	v_sub_f32_e32 v34, v34, v233
	v_sub_f32_e32 v35, v35, v233
	v_sub_f32_e32 v36, v36, v233
	v_sub_f32_e32 v37, v37, v233
	v_sub_f32_e32 v38, v38, v233
	v_sub_f32_e32 v39, v39, v233
	v_sub_f32_e32 v40, v40, v233
	v_sub_f32_e32 v41, v41, v233
	v_sub_f32_e32 v42, v42, v233
	v_sub_f32_e32 v43, v43, v233
	v_sub_f32_e32 v44, v44, v233
	v_sub_f32_e32 v45, v45, v233
	v_sub_f32_e32 v46, v46, v233
	v_sub_f32_e32 v47, v47, v233
	v_sub_f32_e32 v48, v48, v233
	v_sub_f32_e32 v49, v49, v233
	v_sub_f32_e32 v50, v50, v233
	v_sub_f32_e32 v51, v51, v233
	v_sub_f32_e32 v52, v52, v233
	v_sub_f32_e32 v53, v53, v233
	v_sub_f32_e32 v54, v54, v233
	v_sub_f32_e32 v55, v55, v233
	v_sub_f32_e32 v56, v56, v233
	v_sub_f32_e32 v57, v57, v233
	v_sub_f32_e32 v58, v58, v233
	v_sub_f32_e32 v59, v59, v233
	v_sub_f32_e32 v60, v60, v233
	v_sub_f32_e32 v61, v61, v233
	v_sub_f32_e32 v62, v62, v233
	v_sub_f32_e32 v63, v63, v233
	v_sub_f32_e32 v64, v64, v233
	v_sub_f32_e32 v65, v65, v233
	v_sub_f32_e32 v122, 0, v230
	v_mov_b32_e32 v123, v122
	v_mov_b32_e32 v124, v122
	v_mov_b32_e32 v125, v122
	v_mov_b32_e32 v126, v122
	v_mov_b32_e32 v127, v122
	v_mov_b32_e32 v128, v122
	v_mov_b32_e32 v129, v122
	v_mov_b32_e32 v130, v122
	v_mov_b32_e32 v131, v122
	v_mov_b32_e32 v132, v122
	v_mov_b32_e32 v133, v122
	v_mov_b32_e32 v134, v122
	v_mov_b32_e32 v135, v122
	v_mov_b32_e32 v136, v122
	v_mov_b32_e32 v137, v122
	ds_read_b128 v[138:141], v220 offset:13312
	ds_read_b128 v[142:145], v220 offset:19968
	ds_read_b128 v[146:149], v220 offset:13344
	ds_read_b128 v[150:153], v220 offset:20000
	ds_read_b128 v[154:157], v220 offset:13376
	ds_read_b128 v[158:161], v220 offset:20032
	s_movk_i32 s16, 16
.Lmls_loop:
	v_exp_f32_e32 v34, v34
	v_exp_f32_e32 v35, v35
	v_exp_f32_e32 v36, v36
	v_exp_f32_e32 v37, v37
	s_waitcnt lgkmcnt(4)
	v_mfma_f32_32x32x16_bf16 v[66:81], v[138:141], v[98:101], v[122:137]
	ds_read_b128 v[138:141], v220 offset:13408
	v_add_f32_e32 v231, v231, v34
	v_add_f32_e32 v232, v232, v35
	v_exp_f32_e32 v38, v38
	v_exp_f32_e32 v39, v39
	v_mfma_f32_32x32x16_bf16 v[82:97], v[142:145], v[98:101], v[122:137]
	ds_read_b128 v[142:145], v220 offset:20064
	v_add_f32_e32 v231, v231, v36
	v_add_f32_e32 v232, v232, v37
	v_exp_f32_e32 v40, v40
	v_exp_f32_e32 v41, v41
	s_waitcnt lgkmcnt(4)
	v_mfma_f32_32x32x16_bf16 v[66:81], v[146:149], v[102:105], v[66:81]
	ds_read_b128 v[146:149], v220 offset:13440
	global_load_dwordx4 v[200:203], v226, s[4:5]
	global_load_dwordx4 v[204:207], v227, s[4:5]
	global_load_dwordx4 v[208:211], v228, s[4:5]
	s_add_u32 s4, s4, 0x6000
	s_addc_u32 s5, s5, 0
	global_load_dwordx4 v[212:215], v229, s[10:11]
	s_add_u32 s10, s10, 0x80
	s_addc_u32 s11, s11, 0
	v_add_f32_e32 v231, v231, v38
	v_add_f32_e32 v232, v232, v39
	v_add_f32_e32 v231, v231, v40
	v_add_f32_e32 v232, v232, v41
	v_cvt_pk_bf16_f32 v34, v34, v35
	v_cvt_pk_bf16_f32 v35, v36, v37
	v_mfma_f32_32x32x16_bf16 v[82:97], v[150:153], v[102:105], v[82:97]
	ds_read_b128 v[150:153], v220 offset:20096
	v_cvt_pk_bf16_f32 v36, v38, v39
	v_cvt_pk_bf16_f32 v37, v40, v41
	v_exp_f32_e32 v42, v42
	v_exp_f32_e32 v43, v43
	s_waitcnt lgkmcnt(4)
	v_mfma_f32_32x32x16_bf16 v[66:81], v[154:157], v[106:109], v[66:81]
	ds_read_b128 v[154:157], v220 offset:13472
	v_exp_f32_e32 v44, v44
	v_exp_f32_e32 v45, v45
	v_add_f32_e32 v231, v231, v42
	v_add_f32_e32 v232, v232, v43
	v_mfma_f32_32x32x16_bf16 v[82:97], v[158:161], v[106:109], v[82:97]
	ds_read_b128 v[158:161], v220 offset:20128
	v_exp_f32_e32 v46, v46
	v_exp_f32_e32 v47, v47
	v_add_f32_e32 v231, v231, v44
	v_add_f32_e32 v232, v232, v45
	v_exp_f32_e32 v48, v48
	s_waitcnt lgkmcnt(4)
	v_mfma_f32_32x32x16_bf16 v[66:81], v[138:141], v[110:113], v[66:81]
	ds_read_b128 v[162:165], v221 offset:0
	v_exp_f32_e32 v49, v49
	v_add_f32_e32 v231, v231, v46
	v_add_f32_e32 v232, v232, v47
	v_add_f32_e32 v231, v231, v48
	v_mfma_f32_32x32x16_bf16 v[82:97], v[142:145], v[110:113], v[82:97]
	ds_read_b128 v[166:169], v221 offset:4608
	v_add_f32_e32 v232, v232, v49
	v_cvt_pk_bf16_f32 v42, v42, v43
	v_cvt_pk_bf16_f32 v43, v44, v45
	v_cvt_pk_bf16_f32 v44, v46, v47
	v_cvt_pk_bf16_f32 v45, v48, v49
	v_exp_f32_e32 v50, v50
	s_waitcnt lgkmcnt(4)
	v_mfma_f32_32x32x16_bf16 v[66:81], v[146:149], v[114:117], v[66:81]
	ds_read_b128 v[170:173], v221 offset:32
	v_exp_f32_e32 v51, v51
	v_exp_f32_e32 v52, v52
	v_exp_f32_e32 v53, v53
	v_mfma_f32_32x32x16_bf16 v[82:97], v[150:153], v[114:117], v[82:97]
	ds_read_b128 v[174:177], v221 offset:4640
	v_add_f32_e32 v231, v231, v50
	v_add_f32_e32 v232, v232, v51
	v_exp_f32_e32 v54, v54
	v_exp_f32_e32 v55, v55
	s_waitcnt lgkmcnt(4)
	v_mfma_f32_32x32x16_bf16 v[66:81], v[154:157], v[118:121], v[66:81]
	ds_read_b128 v[180:183], v221 offset:64
	v_add_f32_e32 v231, v231, v52
	v_add_f32_e32 v232, v232, v53
	v_exp_f32_e32 v56, v56
	v_exp_f32_e32 v57, v57
	v_mfma_f32_32x32x16_bf16 v[82:97], v[158:161], v[118:121], v[82:97]
	ds_read_b128 v[184:187], v221 offset:4672
	v_add_f32_e32 v231, v231, v54
	v_add_f32_e32 v232, v232, v55
	v_add_f32_e32 v231, v231, v56
	v_add_f32_e32 v232, v232, v57
	v_cvt_pk_bf16_f32 v50, v50, v51
	v_cvt_pk_bf16_f32 v51, v52, v53
	v_cvt_pk_bf16_f32 v52, v54, v55
	s_waitcnt lgkmcnt(4)
	v_mfma_f32_32x32x16_bf16 v[2:17], v[162:165], v[34:37], v[2:17]
	ds_read_b128 v[188:191], v221 offset:96
	v_cvt_pk_bf16_f32 v53, v56, v57
	v_exp_f32_e32 v58, v58
	v_exp_f32_e32 v59, v59
	v_exp_f32_e32 v60, v60
	v_mfma_f32_32x32x16_bf16 v[18:33], v[166:169], v[34:37], v[18:33]
	ds_read_b128 v[192:195], v221 offset:4704
	v_exp_f32_e32 v61, v61
	v_add_f32_e32 v231, v231, v58
	v_add_f32_e32 v232, v232, v59
	v_exp_f32_e32 v62, v62
	s_waitcnt lgkmcnt(4)
	v_mfma_f32_32x32x16_bf16 v[2:17], v[170:173], v[42:45], v[2:17]
	v_exp_f32_e32 v63, v63
	v_add_f32_e32 v231, v231, v60
	v_add_f32_e32 v232, v232, v61
	v_exp_f32_e32 v64, v64
	v_mfma_f32_32x32x16_bf16 v[18:33], v[174:177], v[42:45], v[18:33]
	s_waitcnt vmcnt(4)
	ds_write_b64 v225, v[216:217] offset:18432
	ds_write_b64 v225, v[218:219] offset:18448
	v_exp_f32_e32 v65, v65
	v_add_f32_e32 v231, v231, v62
	v_add_f32_e32 v232, v232, v63
	v_add_f32_e32 v231, v231, v64
	v_add_f32_e32 v232, v232, v65
	s_waitcnt lgkmcnt(4)
	v_mfma_f32_32x32x16_bf16 v[2:17], v[180:183], v[50:53], v[2:17]
	v_cvt_pk_bf16_f32 v58, v58, v59
	v_cvt_pk_bf16_f32 v59, v60, v61
	v_cvt_pk_bf16_f32 v60, v62, v63
	v_cvt_pk_bf16_f32 v61, v64, v65
	v_max3_f32 v234, v66, v67, v68
	v_max3_f32 v235, v82, v83, v84
	v_mfma_f32_32x32x16_bf16 v[18:33], v[184:187], v[50:53], v[18:33]
	v_max3_f32 v234, v234, v69, v70
	v_max3_f32 v235, v235, v85, v86
	v_max3_f32 v234, v234, v71, v72
	v_max3_f32 v235, v235, v87, v88
	v_max3_f32 v234, v234, v73, v74
	v_max3_f32 v235, v235, v89, v90
	v_max3_f32 v234, v234, v75, v76
	s_waitcnt lgkmcnt(2)
	v_mfma_f32_32x32x16_bf16 v[2:17], v[188:191], v[58:61], v[2:17]
	v_max3_f32 v235, v235, v91, v92
	v_max3_f32 v234, v234, v77, v78
	v_max3_f32 v235, v235, v93, v94
	v_max3_f32 v234, v234, v79, v80
	v_max3_f32 v235, v235, v95, v96
	v_max3_f32 v234, v234, v81, v97
	v_mfma_f32_32x32x16_bf16 v[18:33], v[192:195], v[58:61], v[18:33]
	v_max_f32_e32 v234, v234, v235
	v_mov_b32_e32 v235, v234
	s_nop 1
	v_permlane32_swap_b32_e32 v234, v235
	v_max_f32_e32 v233, v234, v235
	v_cmp_lt_f32_e32 vcc, 4.0, v233
	s_cbranch_vccz .Lmls_nr_p0
	s_nop 15
	v_max_f32_e32 v234, 0, v233
	v_exp_f32_e64 v235, -v234
	v_add_f32_e32 v230, v230, v234
	v_sub_f32_e32 v66, v66, v234
	v_sub_f32_e32 v67, v67, v234
	v_sub_f32_e32 v68, v68, v234
	v_sub_f32_e32 v69, v69, v234
	v_sub_f32_e32 v70, v70, v234
	v_sub_f32_e32 v71, v71, v234
	v_sub_f32_e32 v72, v72, v234
	v_sub_f32_e32 v73, v73, v234
	v_sub_f32_e32 v74, v74, v234
	v_sub_f32_e32 v75, v75, v234
	v_sub_f32_e32 v76, v76, v234
	v_sub_f32_e32 v77, v77, v234
	v_sub_f32_e32 v78, v78, v234
	v_sub_f32_e32 v79, v79, v234
	v_sub_f32_e32 v80, v80, v234
	v_sub_f32_e32 v81, v81, v234
	v_sub_f32_e32 v82, v82, v234
	v_sub_f32_e32 v83, v83, v234
	v_sub_f32_e32 v84, v84, v234
	v_sub_f32_e32 v85, v85, v234
	v_sub_f32_e32 v86, v86, v234
	v_sub_f32_e32 v87, v87, v234
	v_sub_f32_e32 v88, v88, v234
	v_sub_f32_e32 v89, v89, v234
	v_sub_f32_e32 v90, v90, v234
	v_sub_f32_e32 v91, v91, v234
	v_sub_f32_e32 v92, v92, v234
	v_sub_f32_e32 v93, v93, v234
	v_sub_f32_e32 v94, v94, v234
	v_sub_f32_e32 v95, v95, v234
	v_sub_f32_e32 v96, v96, v234
	v_sub_f32_e32 v97, v97, v234
	v_mul_f32_e32 v231, v231, v235
	v_mul_f32_e32 v232, v232, v235
	v_mul_f32_e32 v2, v2, v235
	v_mul_f32_e32 v3, v3, v235
	v_mul_f32_e32 v4, v4, v235
	v_mul_f32_e32 v5, v5, v235
	v_mul_f32_e32 v6, v6, v235
	v_mul_f32_e32 v7, v7, v235
	v_mul_f32_e32 v8, v8, v235
	v_mul_f32_e32 v9, v9, v235
	v_mul_f32_e32 v10, v10, v235
	v_mul_f32_e32 v11, v11, v235
	v_mul_f32_e32 v12, v12, v235
	v_mul_f32_e32 v13, v13, v235
	v_mul_f32_e32 v14, v14, v235
	v_mul_f32_e32 v15, v15, v235
	v_mul_f32_e32 v16, v16, v235
	v_mul_f32_e32 v17, v17, v235
	v_mul_f32_e32 v18, v18, v235
	v_mul_f32_e32 v19, v19, v235
	v_mul_f32_e32 v20, v20, v235
	v_mul_f32_e32 v21, v21, v235
	v_mul_f32_e32 v22, v22, v235
	v_mul_f32_e32 v23, v23, v235
	v_mul_f32_e32 v24, v24, v235
	v_mul_f32_e32 v25, v25, v235
	v_mul_f32_e32 v26, v26, v235
	v_mul_f32_e32 v27, v27, v235
	v_mul_f32_e32 v28, v28, v235
	v_mul_f32_e32 v29, v29, v235
	v_mul_f32_e32 v30, v30, v235
	v_mul_f32_e32 v31, v31, v235
	v_mul_f32_e32 v32, v32, v235
	v_mul_f32_e32 v33, v33, v235
	v_sub_f32_e32 v122, 0, v230
	v_mov_b32_e32 v123, v122
	v_mov_b32_e32 v124, v122
	v_mov_b32_e32 v125, v122
	v_mov_b32_e32 v126, v122
	v_mov_b32_e32 v127, v122
	v_mov_b32_e32 v128, v122
	v_mov_b32_e32 v129, v122
	v_mov_b32_e32 v130, v122
	v_mov_b32_e32 v131, v122
	v_mov_b32_e32 v132, v122
	v_mov_b32_e32 v133, v122
	v_mov_b32_e32 v134, v122
	v_mov_b32_e32 v135, v122
	v_mov_b32_e32 v136, v122
	v_mov_b32_e32 v137, v122
.Lmls_nr_p0:
	ds_read_b128 v[138:141], v220 offset:26624
	ds_read_b128 v[142:145], v220 offset:33280
	ds_read_b128 v[146:149], v220 offset:26656
	ds_read_b128 v[150:153], v220 offset:33312
	ds_read_b128 v[154:157], v220 offset:26688
	ds_read_b128 v[158:161], v220 offset:33344
	s_waitcnt lgkmcnt(6)
	s_barrier
	v_exp_f32_e32 v66, v66
	v_exp_f32_e32 v67, v67
	v_exp_f32_e32 v68, v68
	v_exp_f32_e32 v69, v69
	s_waitcnt lgkmcnt(4)
	v_mfma_f32_32x32x16_bf16 v[34:49], v[138:141], v[98:101], v[122:137]
	ds_read_b128 v[138:141], v220 offset:26720
	v_add_f32_e32 v231, v231, v66
	v_add_f32_e32 v232, v232, v67
	v_exp_f32_e32 v70, v70
	v_exp_f32_e32 v71, v71
	v_mfma_f32_32x32x16_bf16 v[50:65], v[142:145], v[98:101], v[122:137]
	ds_read_b128 v[142:145], v220 offset:33376
	v_add_f32_e32 v231, v231, v68
	v_add_f32_e32 v232, v232, v69
	v_exp_f32_e32 v72, v72
	v_exp_f32_e32 v73, v73
	s_waitcnt lgkmcnt(4)
	v_mfma_f32_32x32x16_bf16 v[34:49], v[146:149], v[102:105], v[34:49]
	ds_read_b128 v[146:149], v220 offset:26752
	global_load_dwordx4 v[216:219], v229, s[10:11]
	s_add_u32 s10, s10, 0x80
	s_addc_u32 s11, s11, 0
	v_add_f32_e32 v231, v231, v70
	v_add_f32_e32 v232, v232, v71
	v_add_f32_e32 v231, v231, v72
	v_add_f32_e32 v232, v232, v73
	v_cvt_pk_bf16_f32 v66, v66, v67
	v_cvt_pk_bf16_f32 v67, v68, v69
	v_mfma_f32_32x32x16_bf16 v[50:65], v[150:153], v[102:105], v[50:65]
	ds_read_b128 v[150:153], v220 offset:33408
	v_cvt_pk_bf16_f32 v68, v70, v71
	v_cvt_pk_bf16_f32 v69, v72, v73
	v_exp_f32_e32 v74, v74
	v_exp_f32_e32 v75, v75
	s_waitcnt lgkmcnt(4)
	v_mfma_f32_32x32x16_bf16 v[34:49], v[154:157], v[106:109], v[34:49]
	ds_read_b128 v[154:157], v220 offset:26784
	v_exp_f32_e32 v76, v76
	v_exp_f32_e32 v77, v77
	v_add_f32_e32 v231, v231, v74
	v_add_f32_e32 v232, v232, v75
	v_mfma_f32_32x32x16_bf16 v[50:65], v[158:161], v[106:109], v[50:65]
	ds_read_b128 v[158:161], v220 offset:33440
	v_exp_f32_e32 v78, v78
	v_exp_f32_e32 v79, v79
	v_add_f32_e32 v231, v231, v76
	v_add_f32_e32 v232, v232, v77
	v_exp_f32_e32 v80, v80
	s_waitcnt lgkmcnt(4)
	v_mfma_f32_32x32x16_bf16 v[34:49], v[138:141], v[110:113], v[34:49]
	ds_read_b128 v[162:165], v221 offset:9216
	v_exp_f32_e32 v81, v81
	v_add_f32_e32 v231, v231, v78
	v_add_f32_e32 v232, v232, v79
	v_add_f32_e32 v231, v231, v80
	v_mfma_f32_32x32x16_bf16 v[50:65], v[142:145], v[110:113], v[50:65]
	ds_read_b128 v[166:169], v221 offset:13824
	v_add_f32_e32 v232, v232, v81
	v_cvt_pk_bf16_f32 v74, v74, v75
	v_cvt_pk_bf16_f32 v75, v76, v77
	v_cvt_pk_bf16_f32 v76, v78, v79
	v_cvt_pk_bf16_f32 v77, v80, v81
	v_exp_f32_e32 v82, v82
	s_waitcnt lgkmcnt(4)
	v_mfma_f32_32x32x16_bf16 v[34:49], v[146:149], v[114:117], v[34:49]
	ds_read_b128 v[170:173], v221 offset:9248
	v_exp_f32_e32 v83, v83
	v_exp_f32_e32 v84, v84
	v_exp_f32_e32 v85, v85
	v_mfma_f32_32x32x16_bf16 v[50:65], v[150:153], v[114:117], v[50:65]
	ds_read_b128 v[174:177], v221 offset:13856
	v_add_f32_e32 v231, v231, v82
	v_add_f32_e32 v232, v232, v83
	v_exp_f32_e32 v86, v86
	v_exp_f32_e32 v87, v87
	s_waitcnt lgkmcnt(4)
	v_mfma_f32_32x32x16_bf16 v[34:49], v[154:157], v[118:121], v[34:49]
	ds_read_b128 v[180:183], v221 offset:9280
	v_add_f32_e32 v231, v231, v84
	v_add_f32_e32 v232, v232, v85
	v_exp_f32_e32 v88, v88
	v_exp_f32_e32 v89, v89
	v_mfma_f32_32x32x16_bf16 v[50:65], v[158:161], v[118:121], v[50:65]
	ds_read_b128 v[184:187], v221 offset:13888
	v_add_f32_e32 v231, v231, v86
	v_add_f32_e32 v232, v232, v87
	v_add_f32_e32 v231, v231, v88
	v_add_f32_e32 v232, v232, v89
	v_cvt_pk_bf16_f32 v82, v82, v83
	v_cvt_pk_bf16_f32 v83, v84, v85
	v_cvt_pk_bf16_f32 v84, v86, v87
	s_waitcnt lgkmcnt(4)
	v_mfma_f32_32x32x16_bf16 v[2:17], v[162:165], v[66:69], v[2:17]
	ds_read_b128 v[188:191], v221 offset:9312
	v_cvt_pk_bf16_f32 v85, v88, v89
	v_exp_f32_e32 v90, v90
	v_exp_f32_e32 v91, v91
	v_exp_f32_e32 v92, v92
	v_mfma_f32_32x32x16_bf16 v[18:33], v[166:169], v[66:69], v[18:33]
	ds_read_b128 v[192:195], v221 offset:13920
	v_exp_f32_e32 v93, v93
	v_add_f32_e32 v231, v231, v90
	v_add_f32_e32 v232, v232, v91
	v_exp_f32_e32 v94, v94
	s_waitcnt lgkmcnt(4)
	v_mfma_f32_32x32x16_bf16 v[2:17], v[170:173], v[74:77], v[2:17]
	v_exp_f32_e32 v95, v95
	v_add_f32_e32 v231, v231, v92
	v_add_f32_e32 v232, v232, v93
	v_exp_f32_e32 v96, v96
	v_mfma_f32_32x32x16_bf16 v[18:33], v[174:177], v[74:77], v[18:33]
	s_waitcnt vmcnt(1)
	ds_write_b128 v222, v[200:203] offset:0
	ds_write_b128 v223, v[204:207] offset:0
	ds_write_b128 v224, v[208:211] offset:0
	ds_write_b64 v225, v[212:213] offset:27648
	ds_write_b64 v225, v[214:215] offset:27664
	v_exp_f32_e32 v97, v97
	v_add_f32_e32 v231, v231, v94
	v_add_f32_e32 v232, v232, v95
	v_add_f32_e32 v231, v231, v96
	v_add_f32_e32 v232, v232, v97
	s_waitcnt lgkmcnt(7)
	v_mfma_f32_32x32x16_bf16 v[2:17], v[180:183], v[82:85], v[2:17]
	v_cvt_pk_bf16_f32 v90, v90, v91
	v_cvt_pk_bf16_f32 v91, v92, v93
	v_cvt_pk_bf16_f32 v92, v94, v95
	v_cvt_pk_bf16_f32 v93, v96, v97
	v_max3_f32 v234, v34, v35, v36
	v_max3_f32 v235, v50, v51, v52
	v_mfma_f32_32x32x16_bf16 v[18:33], v[184:187], v[82:85], v[18:33]
	v_max3_f32 v234, v234, v37, v38
	v_max3_f32 v235, v235, v53, v54
	v_max3_f32 v234, v234, v39, v40
	v_max3_f32 v235, v235, v55, v56
	v_max3_f32 v234, v234, v41, v42
	v_max3_f32 v235, v235, v57, v58
	v_max3_f32 v234, v234, v43, v44
	s_waitcnt lgkmcnt(5)
	v_mfma_f32_32x32x16_bf16 v[2:17], v[188:191], v[90:93], v[2:17]
	v_max3_f32 v235, v235, v59, v60
	v_max3_f32 v234, v234, v45, v46
	v_max3_f32 v235, v235, v61, v62
	v_max3_f32 v234, v234, v47, v48
	v_max3_f32 v235, v235, v63, v64
	v_max3_f32 v234, v234, v49, v65
	v_mfma_f32_32x32x16_bf16 v[18:33], v[192:195], v[90:93], v[18:33]
	v_max_f32_e32 v234, v234, v235
	v_mov_b32_e32 v235, v234
	s_nop 1
	v_permlane32_swap_b32_e32 v234, v235
	v_max_f32_e32 v233, v234, v235
	v_cmp_lt_f32_e32 vcc, 4.0, v233
	s_cbranch_vccz .Lmls_nr_p1
	s_nop 15
	v_max_f32_e32 v234, 0, v233
	v_exp_f32_e64 v235, -v234
	v_add_f32_e32 v230, v230, v234
	v_sub_f32_e32 v34, v34, v234
	v_sub_f32_e32 v35, v35, v234
	v_sub_f32_e32 v36, v36, v234
	v_sub_f32_e32 v37, v37, v234
	v_sub_f32_e32 v38, v38, v234
	v_sub_f32_e32 v39, v39, v234
	v_sub_f32_e32 v40, v40, v234
	v_sub_f32_e32 v41, v41, v234
	v_sub_f32_e32 v42, v42, v234
	v_sub_f32_e32 v43, v43, v234
	v_sub_f32_e32 v44, v44, v234
	v_sub_f32_e32 v45, v45, v234
	v_sub_f32_e32 v46, v46, v234
	v_sub_f32_e32 v47, v47, v234
	v_sub_f32_e32 v48, v48, v234
	v_sub_f32_e32 v49, v49, v234
	v_sub_f32_e32 v50, v50, v234
	v_sub_f32_e32 v51, v51, v234
	v_sub_f32_e32 v52, v52, v234
	v_sub_f32_e32 v53, v53, v234
	v_sub_f32_e32 v54, v54, v234
	v_sub_f32_e32 v55, v55, v234
	v_sub_f32_e32 v56, v56, v234
	v_sub_f32_e32 v57, v57, v234
	v_sub_f32_e32 v58, v58, v234
	v_sub_f32_e32 v59, v59, v234
	v_sub_f32_e32 v60, v60, v234
	v_sub_f32_e32 v61, v61, v234
	v_sub_f32_e32 v62, v62, v234
	v_sub_f32_e32 v63, v63, v234
	v_sub_f32_e32 v64, v64, v234
	v_sub_f32_e32 v65, v65, v234
	v_mul_f32_e32 v231, v231, v235
	v_mul_f32_e32 v232, v232, v235
	v_mul_f32_e32 v2, v2, v235
	v_mul_f32_e32 v3, v3, v235
	v_mul_f32_e32 v4, v4, v235
	v_mul_f32_e32 v5, v5, v235
	v_mul_f32_e32 v6, v6, v235
	v_mul_f32_e32 v7, v7, v235
	v_mul_f32_e32 v8, v8, v235
	v_mul_f32_e32 v9, v9, v235
	v_mul_f32_e32 v10, v10, v235
	v_mul_f32_e32 v11, v11, v235
	v_mul_f32_e32 v12, v12, v235
	v_mul_f32_e32 v13, v13, v235
	v_mul_f32_e32 v14, v14, v235
	v_mul_f32_e32 v15, v15, v235
	v_mul_f32_e32 v16, v16, v235
	v_mul_f32_e32 v17, v17, v235
	v_mul_f32_e32 v18, v18, v235
	v_mul_f32_e32 v19, v19, v235
	v_mul_f32_e32 v20, v20, v235
	v_mul_f32_e32 v21, v21, v235
	v_mul_f32_e32 v22, v22, v235
	v_mul_f32_e32 v23, v23, v235
	v_mul_f32_e32 v24, v24, v235
	v_mul_f32_e32 v25, v25, v235
	v_mul_f32_e32 v26, v26, v235
	v_mul_f32_e32 v27, v27, v235
	v_mul_f32_e32 v28, v28, v235
	v_mul_f32_e32 v29, v29, v235
	v_mul_f32_e32 v30, v30, v235
	v_mul_f32_e32 v31, v31, v235
	v_mul_f32_e32 v32, v32, v235
	v_mul_f32_e32 v33, v33, v235
	v_sub_f32_e32 v122, 0, v230
	v_mov_b32_e32 v123, v122
	v_mov_b32_e32 v124, v122
	v_mov_b32_e32 v125, v122
	v_mov_b32_e32 v126, v122
	v_mov_b32_e32 v127, v122
	v_mov_b32_e32 v128, v122
	v_mov_b32_e32 v129, v122
	v_mov_b32_e32 v130, v122
	v_mov_b32_e32 v131, v122
	v_mov_b32_e32 v132, v122
	v_mov_b32_e32 v133, v122
	v_mov_b32_e32 v134, v122
	v_mov_b32_e32 v135, v122
	v_mov_b32_e32 v136, v122
	v_mov_b32_e32 v137, v122
.Lmls_nr_p1:
	ds_read_b128 v[138:141], v220 offset:39936
	ds_read_b128 v[142:145], v220 offset:46592
	ds_read_b128 v[146:149], v220 offset:39968
	ds_read_b128 v[150:153], v220 offset:46624
	ds_read_b128 v[154:157], v220 offset:40000
	ds_read_b128 v[158:161], v220 offset:46656
	s_waitcnt lgkmcnt(6)
	s_barrier
	v_exp_f32_e32 v34, v34
	v_exp_f32_e32 v35, v35
	v_exp_f32_e32 v36, v36
	v_exp_f32_e32 v37, v37
	s_waitcnt lgkmcnt(4)
	v_mfma_f32_32x32x16_bf16 v[66:81], v[138:141], v[98:101], v[122:137]
	ds_read_b128 v[138:141], v220 offset:40032
	v_add_f32_e32 v231, v231, v34
	v_add_f32_e32 v232, v232, v35
	v_exp_f32_e32 v38, v38
	v_exp_f32_e32 v39, v39
	v_mfma_f32_32x32x16_bf16 v[82:97], v[142:145], v[98:101], v[122:137]
	ds_read_b128 v[142:145], v220 offset:46688
	v_add_f32_e32 v231, v231, v36
	v_add_f32_e32 v232, v232, v37
	v_exp_f32_e32 v40, v40
	v_exp_f32_e32 v41, v41
	s_waitcnt lgkmcnt(4)
	v_mfma_f32_32x32x16_bf16 v[66:81], v[146:149], v[102:105], v[66:81]
	ds_read_b128 v[146:149], v220 offset:40064
	global_load_dwordx4 v[200:203], v226, s[4:5]
	global_load_dwordx4 v[204:207], v227, s[4:5]
	global_load_dwordx4 v[208:211], v228, s[4:5]
	s_add_u32 s4, s4, 0x6000
	s_addc_u32 s5, s5, 0
	global_load_dwordx4 v[212:215], v229, s[10:11]
	s_add_u32 s10, s10, 0x80
	s_addc_u32 s11, s11, 0
	v_add_f32_e32 v231, v231, v38
	v_add_f32_e32 v232, v232, v39
	v_add_f32_e32 v231, v231, v40
	v_add_f32_e32 v232, v232, v41
	v_cvt_pk_bf16_f32 v34, v34, v35
	v_cvt_pk_bf16_f32 v35, v36, v37
	v_mfma_f32_32x32x16_bf16 v[82:97], v[150:153], v[102:105], v[82:97]
	ds_read_b128 v[150:153], v220 offset:46720
	v_cvt_pk_bf16_f32 v36, v38, v39
	v_cvt_pk_bf16_f32 v37, v40, v41
	v_exp_f32_e32 v42, v42
	v_exp_f32_e32 v43, v43
	s_waitcnt lgkmcnt(4)
	v_mfma_f32_32x32x16_bf16 v[66:81], v[154:157], v[106:109], v[66:81]
	ds_read_b128 v[154:157], v220 offset:40096
	v_exp_f32_e32 v44, v44
	v_exp_f32_e32 v45, v45
	v_add_f32_e32 v231, v231, v42
	v_add_f32_e32 v232, v232, v43
	v_mfma_f32_32x32x16_bf16 v[82:97], v[158:161], v[106:109], v[82:97]
	ds_read_b128 v[158:161], v220 offset:46752
	v_exp_f32_e32 v46, v46
	v_exp_f32_e32 v47, v47
	v_add_f32_e32 v231, v231, v44
	v_add_f32_e32 v232, v232, v45
	v_exp_f32_e32 v48, v48
	s_waitcnt lgkmcnt(4)
	v_mfma_f32_32x32x16_bf16 v[66:81], v[138:141], v[110:113], v[66:81]
	ds_read_b128 v[162:165], v221 offset:18432
	v_exp_f32_e32 v49, v49
	v_add_f32_e32 v231, v231, v46
	v_add_f32_e32 v232, v232, v47
	v_add_f32_e32 v231, v231, v48
	v_mfma_f32_32x32x16_bf16 v[82:97], v[142:145], v[110:113], v[82:97]
	ds_read_b128 v[166:169], v221 offset:23040
	v_add_f32_e32 v232, v232, v49
	v_cvt_pk_bf16_f32 v42, v42, v43
	v_cvt_pk_bf16_f32 v43, v44, v45
	v_cvt_pk_bf16_f32 v44, v46, v47
	v_cvt_pk_bf16_f32 v45, v48, v49
	v_exp_f32_e32 v50, v50
	s_waitcnt lgkmcnt(4)
	v_mfma_f32_32x32x16_bf16 v[66:81], v[146:149], v[114:117], v[66:81]
	ds_read_b128 v[170:173], v221 offset:18464
	v_exp_f32_e32 v51, v51
	v_exp_f32_e32 v52, v52
	v_exp_f32_e32 v53, v53
	v_mfma_f32_32x32x16_bf16 v[82:97], v[150:153], v[114:117], v[82:97]
	ds_read_b128 v[174:177], v221 offset:23072
	v_add_f32_e32 v231, v231, v50
	v_add_f32_e32 v232, v232, v51
	v_exp_f32_e32 v54, v54
	v_exp_f32_e32 v55, v55
	s_waitcnt lgkmcnt(4)
	v_mfma_f32_32x32x16_bf16 v[66:81], v[154:157], v[118:121], v[66:81]
	ds_read_b128 v[180:183], v221 offset:18496
	v_add_f32_e32 v231, v231, v52
	v_add_f32_e32 v232, v232, v53
	v_exp_f32_e32 v56, v56
	v_exp_f32_e32 v57, v57
	v_mfma_f32_32x32x16_bf16 v[82:97], v[158:161], v[118:121], v[82:97]
	ds_read_b128 v[184:187], v221 offset:23104
	v_add_f32_e32 v231, v231, v54
	v_add_f32_e32 v232, v232, v55
	v_add_f32_e32 v231, v231, v56
	v_add_f32_e32 v232, v232, v57
	v_cvt_pk_bf16_f32 v50, v50, v51
	v_cvt_pk_bf16_f32 v51, v52, v53
	v_cvt_pk_bf16_f32 v52, v54, v55
	s_waitcnt lgkmcnt(4)
	v_mfma_f32_32x32x16_bf16 v[2:17], v[162:165], v[34:37], v[2:17]
	ds_read_b128 v[188:191], v221 offset:18528
	v_cvt_pk_bf16_f32 v53, v56, v57
	v_exp_f32_e32 v58, v58
	v_exp_f32_e32 v59, v59
	v_exp_f32_e32 v60, v60
	v_mfma_f32_32x32x16_bf16 v[18:33], v[166:169], v[34:37], v[18:33]
	ds_read_b128 v[192:195], v221 offset:23136
	v_exp_f32_e32 v61, v61
	v_add_f32_e32 v231, v231, v58
	v_add_f32_e32 v232, v232, v59
	v_exp_f32_e32 v62, v62
	s_waitcnt lgkmcnt(4)
	v_mfma_f32_32x32x16_bf16 v[2:17], v[170:173], v[42:45], v[2:17]
	v_exp_f32_e32 v63, v63
	v_add_f32_e32 v231, v231, v60
	v_add_f32_e32 v232, v232, v61
	v_exp_f32_e32 v64, v64
	v_mfma_f32_32x32x16_bf16 v[18:33], v[174:177], v[42:45], v[18:33]
	s_waitcnt vmcnt(4)
	ds_write_b64 v225, v[216:217] offset:0
	ds_write_b64 v225, v[218:219] offset:16
	v_exp_f32_e32 v65, v65
	v_add_f32_e32 v231, v231, v62
	v_add_f32_e32 v232, v232, v63
	v_add_f32_e32 v231, v231, v64
	v_add_f32_e32 v232, v232, v65
	s_waitcnt lgkmcnt(4)
	v_mfma_f32_32x32x16_bf16 v[2:17], v[180:183], v[50:53], v[2:17]
	v_cvt_pk_bf16_f32 v58, v58, v59
	v_cvt_pk_bf16_f32 v59, v60, v61
	v_cvt_pk_bf16_f32 v60, v62, v63
	v_cvt_pk_bf16_f32 v61, v64, v65
	v_max3_f32 v234, v66, v67, v68
	v_max3_f32 v235, v82, v83, v84
	v_mfma_f32_32x32x16_bf16 v[18:33], v[184:187], v[50:53], v[18:33]
	v_max3_f32 v234, v234, v69, v70
	v_max3_f32 v235, v235, v85, v86
	v_max3_f32 v234, v234, v71, v72
	v_max3_f32 v235, v235, v87, v88
	v_max3_f32 v234, v234, v73, v74
	v_max3_f32 v235, v235, v89, v90
	v_max3_f32 v234, v234, v75, v76
	s_waitcnt lgkmcnt(2)
	v_mfma_f32_32x32x16_bf16 v[2:17], v[188:191], v[58:61], v[2:17]
	v_max3_f32 v235, v235, v91, v92
	v_max3_f32 v234, v234, v77, v78
	v_max3_f32 v235, v235, v93, v94
	v_max3_f32 v234, v234, v79, v80
	v_max3_f32 v235, v235, v95, v96
	v_max3_f32 v234, v234, v81, v97
	v_mfma_f32_32x32x16_bf16 v[18:33], v[192:195], v[58:61], v[18:33]
	v_max_f32_e32 v234, v234, v235
	v_mov_b32_e32 v235, v234
	s_nop 1
	v_permlane32_swap_b32_e32 v234, v235
	v_max_f32_e32 v233, v234, v235
	v_cmp_lt_f32_e32 vcc, 4.0, v233
	s_cbranch_vccz .Lmls_nr_p2
	s_nop 15
	v_max_f32_e32 v234, 0, v233
	v_exp_f32_e64 v235, -v234
	v_add_f32_e32 v230, v230, v234
	v_sub_f32_e32 v66, v66, v234
	v_sub_f32_e32 v67, v67, v234
	v_sub_f32_e32 v68, v68, v234
	v_sub_f32_e32 v69, v69, v234
	v_sub_f32_e32 v70, v70, v234
	v_sub_f32_e32 v71, v71, v234
	v_sub_f32_e32 v72, v72, v234
	v_sub_f32_e32 v73, v73, v234
	v_sub_f32_e32 v74, v74, v234
	v_sub_f32_e32 v75, v75, v234
	v_sub_f32_e32 v76, v76, v234
	v_sub_f32_e32 v77, v77, v234
	v_sub_f32_e32 v78, v78, v234
	v_sub_f32_e32 v79, v79, v234
	v_sub_f32_e32 v80, v80, v234
	v_sub_f32_e32 v81, v81, v234
	v_sub_f32_e32 v82, v82, v234
	v_sub_f32_e32 v83, v83, v234
	v_sub_f32_e32 v84, v84, v234
	v_sub_f32_e32 v85, v85, v234
	v_sub_f32_e32 v86, v86, v234
	v_sub_f32_e32 v87, v87, v234
	v_sub_f32_e32 v88, v88, v234
	v_sub_f32_e32 v89, v89, v234
	v_sub_f32_e32 v90, v90, v234
	v_sub_f32_e32 v91, v91, v234
	v_sub_f32_e32 v92, v92, v234
	v_sub_f32_e32 v93, v93, v234
	v_sub_f32_e32 v94, v94, v234
	v_sub_f32_e32 v95, v95, v234
	v_sub_f32_e32 v96, v96, v234
	v_sub_f32_e32 v97, v97, v234
	v_mul_f32_e32 v231, v231, v235
	v_mul_f32_e32 v232, v232, v235
	v_mul_f32_e32 v2, v2, v235
	v_mul_f32_e32 v3, v3, v235
	v_mul_f32_e32 v4, v4, v235
	v_mul_f32_e32 v5, v5, v235
	v_mul_f32_e32 v6, v6, v235
	v_mul_f32_e32 v7, v7, v235
	v_mul_f32_e32 v8, v8, v235
	v_mul_f32_e32 v9, v9, v235
	v_mul_f32_e32 v10, v10, v235
	v_mul_f32_e32 v11, v11, v235
	v_mul_f32_e32 v12, v12, v235
	v_mul_f32_e32 v13, v13, v235
	v_mul_f32_e32 v14, v14, v235
	v_mul_f32_e32 v15, v15, v235
	v_mul_f32_e32 v16, v16, v235
	v_mul_f32_e32 v17, v17, v235
	v_mul_f32_e32 v18, v18, v235
	v_mul_f32_e32 v19, v19, v235
	v_mul_f32_e32 v20, v20, v235
	v_mul_f32_e32 v21, v21, v235
	v_mul_f32_e32 v22, v22, v235
	v_mul_f32_e32 v23, v23, v235
	v_mul_f32_e32 v24, v24, v235
	v_mul_f32_e32 v25, v25, v235
	v_mul_f32_e32 v26, v26, v235
	v_mul_f32_e32 v27, v27, v235
	v_mul_f32_e32 v28, v28, v235
	v_mul_f32_e32 v29, v29, v235
	v_mul_f32_e32 v30, v30, v235
	v_mul_f32_e32 v31, v31, v235
	v_mul_f32_e32 v32, v32, v235
	v_mul_f32_e32 v33, v33, v235
	v_sub_f32_e32 v122, 0, v230
	v_mov_b32_e32 v123, v122
	v_mov_b32_e32 v124, v122
	v_mov_b32_e32 v125, v122
	v_mov_b32_e32 v126, v122
	v_mov_b32_e32 v127, v122
	v_mov_b32_e32 v128, v122
	v_mov_b32_e32 v129, v122
	v_mov_b32_e32 v130, v122
	v_mov_b32_e32 v131, v122
	v_mov_b32_e32 v132, v122
	v_mov_b32_e32 v133, v122
	v_mov_b32_e32 v134, v122
	v_mov_b32_e32 v135, v122
	v_mov_b32_e32 v136, v122
	v_mov_b32_e32 v137, v122
.Lmls_nr_p2:
	ds_read_b128 v[138:141], v220 offset:0
	ds_read_b128 v[142:145], v220 offset:6656
	ds_read_b128 v[146:149], v220 offset:32
	ds_read_b128 v[150:153], v220 offset:6688
	ds_read_b128 v[154:157], v220 offset:64
	ds_read_b128 v[158:161], v220 offset:6720
	s_waitcnt lgkmcnt(6)
	s_barrier
	v_exp_f32_e32 v66, v66
	v_exp_f32_e32 v67, v67
	v_exp_f32_e32 v68, v68
	v_exp_f32_e32 v69, v69
	s_waitcnt lgkmcnt(4)
	v_mfma_f32_32x32x16_bf16 v[34:49], v[138:141], v[98:101], v[122:137]
	ds_read_b128 v[138:141], v220 offset:96
	v_add_f32_e32 v231, v231, v66
	v_add_f32_e32 v232, v232, v67
	v_exp_f32_e32 v70, v70
	v_exp_f32_e32 v71, v71
	v_mfma_f32_32x32x16_bf16 v[50:65], v[142:145], v[98:101], v[122:137]
	ds_read_b128 v[142:145], v220 offset:6752
	v_add_f32_e32 v231, v231, v68
	v_add_f32_e32 v232, v232, v69
	v_exp_f32_e32 v72, v72
	v_exp_f32_e32 v73, v73
	s_waitcnt lgkmcnt(4)
	v_mfma_f32_32x32x16_bf16 v[34:49], v[146:149], v[102:105], v[34:49]
	ds_read_b128 v[146:149], v220 offset:128
	global_load_dwordx4 v[216:219], v229, s[10:11]
	s_add_u32 s10, s10, 0x80
	s_addc_u32 s11, s11, 0
	v_add_f32_e32 v231, v231, v70
	v_add_f32_e32 v232, v232, v71
	v_add_f32_e32 v231, v231, v72
	v_add_f32_e32 v232, v232, v73
	v_cvt_pk_bf16_f32 v66, v66, v67
	v_cvt_pk_bf16_f32 v67, v68, v69
	v_mfma_f32_32x32x16_bf16 v[50:65], v[150:153], v[102:105], v[50:65]
	ds_read_b128 v[150:153], v220 offset:6784
	v_cvt_pk_bf16_f32 v68, v70, v71
	v_cvt_pk_bf16_f32 v69, v72, v73
	v_exp_f32_e32 v74, v74
	v_exp_f32_e32 v75, v75
	s_waitcnt lgkmcnt(4)
	v_mfma_f32_32x32x16_bf16 v[34:49], v[154:157], v[106:109], v[34:49]
	ds_read_b128 v[154:157], v220 offset:160
	v_exp_f32_e32 v76, v76
	v_exp_f32_e32 v77, v77
	v_add_f32_e32 v231, v231, v74
	v_add_f32_e32 v232, v232, v75
	v_mfma_f32_32x32x16_bf16 v[50:65], v[158:161], v[106:109], v[50:65]
	ds_read_b128 v[158:161], v220 offset:6816
	v_exp_f32_e32 v78, v78
	v_exp_f32_e32 v79, v79
	v_add_f32_e32 v231, v231, v76
	v_add_f32_e32 v232, v232, v77
	v_exp_f32_e32 v80, v80
	s_waitcnt lgkmcnt(4)
	v_mfma_f32_32x32x16_bf16 v[34:49], v[138:141], v[110:113], v[34:49]
	ds_read_b128 v[162:165], v221 offset:27648
	v_exp_f32_e32 v81, v81
	v_add_f32_e32 v231, v231, v78
	v_add_f32_e32 v232, v232, v79
	v_add_f32_e32 v231, v231, v80
	v_mfma_f32_32x32x16_bf16 v[50:65], v[142:145], v[110:113], v[50:65]
	ds_read_b128 v[166:169], v221 offset:32256
	v_add_f32_e32 v232, v232, v81
	v_cvt_pk_bf16_f32 v74, v74, v75
	v_cvt_pk_bf16_f32 v75, v76, v77
	v_cvt_pk_bf16_f32 v76, v78, v79
	v_cvt_pk_bf16_f32 v77, v80, v81
	v_exp_f32_e32 v82, v82
	s_waitcnt lgkmcnt(4)
	v_mfma_f32_32x32x16_bf16 v[34:49], v[146:149], v[114:117], v[34:49]
	ds_read_b128 v[170:173], v221 offset:27680
	v_exp_f32_e32 v83, v83
	v_exp_f32_e32 v84, v84
	v_exp_f32_e32 v85, v85
	v_mfma_f32_32x32x16_bf16 v[50:65], v[150:153], v[114:117], v[50:65]
	ds_read_b128 v[174:177], v221 offset:32288
	v_add_f32_e32 v231, v231, v82
	v_add_f32_e32 v232, v232, v83
	v_exp_f32_e32 v86, v86
	v_exp_f32_e32 v87, v87
	s_waitcnt lgkmcnt(4)
	v_mfma_f32_32x32x16_bf16 v[34:49], v[154:157], v[118:121], v[34:49]
	ds_read_b128 v[180:183], v221 offset:27712
	v_add_f32_e32 v231, v231, v84
	v_add_f32_e32 v232, v232, v85
	v_exp_f32_e32 v88, v88
	v_exp_f32_e32 v89, v89
	v_mfma_f32_32x32x16_bf16 v[50:65], v[158:161], v[118:121], v[50:65]
	ds_read_b128 v[184:187], v221 offset:32320
	v_add_f32_e32 v231, v231, v86
	v_add_f32_e32 v232, v232, v87
	v_add_f32_e32 v231, v231, v88
	v_add_f32_e32 v232, v232, v89
	v_cvt_pk_bf16_f32 v82, v82, v83
	v_cvt_pk_bf16_f32 v83, v84, v85
	v_cvt_pk_bf16_f32 v84, v86, v87
	s_waitcnt lgkmcnt(4)
	v_mfma_f32_32x32x16_bf16 v[2:17], v[162:165], v[66:69], v[2:17]
	ds_read_b128 v[188:191], v221 offset:27744
	v_cvt_pk_bf16_f32 v85, v88, v89
	v_exp_f32_e32 v90, v90
	v_exp_f32_e32 v91, v91
	v_exp_f32_e32 v92, v92
	v_mfma_f32_32x32x16_bf16 v[18:33], v[166:169], v[66:69], v[18:33]
	ds_read_b128 v[192:195], v221 offset:32352
	v_exp_f32_e32 v93, v93
	v_add_f32_e32 v231, v231, v90
	v_add_f32_e32 v232, v232, v91
	v_exp_f32_e32 v94, v94
	s_waitcnt lgkmcnt(4)
	v_mfma_f32_32x32x16_bf16 v[2:17], v[170:173], v[74:77], v[2:17]
	v_exp_f32_e32 v95, v95
	v_add_f32_e32 v231, v231, v92
	v_add_f32_e32 v232, v232, v93
	v_exp_f32_e32 v96, v96
	v_mfma_f32_32x32x16_bf16 v[18:33], v[174:177], v[74:77], v[18:33]
	s_waitcnt vmcnt(1)
	ds_write_b128 v222, v[200:203] offset:26624
	ds_write_b128 v223, v[204:207] offset:26624
	ds_write_b128 v224, v[208:211] offset:26624
	ds_write_b64 v225, v[212:213] offset:9216
	ds_write_b64 v225, v[214:215] offset:9232
	v_exp_f32_e32 v97, v97
	v_add_f32_e32 v231, v231, v94
	v_add_f32_e32 v232, v232, v95
	v_add_f32_e32 v231, v231, v96
	v_add_f32_e32 v232, v232, v97
	s_waitcnt lgkmcnt(7)
	v_mfma_f32_32x32x16_bf16 v[2:17], v[180:183], v[82:85], v[2:17]
	v_cvt_pk_bf16_f32 v90, v90, v91
	v_cvt_pk_bf16_f32 v91, v92, v93
	v_cvt_pk_bf16_f32 v92, v94, v95
	v_cvt_pk_bf16_f32 v93, v96, v97
	v_max3_f32 v234, v34, v35, v36
	v_max3_f32 v235, v50, v51, v52
	v_mfma_f32_32x32x16_bf16 v[18:33], v[184:187], v[82:85], v[18:33]
	v_max3_f32 v234, v234, v37, v38
	v_max3_f32 v235, v235, v53, v54
	v_max3_f32 v234, v234, v39, v40
	v_max3_f32 v235, v235, v55, v56
	v_max3_f32 v234, v234, v41, v42
	v_max3_f32 v235, v235, v57, v58
	v_max3_f32 v234, v234, v43, v44
	s_waitcnt lgkmcnt(5)
	v_mfma_f32_32x32x16_bf16 v[2:17], v[188:191], v[90:93], v[2:17]
	v_max3_f32 v235, v235, v59, v60
	v_max3_f32 v234, v234, v45, v46
	v_max3_f32 v235, v235, v61, v62
	v_max3_f32 v234, v234, v47, v48
	v_max3_f32 v235, v235, v63, v64
	v_max3_f32 v234, v234, v49, v65
	v_mfma_f32_32x32x16_bf16 v[18:33], v[192:195], v[90:93], v[18:33]
	v_max_f32_e32 v234, v234, v235
	v_mov_b32_e32 v235, v234
	s_nop 1
	v_permlane32_swap_b32_e32 v234, v235
	v_max_f32_e32 v233, v234, v235
	v_cmp_lt_f32_e32 vcc, 4.0, v233
	s_cbranch_vccz .Lmls_nr_p3
	s_nop 15
	v_max_f32_e32 v234, 0, v233
	v_exp_f32_e64 v235, -v234
	v_add_f32_e32 v230, v230, v234
	v_sub_f32_e32 v34, v34, v234
	v_sub_f32_e32 v35, v35, v234
	v_sub_f32_e32 v36, v36, v234
	v_sub_f32_e32 v37, v37, v234
	v_sub_f32_e32 v38, v38, v234
	v_sub_f32_e32 v39, v39, v234
	v_sub_f32_e32 v40, v40, v234
	v_sub_f32_e32 v41, v41, v234
	v_sub_f32_e32 v42, v42, v234
	v_sub_f32_e32 v43, v43, v234
	v_sub_f32_e32 v44, v44, v234
	v_sub_f32_e32 v45, v45, v234
	v_sub_f32_e32 v46, v46, v234
	v_sub_f32_e32 v47, v47, v234
	v_sub_f32_e32 v48, v48, v234
	v_sub_f32_e32 v49, v49, v234
	v_sub_f32_e32 v50, v50, v234
	v_sub_f32_e32 v51, v51, v234
	v_sub_f32_e32 v52, v52, v234
	v_sub_f32_e32 v53, v53, v234
	v_sub_f32_e32 v54, v54, v234
	v_sub_f32_e32 v55, v55, v234
	v_sub_f32_e32 v56, v56, v234
	v_sub_f32_e32 v57, v57, v234
	v_sub_f32_e32 v58, v58, v234
	v_sub_f32_e32 v59, v59, v234
	v_sub_f32_e32 v60, v60, v234
	v_sub_f32_e32 v61, v61, v234
	v_sub_f32_e32 v62, v62, v234
	v_sub_f32_e32 v63, v63, v234
	v_sub_f32_e32 v64, v64, v234
	v_sub_f32_e32 v65, v65, v234
	v_mul_f32_e32 v231, v231, v235
	v_mul_f32_e32 v232, v232, v235
	v_mul_f32_e32 v2, v2, v235
	v_mul_f32_e32 v3, v3, v235
	v_mul_f32_e32 v4, v4, v235
	v_mul_f32_e32 v5, v5, v235
	v_mul_f32_e32 v6, v6, v235
	v_mul_f32_e32 v7, v7, v235
	v_mul_f32_e32 v8, v8, v235
	v_mul_f32_e32 v9, v9, v235
	v_mul_f32_e32 v10, v10, v235
	v_mul_f32_e32 v11, v11, v235
	v_mul_f32_e32 v12, v12, v235
	v_mul_f32_e32 v13, v13, v235
	v_mul_f32_e32 v14, v14, v235
	v_mul_f32_e32 v15, v15, v235
	v_mul_f32_e32 v16, v16, v235
	v_mul_f32_e32 v17, v17, v235
	v_mul_f32_e32 v18, v18, v235
	v_mul_f32_e32 v19, v19, v235
	v_mul_f32_e32 v20, v20, v235
	v_mul_f32_e32 v21, v21, v235
	v_mul_f32_e32 v22, v22, v235
	v_mul_f32_e32 v23, v23, v235
	v_mul_f32_e32 v24, v24, v235
	v_mul_f32_e32 v25, v25, v235
	v_mul_f32_e32 v26, v26, v235
	v_mul_f32_e32 v27, v27, v235
	v_mul_f32_e32 v28, v28, v235
	v_mul_f32_e32 v29, v29, v235
	v_mul_f32_e32 v30, v30, v235
	v_mul_f32_e32 v31, v31, v235
	v_mul_f32_e32 v32, v32, v235
	v_mul_f32_e32 v33, v33, v235
	v_sub_f32_e32 v122, 0, v230
	v_mov_b32_e32 v123, v122
	v_mov_b32_e32 v124, v122
	v_mov_b32_e32 v125, v122
	v_mov_b32_e32 v126, v122
	v_mov_b32_e32 v127, v122
	v_mov_b32_e32 v128, v122
	v_mov_b32_e32 v129, v122
	v_mov_b32_e32 v130, v122
	v_mov_b32_e32 v131, v122
	v_mov_b32_e32 v132, v122
	v_mov_b32_e32 v133, v122
	v_mov_b32_e32 v134, v122
	v_mov_b32_e32 v135, v122
	v_mov_b32_e32 v136, v122
	v_mov_b32_e32 v137, v122
.Lmls_nr_p3:
	ds_read_b128 v[138:141], v220 offset:13312
	ds_read_b128 v[142:145], v220 offset:19968
	ds_read_b128 v[146:149], v220 offset:13344
	ds_read_b128 v[150:153], v220 offset:20000
	ds_read_b128 v[154:157], v220 offset:13376
	ds_read_b128 v[158:161], v220 offset:20032
	s_waitcnt lgkmcnt(6)
	s_barrier
	s_add_i32 s16, s16, -1
	s_cmp_lg_u32 s16, 0
	s_cbranch_scc1 .Lmls_loop
	v_exp_f32_e32 v34, v34
	v_exp_f32_e32 v35, v35
	v_exp_f32_e32 v36, v36
	v_exp_f32_e32 v37, v37
	s_waitcnt lgkmcnt(4)
	v_mfma_f32_32x32x16_bf16 v[66:81], v[138:141], v[98:101], v[122:137]
	ds_read_b128 v[138:141], v220 offset:13408
	v_add_f32_e32 v231, v231, v34
	v_add_f32_e32 v232, v232, v35
	v_exp_f32_e32 v38, v38
	v_exp_f32_e32 v39, v39
	v_mfma_f32_32x32x16_bf16 v[82:97], v[142:145], v[98:101], v[122:137]
	ds_read_b128 v[142:145], v220 offset:20064
	v_add_f32_e32 v231, v231, v36
	v_add_f32_e32 v232, v232, v37
	v_exp_f32_e32 v40, v40
	v_exp_f32_e32 v41, v41
	s_waitcnt lgkmcnt(4)
	v_mfma_f32_32x32x16_bf16 v[66:81], v[146:149], v[102:105], v[66:81]
	ds_read_b128 v[146:149], v220 offset:13440
	global_load_dwordx4 v[212:215], v229, s[10:11]
	s_add_u32 s10, s10, 0x80
	s_addc_u32 s11, s11, 0
	v_add_f32_e32 v231, v231, v38
	v_add_f32_e32 v232, v232, v39
	v_add_f32_e32 v231, v231, v40
	v_add_f32_e32 v232, v232, v41
	v_cvt_pk_bf16_f32 v34, v34, v35
	v_cvt_pk_bf16_f32 v35, v36, v37
	v_mfma_f32_32x32x16_bf16 v[82:97], v[150:153], v[102:105], v[82:97]
	ds_read_b128 v[150:153], v220 offset:20096
	v_cvt_pk_bf16_f32 v36, v38, v39
	v_cvt_pk_bf16_f32 v37, v40, v41
	v_exp_f32_e32 v42, v42
	v_exp_f32_e32 v43, v43
	s_waitcnt lgkmcnt(4)
	v_mfma_f32_32x32x16_bf16 v[66:81], v[154:157], v[106:109], v[66:81]
	ds_read_b128 v[154:157], v220 offset:13472
	v_exp_f32_e32 v44, v44
	v_exp_f32_e32 v45, v45
	v_add_f32_e32 v231, v231, v42
	v_add_f32_e32 v232, v232, v43
	v_mfma_f32_32x32x16_bf16 v[82:97], v[158:161], v[106:109], v[82:97]
	ds_read_b128 v[158:161], v220 offset:20128
	v_exp_f32_e32 v46, v46
	v_exp_f32_e32 v47, v47
	v_add_f32_e32 v231, v231, v44
	v_add_f32_e32 v232, v232, v45
	v_exp_f32_e32 v48, v48
	s_waitcnt lgkmcnt(4)
	v_mfma_f32_32x32x16_bf16 v[66:81], v[138:141], v[110:113], v[66:81]
	ds_read_b128 v[162:165], v221 offset:0
	v_exp_f32_e32 v49, v49
	v_add_f32_e32 v231, v231, v46
	v_add_f32_e32 v232, v232, v47
	v_add_f32_e32 v231, v231, v48
	v_mfma_f32_32x32x16_bf16 v[82:97], v[142:145], v[110:113], v[82:97]
	ds_read_b128 v[166:169], v221 offset:4608
	v_add_f32_e32 v232, v232, v49
	v_cvt_pk_bf16_f32 v42, v42, v43
	v_cvt_pk_bf16_f32 v43, v44, v45
	v_cvt_pk_bf16_f32 v44, v46, v47
	v_cvt_pk_bf16_f32 v45, v48, v49
	v_exp_f32_e32 v50, v50
	s_waitcnt lgkmcnt(4)
	v_mfma_f32_32x32x16_bf16 v[66:81], v[146:149], v[114:117], v[66:81]
	ds_read_b128 v[170:173], v221 offset:32
	v_exp_f32_e32 v51, v51
	v_exp_f32_e32 v52, v52
	v_exp_f32_e32 v53, v53
	v_mfma_f32_32x32x16_bf16 v[82:97], v[150:153], v[114:117], v[82:97]
	ds_read_b128 v[174:177], v221 offset:4640
	v_add_f32_e32 v231, v231, v50
	v_add_f32_e32 v232, v232, v51
	v_exp_f32_e32 v54, v54
	v_exp_f32_e32 v55, v55
	s_waitcnt lgkmcnt(4)
	v_mfma_f32_32x32x16_bf16 v[66:81], v[154:157], v[118:121], v[66:81]
	ds_read_b128 v[180:183], v221 offset:64
	v_add_f32_e32 v231, v231, v52
	v_add_f32_e32 v232, v232, v53
	v_exp_f32_e32 v56, v56
	v_exp_f32_e32 v57, v57
	v_mfma_f32_32x32x16_bf16 v[82:97], v[158:161], v[118:121], v[82:97]
	ds_read_b128 v[184:187], v221 offset:4672
	v_add_f32_e32 v231, v231, v54
	v_add_f32_e32 v232, v232, v55
	v_add_f32_e32 v231, v231, v56
	v_add_f32_e32 v232, v232, v57
	v_cvt_pk_bf16_f32 v50, v50, v51
	v_cvt_pk_bf16_f32 v51, v52, v53
	v_cvt_pk_bf16_f32 v52, v54, v55
	s_waitcnt lgkmcnt(4)
	v_mfma_f32_32x32x16_bf16 v[2:17], v[162:165], v[34:37], v[2:17]
	ds_read_b128 v[188:191], v221 offset:96
	v_cvt_pk_bf16_f32 v53, v56, v57
	v_exp_f32_e32 v58, v58
	v_exp_f32_e32 v59, v59
	v_exp_f32_e32 v60, v60
	v_mfma_f32_32x32x16_bf16 v[18:33], v[166:169], v[34:37], v[18:33]
	ds_read_b128 v[192:195], v221 offset:4704
	v_exp_f32_e32 v61, v61
	v_add_f32_e32 v231, v231, v58
	v_add_f32_e32 v232, v232, v59
	v_exp_f32_e32 v62, v62
	s_waitcnt lgkmcnt(4)
	v_mfma_f32_32x32x16_bf16 v[2:17], v[170:173], v[42:45], v[2:17]
	v_exp_f32_e32 v63, v63
	v_add_f32_e32 v231, v231, v60
	v_add_f32_e32 v232, v232, v61
	v_exp_f32_e32 v64, v64
	v_mfma_f32_32x32x16_bf16 v[18:33], v[174:177], v[42:45], v[18:33]
	s_waitcnt vmcnt(1)
	ds_write_b64 v225, v[216:217] offset:18432
	ds_write_b64 v225, v[218:219] offset:18448
	v_exp_f32_e32 v65, v65
	v_add_f32_e32 v231, v231, v62
	v_add_f32_e32 v232, v232, v63
	v_add_f32_e32 v231, v231, v64
	v_add_f32_e32 v232, v232, v65
	s_waitcnt lgkmcnt(4)
	v_mfma_f32_32x32x16_bf16 v[2:17], v[180:183], v[50:53], v[2:17]
	v_cvt_pk_bf16_f32 v58, v58, v59
	v_cvt_pk_bf16_f32 v59, v60, v61
	v_cvt_pk_bf16_f32 v60, v62, v63
	v_cvt_pk_bf16_f32 v61, v64, v65
	v_max3_f32 v234, v66, v67, v68
	v_max3_f32 v235, v82, v83, v84
	v_mfma_f32_32x32x16_bf16 v[18:33], v[184:187], v[50:53], v[18:33]
	v_max3_f32 v234, v234, v69, v70
	v_max3_f32 v235, v235, v85, v86
	v_max3_f32 v234, v234, v71, v72
	v_max3_f32 v235, v235, v87, v88
	v_max3_f32 v234, v234, v73, v74
	v_max3_f32 v235, v235, v89, v90
	v_max3_f32 v234, v234, v75, v76
	s_waitcnt lgkmcnt(2)
	v_mfma_f32_32x32x16_bf16 v[2:17], v[188:191], v[58:61], v[2:17]
	v_max3_f32 v235, v235, v91, v92
	v_max3_f32 v234, v234, v77, v78
	v_max3_f32 v235, v235, v93, v94
	v_max3_f32 v234, v234, v79, v80
	v_max3_f32 v235, v235, v95, v96
	v_max3_f32 v234, v234, v81, v97
	v_mfma_f32_32x32x16_bf16 v[18:33], v[192:195], v[58:61], v[18:33]
	v_max_f32_e32 v234, v234, v235
	v_mov_b32_e32 v235, v234
	s_nop 1
	v_permlane32_swap_b32_e32 v234, v235
	v_max_f32_e32 v233, v234, v235
	v_cmp_lt_f32_e32 vcc, 4.0, v233
	s_cbranch_vccz .Lmls_nr_t0
	s_nop 15
	v_max_f32_e32 v234, 0, v233
	v_exp_f32_e64 v235, -v234
	v_add_f32_e32 v230, v230, v234
	v_sub_f32_e32 v66, v66, v234
	v_sub_f32_e32 v67, v67, v234
	v_sub_f32_e32 v68, v68, v234
	v_sub_f32_e32 v69, v69, v234
	v_sub_f32_e32 v70, v70, v234
	v_sub_f32_e32 v71, v71, v234
	v_sub_f32_e32 v72, v72, v234
	v_sub_f32_e32 v73, v73, v234
	v_sub_f32_e32 v74, v74, v234
	v_sub_f32_e32 v75, v75, v234
	v_sub_f32_e32 v76, v76, v234
	v_sub_f32_e32 v77, v77, v234
	v_sub_f32_e32 v78, v78, v234
	v_sub_f32_e32 v79, v79, v234
	v_sub_f32_e32 v80, v80, v234
	v_sub_f32_e32 v81, v81, v234
	v_sub_f32_e32 v82, v82, v234
	v_sub_f32_e32 v83, v83, v234
	v_sub_f32_e32 v84, v84, v234
	v_sub_f32_e32 v85, v85, v234
	v_sub_f32_e32 v86, v86, v234
	v_sub_f32_e32 v87, v87, v234
	v_sub_f32_e32 v88, v88, v234
	v_sub_f32_e32 v89, v89, v234
	v_sub_f32_e32 v90, v90, v234
	v_sub_f32_e32 v91, v91, v234
	v_sub_f32_e32 v92, v92, v234
	v_sub_f32_e32 v93, v93, v234
	v_sub_f32_e32 v94, v94, v234
	v_sub_f32_e32 v95, v95, v234
	v_sub_f32_e32 v96, v96, v234
	v_sub_f32_e32 v97, v97, v234
	v_mul_f32_e32 v231, v231, v235
	v_mul_f32_e32 v232, v232, v235
	v_mul_f32_e32 v2, v2, v235
	v_mul_f32_e32 v3, v3, v235
	v_mul_f32_e32 v4, v4, v235
	v_mul_f32_e32 v5, v5, v235
	v_mul_f32_e32 v6, v6, v235
	v_mul_f32_e32 v7, v7, v235
	v_mul_f32_e32 v8, v8, v235
	v_mul_f32_e32 v9, v9, v235
	v_mul_f32_e32 v10, v10, v235
	v_mul_f32_e32 v11, v11, v235
	v_mul_f32_e32 v12, v12, v235
	v_mul_f32_e32 v13, v13, v235
	v_mul_f32_e32 v14, v14, v235
	v_mul_f32_e32 v15, v15, v235
	v_mul_f32_e32 v16, v16, v235
	v_mul_f32_e32 v17, v17, v235
	v_mul_f32_e32 v18, v18, v235
	v_mul_f32_e32 v19, v19, v235
	v_mul_f32_e32 v20, v20, v235
	v_mul_f32_e32 v21, v21, v235
	v_mul_f32_e32 v22, v22, v235
	v_mul_f32_e32 v23, v23, v235
	v_mul_f32_e32 v24, v24, v235
	v_mul_f32_e32 v25, v25, v235
	v_mul_f32_e32 v26, v26, v235
	v_mul_f32_e32 v27, v27, v235
	v_mul_f32_e32 v28, v28, v235
	v_mul_f32_e32 v29, v29, v235
	v_mul_f32_e32 v30, v30, v235
	v_mul_f32_e32 v31, v31, v235
	v_mul_f32_e32 v32, v32, v235
	v_mul_f32_e32 v33, v33, v235
	v_sub_f32_e32 v122, 0, v230
	v_mov_b32_e32 v123, v122
	v_mov_b32_e32 v124, v122
	v_mov_b32_e32 v125, v122
	v_mov_b32_e32 v126, v122
	v_mov_b32_e32 v127, v122
	v_mov_b32_e32 v128, v122
	v_mov_b32_e32 v129, v122
	v_mov_b32_e32 v130, v122
	v_mov_b32_e32 v131, v122
	v_mov_b32_e32 v132, v122
	v_mov_b32_e32 v133, v122
	v_mov_b32_e32 v134, v122
	v_mov_b32_e32 v135, v122
	v_mov_b32_e32 v136, v122
	v_mov_b32_e32 v137, v122
.Lmls_nr_t0:
	ds_read_b128 v[138:141], v220 offset:26624
	ds_read_b128 v[142:145], v220 offset:33280
	ds_read_b128 v[146:149], v220 offset:26656
	ds_read_b128 v[150:153], v220 offset:33312
	ds_read_b128 v[154:157], v220 offset:26688
	ds_read_b128 v[158:161], v220 offset:33344
	s_waitcnt lgkmcnt(6)
	s_barrier
	v_exp_f32_e32 v66, v66
	v_exp_f32_e32 v67, v67
	v_exp_f32_e32 v68, v68
	v_exp_f32_e32 v69, v69
	s_waitcnt lgkmcnt(4)
	v_mfma_f32_32x32x16_bf16 v[34:49], v[138:141], v[98:101], v[122:137]
	ds_read_b128 v[138:141], v220 offset:26720
	v_add_f32_e32 v231, v231, v66
	v_add_f32_e32 v232, v232, v67
	v_exp_f32_e32 v70, v70
	v_exp_f32_e32 v71, v71
	v_mfma_f32_32x32x16_bf16 v[50:65], v[142:145], v[98:101], v[122:137]
	ds_read_b128 v[142:145], v220 offset:33376
	v_add_f32_e32 v231, v231, v68
	v_add_f32_e32 v232, v232, v69
	v_exp_f32_e32 v72, v72
	v_exp_f32_e32 v73, v73
	s_waitcnt lgkmcnt(4)
	v_mfma_f32_32x32x16_bf16 v[34:49], v[146:149], v[102:105], v[34:49]
	ds_read_b128 v[146:149], v220 offset:26752
	v_add_f32_e32 v231, v231, v70
	v_add_f32_e32 v232, v232, v71
	v_add_f32_e32 v231, v231, v72
	v_add_f32_e32 v232, v232, v73
	v_cvt_pk_bf16_f32 v66, v66, v67
	v_cvt_pk_bf16_f32 v67, v68, v69
	v_mfma_f32_32x32x16_bf16 v[50:65], v[150:153], v[102:105], v[50:65]
	ds_read_b128 v[150:153], v220 offset:33408
	v_cvt_pk_bf16_f32 v68, v70, v71
	v_cvt_pk_bf16_f32 v69, v72, v73
	v_exp_f32_e32 v74, v74
	v_exp_f32_e32 v75, v75
	s_waitcnt lgkmcnt(4)
	v_mfma_f32_32x32x16_bf16 v[34:49], v[154:157], v[106:109], v[34:49]
	ds_read_b128 v[154:157], v220 offset:26784
	v_exp_f32_e32 v76, v76
	v_exp_f32_e32 v77, v77
	v_add_f32_e32 v231, v231, v74
	v_add_f32_e32 v232, v232, v75
	v_mfma_f32_32x32x16_bf16 v[50:65], v[158:161], v[106:109], v[50:65]
	ds_read_b128 v[158:161], v220 offset:33440
	v_exp_f32_e32 v78, v78
	v_exp_f32_e32 v79, v79
	v_add_f32_e32 v231, v231, v76
	v_add_f32_e32 v232, v232, v77
	v_exp_f32_e32 v80, v80
	s_waitcnt lgkmcnt(4)
	v_mfma_f32_32x32x16_bf16 v[34:49], v[138:141], v[110:113], v[34:49]
	ds_read_b128 v[162:165], v221 offset:9216
	v_exp_f32_e32 v81, v81
	v_add_f32_e32 v231, v231, v78
	v_add_f32_e32 v232, v232, v79
	v_add_f32_e32 v231, v231, v80
	v_mfma_f32_32x32x16_bf16 v[50:65], v[142:145], v[110:113], v[50:65]
	ds_read_b128 v[166:169], v221 offset:13824
	v_add_f32_e32 v232, v232, v81
	v_cvt_pk_bf16_f32 v74, v74, v75
	v_cvt_pk_bf16_f32 v75, v76, v77
	v_cvt_pk_bf16_f32 v76, v78, v79
	v_cvt_pk_bf16_f32 v77, v80, v81
	v_exp_f32_e32 v82, v82
	s_waitcnt lgkmcnt(4)
	v_mfma_f32_32x32x16_bf16 v[34:49], v[146:149], v[114:117], v[34:49]
	ds_read_b128 v[170:173], v221 offset:9248
	v_exp_f32_e32 v83, v83
	v_exp_f32_e32 v84, v84
	v_exp_f32_e32 v85, v85
	v_mfma_f32_32x32x16_bf16 v[50:65], v[150:153], v[114:117], v[50:65]
	ds_read_b128 v[174:177], v221 offset:13856
	v_add_f32_e32 v231, v231, v82
	v_add_f32_e32 v232, v232, v83
	v_exp_f32_e32 v86, v86
	v_exp_f32_e32 v87, v87
	s_waitcnt lgkmcnt(4)
	v_mfma_f32_32x32x16_bf16 v[34:49], v[154:157], v[118:121], v[34:49]
	ds_read_b128 v[180:183], v221 offset:9280
	v_add_f32_e32 v231, v231, v84
	v_add_f32_e32 v232, v232, v85
	v_exp_f32_e32 v88, v88
	v_exp_f32_e32 v89, v89
	v_mfma_f32_32x32x16_bf16 v[50:65], v[158:161], v[118:121], v[50:65]
	ds_read_b128 v[184:187], v221 offset:13888
	v_add_f32_e32 v231, v231, v86
	v_add_f32_e32 v232, v232, v87
	v_add_f32_e32 v231, v231, v88
	v_add_f32_e32 v232, v232, v89
	v_cvt_pk_bf16_f32 v82, v82, v83
	v_cvt_pk_bf16_f32 v83, v84, v85
	v_cvt_pk_bf16_f32 v84, v86, v87
	s_waitcnt lgkmcnt(4)
	v_mfma_f32_32x32x16_bf16 v[2:17], v[162:165], v[66:69], v[2:17]
	ds_read_b128 v[188:191], v221 offset:9312
	v_cvt_pk_bf16_f32 v85, v88, v89
	v_exp_f32_e32 v90, v90
	v_exp_f32_e32 v91, v91
	v_exp_f32_e32 v92, v92
	v_mfma_f32_32x32x16_bf16 v[18:33], v[166:169], v[66:69], v[18:33]
	ds_read_b128 v[192:195], v221 offset:13920
	v_exp_f32_e32 v93, v93
	v_add_f32_e32 v231, v231, v90
	v_add_f32_e32 v232, v232, v91
	v_exp_f32_e32 v94, v94
	s_waitcnt lgkmcnt(4)
	v_mfma_f32_32x32x16_bf16 v[2:17], v[170:173], v[74:77], v[2:17]
	v_exp_f32_e32 v95, v95
	v_add_f32_e32 v231, v231, v92
	v_add_f32_e32 v232, v232, v93
	v_exp_f32_e32 v96, v96
	v_mfma_f32_32x32x16_bf16 v[18:33], v[174:177], v[74:77], v[18:33]
	s_waitcnt vmcnt(0)
	ds_write_b64 v225, v[212:213] offset:27648
	ds_write_b64 v225, v[214:215] offset:27664
	v_exp_f32_e32 v97, v97
	v_add_f32_e32 v231, v231, v94
	v_add_f32_e32 v232, v232, v95
	v_add_f32_e32 v231, v231, v96
	v_add_f32_e32 v232, v232, v97
	s_waitcnt lgkmcnt(4)
	v_mfma_f32_32x32x16_bf16 v[2:17], v[180:183], v[82:85], v[2:17]
	v_cvt_pk_bf16_f32 v90, v90, v91
	v_cvt_pk_bf16_f32 v91, v92, v93
	v_cvt_pk_bf16_f32 v92, v94, v95
	v_cvt_pk_bf16_f32 v93, v96, v97
	v_max3_f32 v234, v34, v35, v36
	v_max3_f32 v235, v50, v51, v52
	v_mfma_f32_32x32x16_bf16 v[18:33], v[184:187], v[82:85], v[18:33]
	v_max3_f32 v234, v234, v37, v38
	v_max3_f32 v235, v235, v53, v54
	v_max3_f32 v234, v234, v39, v40
	v_max3_f32 v235, v235, v55, v56
	v_max3_f32 v234, v234, v41, v42
	v_max3_f32 v235, v235, v57, v58
	v_max3_f32 v234, v234, v43, v44
	s_waitcnt lgkmcnt(2)
	v_mfma_f32_32x32x16_bf16 v[2:17], v[188:191], v[90:93], v[2:17]
	v_max3_f32 v235, v235, v59, v60
	v_max3_f32 v234, v234, v45, v46
	v_max3_f32 v235, v235, v61, v62
	v_max3_f32 v234, v234, v47, v48
	v_max3_f32 v235, v235, v63, v64
	v_max3_f32 v234, v234, v49, v65
	v_mfma_f32_32x32x16_bf16 v[18:33], v[192:195], v[90:93], v[18:33]
	v_max_f32_e32 v234, v234, v235
	v_mov_b32_e32 v235, v234
	s_nop 1
	v_permlane32_swap_b32_e32 v234, v235
	v_max_f32_e32 v233, v234, v235
	v_cmp_lt_f32_e32 vcc, 4.0, v233
	s_cbranch_vccz .Lmls_nr_t1
	s_nop 15
	v_max_f32_e32 v234, 0, v233
	v_exp_f32_e64 v235, -v234
	v_add_f32_e32 v230, v230, v234
	v_sub_f32_e32 v34, v34, v234
	v_sub_f32_e32 v35, v35, v234
	v_sub_f32_e32 v36, v36, v234
	v_sub_f32_e32 v37, v37, v234
	v_sub_f32_e32 v38, v38, v234
	v_sub_f32_e32 v39, v39, v234
	v_sub_f32_e32 v40, v40, v234
	v_sub_f32_e32 v41, v41, v234
	v_sub_f32_e32 v42, v42, v234
	v_sub_f32_e32 v43, v43, v234
	v_sub_f32_e32 v44, v44, v234
	v_sub_f32_e32 v45, v45, v234
	v_sub_f32_e32 v46, v46, v234
	v_sub_f32_e32 v47, v47, v234
	v_sub_f32_e32 v48, v48, v234
	v_sub_f32_e32 v49, v49, v234
	v_sub_f32_e32 v50, v50, v234
	v_sub_f32_e32 v51, v51, v234
	v_sub_f32_e32 v52, v52, v234
	v_sub_f32_e32 v53, v53, v234
	v_sub_f32_e32 v54, v54, v234
	v_sub_f32_e32 v55, v55, v234
	v_sub_f32_e32 v56, v56, v234
	v_sub_f32_e32 v57, v57, v234
	v_sub_f32_e32 v58, v58, v234
	v_sub_f32_e32 v59, v59, v234
	v_sub_f32_e32 v60, v60, v234
	v_sub_f32_e32 v61, v61, v234
	v_sub_f32_e32 v62, v62, v234
	v_sub_f32_e32 v63, v63, v234
	v_sub_f32_e32 v64, v64, v234
	v_sub_f32_e32 v65, v65, v234
	v_mul_f32_e32 v231, v231, v235
	v_mul_f32_e32 v232, v232, v235
	v_mul_f32_e32 v2, v2, v235
	v_mul_f32_e32 v3, v3, v235
	v_mul_f32_e32 v4, v4, v235
	v_mul_f32_e32 v5, v5, v235
	v_mul_f32_e32 v6, v6, v235
	v_mul_f32_e32 v7, v7, v235
	v_mul_f32_e32 v8, v8, v235
	v_mul_f32_e32 v9, v9, v235
	v_mul_f32_e32 v10, v10, v235
	v_mul_f32_e32 v11, v11, v235
	v_mul_f32_e32 v12, v12, v235
	v_mul_f32_e32 v13, v13, v235
	v_mul_f32_e32 v14, v14, v235
	v_mul_f32_e32 v15, v15, v235
	v_mul_f32_e32 v16, v16, v235
	v_mul_f32_e32 v17, v17, v235
	v_mul_f32_e32 v18, v18, v235
	v_mul_f32_e32 v19, v19, v235
	v_mul_f32_e32 v20, v20, v235
	v_mul_f32_e32 v21, v21, v235
	v_mul_f32_e32 v22, v22, v235
	v_mul_f32_e32 v23, v23, v235
	v_mul_f32_e32 v24, v24, v235
	v_mul_f32_e32 v25, v25, v235
	v_mul_f32_e32 v26, v26, v235
	v_mul_f32_e32 v27, v27, v235
	v_mul_f32_e32 v28, v28, v235
	v_mul_f32_e32 v29, v29, v235
	v_mul_f32_e32 v30, v30, v235
	v_mul_f32_e32 v31, v31, v235
	v_mul_f32_e32 v32, v32, v235
	v_mul_f32_e32 v33, v33, v235
	v_sub_f32_e32 v122, 0, v230
	v_mov_b32_e32 v123, v122
	v_mov_b32_e32 v124, v122
	v_mov_b32_e32 v125, v122
	v_mov_b32_e32 v126, v122
	v_mov_b32_e32 v127, v122
	v_mov_b32_e32 v128, v122
	v_mov_b32_e32 v129, v122
	v_mov_b32_e32 v130, v122
	v_mov_b32_e32 v131, v122
	v_mov_b32_e32 v132, v122
	v_mov_b32_e32 v133, v122
	v_mov_b32_e32 v134, v122
	v_mov_b32_e32 v135, v122
	v_mov_b32_e32 v136, v122
	v_mov_b32_e32 v137, v122
.Lmls_nr_t1:
	ds_read_b128 v[138:141], v220 offset:39936
	ds_read_b128 v[142:145], v220 offset:46592
	ds_read_b128 v[146:149], v220 offset:39968
	ds_read_b128 v[150:153], v220 offset:46624
	ds_read_b128 v[154:157], v220 offset:40000
	ds_read_b128 v[158:161], v220 offset:46656
	s_waitcnt lgkmcnt(6)
	s_barrier
	global_load_dwordx2 v[200:201], v236, s[14:15] offset:0
	global_load_dwordx2 v[202:203], v236, s[14:15] offset:16
	global_load_dwordx2 v[204:205], v236, s[14:15] offset:32
	global_load_dwordx2 v[206:207], v236, s[14:15] offset:48
	global_load_dwordx2 v[208:209], v236, s[14:15] offset:64
	global_load_dwordx2 v[210:211], v236, s[14:15] offset:80
	global_load_dwordx2 v[212:213], v236, s[14:15] offset:96
	global_load_dwordx2 v[214:215], v236, s[14:15] offset:112
	v_exp_f32_e32 v34, v34
	v_exp_f32_e32 v35, v35
	v_exp_f32_e32 v36, v36
	v_exp_f32_e32 v37, v37
	s_waitcnt lgkmcnt(4)
	v_mfma_f32_32x32x16_bf16 v[66:81], v[138:141], v[98:101], v[122:137]
	ds_read_b128 v[138:141], v220 offset:40032
	v_add_f32_e32 v231, v231, v34
	v_add_f32_e32 v232, v232, v35
	v_exp_f32_e32 v38, v38
	v_exp_f32_e32 v39, v39
	v_mfma_f32_32x32x16_bf16 v[82:97], v[142:145], v[98:101], v[122:137]
	ds_read_b128 v[142:145], v220 offset:46688
	v_add_f32_e32 v231, v231, v36
	v_add_f32_e32 v232, v232, v37
	v_exp_f32_e32 v40, v40
	v_exp_f32_e32 v41, v41
	s_waitcnt lgkmcnt(4)
	v_mfma_f32_32x32x16_bf16 v[66:81], v[146:149], v[102:105], v[66:81]
	ds_read_b128 v[146:149], v220 offset:40064
	v_add_f32_e32 v231, v231, v38
	v_add_f32_e32 v232, v232, v39
	v_add_f32_e32 v231, v231, v40
	v_add_f32_e32 v232, v232, v41
	v_cvt_pk_bf16_f32 v34, v34, v35
	v_cvt_pk_bf16_f32 v35, v36, v37
	v_mfma_f32_32x32x16_bf16 v[82:97], v[150:153], v[102:105], v[82:97]
	ds_read_b128 v[150:153], v220 offset:46720
	v_cvt_pk_bf16_f32 v36, v38, v39
	v_cvt_pk_bf16_f32 v37, v40, v41
	v_exp_f32_e32 v42, v42
	v_exp_f32_e32 v43, v43
	s_waitcnt lgkmcnt(4)
	v_mfma_f32_32x32x16_bf16 v[66:81], v[154:157], v[106:109], v[66:81]
	ds_read_b128 v[154:157], v220 offset:40096
	v_exp_f32_e32 v44, v44
	v_exp_f32_e32 v45, v45
	v_add_f32_e32 v231, v231, v42
	v_add_f32_e32 v232, v232, v43
	v_mfma_f32_32x32x16_bf16 v[82:97], v[158:161], v[106:109], v[82:97]
	ds_read_b128 v[158:161], v220 offset:46752
	v_exp_f32_e32 v46, v46
	v_exp_f32_e32 v47, v47
	v_add_f32_e32 v231, v231, v44
	v_add_f32_e32 v232, v232, v45
	v_exp_f32_e32 v48, v48
	s_waitcnt lgkmcnt(4)
	v_mfma_f32_32x32x16_bf16 v[66:81], v[138:141], v[110:113], v[66:81]
	ds_read_b128 v[162:165], v221 offset:18432
	v_exp_f32_e32 v49, v49
	v_add_f32_e32 v231, v231, v46
	v_add_f32_e32 v232, v232, v47
	v_add_f32_e32 v231, v231, v48
	v_mfma_f32_32x32x16_bf16 v[82:97], v[142:145], v[110:113], v[82:97]
	ds_read_b128 v[166:169], v221 offset:23040
	v_add_f32_e32 v232, v232, v49
	v_cvt_pk_bf16_f32 v42, v42, v43
	v_cvt_pk_bf16_f32 v43, v44, v45
	v_cvt_pk_bf16_f32 v44, v46, v47
	v_cvt_pk_bf16_f32 v45, v48, v49
	v_exp_f32_e32 v50, v50
	s_waitcnt lgkmcnt(4)
	v_mfma_f32_32x32x16_bf16 v[66:81], v[146:149], v[114:117], v[66:81]
	ds_read_b128 v[170:173], v221 offset:18464
	v_exp_f32_e32 v51, v51
	v_exp_f32_e32 v52, v52
	v_exp_f32_e32 v53, v53
	v_mfma_f32_32x32x16_bf16 v[82:97], v[150:153], v[114:117], v[82:97]
	ds_read_b128 v[174:177], v221 offset:23072
	v_add_f32_e32 v231, v231, v50
	v_add_f32_e32 v232, v232, v51
	v_exp_f32_e32 v54, v54
	v_exp_f32_e32 v55, v55
	s_waitcnt lgkmcnt(4)
	v_mfma_f32_32x32x16_bf16 v[66:81], v[154:157], v[118:121], v[66:81]
	ds_read_b128 v[180:183], v221 offset:18496
	v_add_f32_e32 v231, v231, v52
	v_add_f32_e32 v232, v232, v53
	v_exp_f32_e32 v56, v56
	v_exp_f32_e32 v57, v57
	v_mfma_f32_32x32x16_bf16 v[82:97], v[158:161], v[118:121], v[82:97]
	ds_read_b128 v[184:187], v221 offset:23104
	v_add_f32_e32 v231, v231, v54
	v_add_f32_e32 v232, v232, v55
	v_add_f32_e32 v231, v231, v56
	v_add_f32_e32 v232, v232, v57
	v_cvt_pk_bf16_f32 v50, v50, v51
	v_cvt_pk_bf16_f32 v51, v52, v53
	v_cvt_pk_bf16_f32 v52, v54, v55
	s_waitcnt lgkmcnt(4)
	v_mfma_f32_32x32x16_bf16 v[2:17], v[162:165], v[34:37], v[2:17]
	ds_read_b128 v[188:191], v221 offset:18528
	v_cvt_pk_bf16_f32 v53, v56, v57
	v_exp_f32_e32 v58, v58
	v_exp_f32_e32 v59, v59
	v_exp_f32_e32 v60, v60
	v_mfma_f32_32x32x16_bf16 v[18:33], v[166:169], v[34:37], v[18:33]
	ds_read_b128 v[192:195], v221 offset:23136
	v_exp_f32_e32 v61, v61
	v_add_f32_e32 v231, v231, v58
	v_add_f32_e32 v232, v232, v59
	v_exp_f32_e32 v62, v62
	s_waitcnt lgkmcnt(4)
	v_mfma_f32_32x32x16_bf16 v[2:17], v[170:173], v[42:45], v[2:17]
	v_exp_f32_e32 v63, v63
	v_add_f32_e32 v231, v231, v60
	v_add_f32_e32 v232, v232, v61
	v_exp_f32_e32 v64, v64
	v_mfma_f32_32x32x16_bf16 v[18:33], v[174:177], v[42:45], v[18:33]
	v_exp_f32_e32 v65, v65
	v_add_f32_e32 v231, v231, v62
	v_add_f32_e32 v232, v232, v63
	v_add_f32_e32 v231, v231, v64
	v_add_f32_e32 v232, v232, v65
	s_waitcnt lgkmcnt(2)
	v_mfma_f32_32x32x16_bf16 v[2:17], v[180:183], v[50:53], v[2:17]
	v_cvt_pk_bf16_f32 v58, v58, v59
	v_cvt_pk_bf16_f32 v59, v60, v61
	v_cvt_pk_bf16_f32 v60, v62, v63
	v_cvt_pk_bf16_f32 v61, v64, v65
	v_max3_f32 v234, v66, v67, v68
	v_max3_f32 v235, v82, v83, v84
	v_mfma_f32_32x32x16_bf16 v[18:33], v[184:187], v[50:53], v[18:33]
	v_max3_f32 v234, v234, v69, v70
	v_max3_f32 v235, v235, v85, v86
	v_max3_f32 v234, v234, v71, v72
	v_max3_f32 v235, v235, v87, v88
	v_max3_f32 v234, v234, v73, v74
	v_max3_f32 v235, v235, v89, v90
	v_max3_f32 v234, v234, v75, v76
	s_waitcnt lgkmcnt(0)
	v_mfma_f32_32x32x16_bf16 v[2:17], v[188:191], v[58:61], v[2:17]
	v_max3_f32 v235, v235, v91, v92
	v_max3_f32 v234, v234, v77, v78
	v_max3_f32 v235, v235, v93, v94
	v_max3_f32 v234, v234, v79, v80
	v_max3_f32 v235, v235, v95, v96
	v_max3_f32 v234, v234, v81, v97
	v_mfma_f32_32x32x16_bf16 v[18:33], v[192:195], v[58:61], v[18:33]
	v_max_f32_e32 v234, v234, v235
	v_mov_b32_e32 v235, v234
	s_nop 1
	v_permlane32_swap_b32_e32 v234, v235
	v_max_f32_e32 v233, v234, v235
	v_cmp_lt_f32_e32 vcc, 4.0, v233
	s_cbranch_vccz .Lmls_nr_t2
	s_nop 15
	v_max_f32_e32 v234, 0, v233
	v_exp_f32_e64 v235, -v234
	v_add_f32_e32 v230, v230, v234
	v_sub_f32_e32 v66, v66, v234
	v_sub_f32_e32 v67, v67, v234
	v_sub_f32_e32 v68, v68, v234
	v_sub_f32_e32 v69, v69, v234
	v_sub_f32_e32 v70, v70, v234
	v_sub_f32_e32 v71, v71, v234
	v_sub_f32_e32 v72, v72, v234
	v_sub_f32_e32 v73, v73, v234
	v_sub_f32_e32 v74, v74, v234
	v_sub_f32_e32 v75, v75, v234
	v_sub_f32_e32 v76, v76, v234
	v_sub_f32_e32 v77, v77, v234
	v_sub_f32_e32 v78, v78, v234
	v_sub_f32_e32 v79, v79, v234
	v_sub_f32_e32 v80, v80, v234
	v_sub_f32_e32 v81, v81, v234
	v_sub_f32_e32 v82, v82, v234
	v_sub_f32_e32 v83, v83, v234
	v_sub_f32_e32 v84, v84, v234
	v_sub_f32_e32 v85, v85, v234
	v_sub_f32_e32 v86, v86, v234
	v_sub_f32_e32 v87, v87, v234
	v_sub_f32_e32 v88, v88, v234
	v_sub_f32_e32 v89, v89, v234
	v_sub_f32_e32 v90, v90, v234
	v_sub_f32_e32 v91, v91, v234
	v_sub_f32_e32 v92, v92, v234
	v_sub_f32_e32 v93, v93, v234
	v_sub_f32_e32 v94, v94, v234
	v_sub_f32_e32 v95, v95, v234
	v_sub_f32_e32 v96, v96, v234
	v_sub_f32_e32 v97, v97, v234
	v_mul_f32_e32 v231, v231, v235
	v_mul_f32_e32 v232, v232, v235
	v_mul_f32_e32 v2, v2, v235
	v_mul_f32_e32 v3, v3, v235
	v_mul_f32_e32 v4, v4, v235
	v_mul_f32_e32 v5, v5, v235
	v_mul_f32_e32 v6, v6, v235
	v_mul_f32_e32 v7, v7, v235
	v_mul_f32_e32 v8, v8, v235
	v_mul_f32_e32 v9, v9, v235
	v_mul_f32_e32 v10, v10, v235
	v_mul_f32_e32 v11, v11, v235
	v_mul_f32_e32 v12, v12, v235
	v_mul_f32_e32 v13, v13, v235
	v_mul_f32_e32 v14, v14, v235
	v_mul_f32_e32 v15, v15, v235
	v_mul_f32_e32 v16, v16, v235
	v_mul_f32_e32 v17, v17, v235
	v_mul_f32_e32 v18, v18, v235
	v_mul_f32_e32 v19, v19, v235
	v_mul_f32_e32 v20, v20, v235
	v_mul_f32_e32 v21, v21, v235
	v_mul_f32_e32 v22, v22, v235
	v_mul_f32_e32 v23, v23, v235
	v_mul_f32_e32 v24, v24, v235
	v_mul_f32_e32 v25, v25, v235
	v_mul_f32_e32 v26, v26, v235
	v_mul_f32_e32 v27, v27, v235
	v_mul_f32_e32 v28, v28, v235
	v_mul_f32_e32 v29, v29, v235
	v_mul_f32_e32 v30, v30, v235
	v_mul_f32_e32 v31, v31, v235
	v_mul_f32_e32 v32, v32, v235
	v_mul_f32_e32 v33, v33, v235
	v_sub_f32_e32 v122, 0, v230
	v_mov_b32_e32 v123, v122
	v_mov_b32_e32 v124, v122
	v_mov_b32_e32 v125, v122
	v_mov_b32_e32 v126, v122
	v_mov_b32_e32 v127, v122
	v_mov_b32_e32 v128, v122
	v_mov_b32_e32 v129, v122
	v_mov_b32_e32 v130, v122
	v_mov_b32_e32 v131, v122
	v_mov_b32_e32 v132, v122
	v_mov_b32_e32 v133, v122
	v_mov_b32_e32 v134, v122
	v_mov_b32_e32 v135, v122
	v_mov_b32_e32 v136, v122
	v_mov_b32_e32 v137, v122
.Lmls_nr_t2:
	s_waitcnt lgkmcnt(0)
	s_barrier
	ds_read_b128 v[162:165], v221 offset:27648
	ds_read_b128 v[166:169], v221 offset:32256
	ds_read_b128 v[170:173], v221 offset:27680
	v_exp_f32_e32 v66, v66
	v_exp_f32_e32 v67, v67
	v_exp_f32_e32 v68, v68
	v_exp_f32_e32 v69, v69
	v_add_f32_e32 v231, v231, v66
	v_add_f32_e32 v232, v232, v67
	v_exp_f32_e32 v70, v70
	v_exp_f32_e32 v71, v71
	v_add_f32_e32 v231, v231, v68
	v_add_f32_e32 v232, v232, v69
	v_exp_f32_e32 v72, v72
	v_exp_f32_e32 v73, v73
	v_add_f32_e32 v231, v231, v70
	v_add_f32_e32 v232, v232, v71
	v_add_f32_e32 v231, v231, v72
	v_add_f32_e32 v232, v232, v73
	v_cvt_pk_bf16_f32 v66, v66, v67
	v_cvt_pk_bf16_f32 v67, v68, v69
	v_cvt_pk_bf16_f32 v68, v70, v71
	v_cvt_pk_bf16_f32 v69, v72, v73
	s_waitcnt lgkmcnt(1)
	s_nop 0
	v_mfma_f32_32x32x16_bf16 v[2:17], v[162:165], v[66:69], v[2:17]
	ds_read_b128 v[174:177], v221 offset:32288
	v_mfma_f32_32x32x16_bf16 v[18:33], v[166:169], v[66:69], v[18:33]
	ds_read_b128 v[180:183], v221 offset:27712
	v_exp_f32_e32 v74, v74
	v_exp_f32_e32 v75, v75
	v_exp_f32_e32 v76, v76
	v_exp_f32_e32 v77, v77
	v_add_f32_e32 v231, v231, v74
	v_add_f32_e32 v232, v232, v75
	v_exp_f32_e32 v78, v78
	v_exp_f32_e32 v79, v79
	v_add_f32_e32 v231, v231, v76
	v_add_f32_e32 v232, v232, v77
	v_exp_f32_e32 v80, v80
	v_exp_f32_e32 v81, v81
	v_add_f32_e32 v231, v231, v78
	v_add_f32_e32 v232, v232, v79
	v_add_f32_e32 v231, v231, v80
	v_add_f32_e32 v232, v232, v81
	v_cvt_pk_bf16_f32 v74, v74, v75
	v_cvt_pk_bf16_f32 v75, v76, v77
	v_cvt_pk_bf16_f32 v76, v78, v79
	v_cvt_pk_bf16_f32 v77, v80, v81
	s_waitcnt lgkmcnt(1)
	s_nop 0
	v_mfma_f32_32x32x16_bf16 v[2:17], v[170:173], v[74:77], v[2:17]
	ds_read_b128 v[184:187], v221 offset:32320
	v_mfma_f32_32x32x16_bf16 v[18:33], v[174:177], v[74:77], v[18:33]
	ds_read_b128 v[188:191], v221 offset:27744
	v_exp_f32_e32 v82, v82
	v_exp_f32_e32 v83, v83
	v_exp_f32_e32 v84, v84
	v_exp_f32_e32 v85, v85
	v_add_f32_e32 v231, v231, v82
	v_add_f32_e32 v232, v232, v83
	v_exp_f32_e32 v86, v86
	v_exp_f32_e32 v87, v87
	v_add_f32_e32 v231, v231, v84
	v_add_f32_e32 v232, v232, v85
	v_exp_f32_e32 v88, v88
	v_exp_f32_e32 v89, v89
	v_add_f32_e32 v231, v231, v86
	v_add_f32_e32 v232, v232, v87
	v_add_f32_e32 v231, v231, v88
	v_add_f32_e32 v232, v232, v89
	v_cvt_pk_bf16_f32 v82, v82, v83
	v_cvt_pk_bf16_f32 v83, v84, v85
	v_cvt_pk_bf16_f32 v84, v86, v87
	v_cvt_pk_bf16_f32 v85, v88, v89
	s_waitcnt lgkmcnt(1)
	s_nop 0
	v_mfma_f32_32x32x16_bf16 v[2:17], v[180:183], v[82:85], v[2:17]
	ds_read_b128 v[192:195], v221 offset:32352
	v_mfma_f32_32x32x16_bf16 v[18:33], v[184:187], v[82:85], v[18:33]
	v_exp_f32_e32 v90, v90
	v_exp_f32_e32 v91, v91
	v_exp_f32_e32 v92, v92
	v_exp_f32_e32 v93, v93
	v_add_f32_e32 v231, v231, v90
	v_add_f32_e32 v232, v232, v91
	v_exp_f32_e32 v94, v94
	v_exp_f32_e32 v95, v95
	v_add_f32_e32 v231, v231, v92
	v_add_f32_e32 v232, v232, v93
	v_exp_f32_e32 v96, v96
	v_exp_f32_e32 v97, v97
	v_add_f32_e32 v231, v231, v94
	v_add_f32_e32 v232, v232, v95
	v_add_f32_e32 v231, v231, v96
	v_add_f32_e32 v232, v232, v97
	v_cvt_pk_bf16_f32 v90, v90, v91
	v_cvt_pk_bf16_f32 v91, v92, v93
	v_cvt_pk_bf16_f32 v92, v94, v95
	v_cvt_pk_bf16_f32 v93, v96, v97
	s_waitcnt lgkmcnt(0)
	s_nop 0
	v_mfma_f32_32x32x16_bf16 v[2:17], v[188:191], v[90:93], v[2:17]
	v_mfma_f32_32x32x16_bf16 v[18:33], v[192:195], v[90:93], v[18:33]
	s_waitcnt lgkmcnt(0)
	s_barrier
	v_add_f32_e32 v231, v231, v232
	v_mov_b32_e32 v235, v231
	s_nop 1
	v_permlane32_swap_b32_e32 v231, v235
	v_add_f32_e32 v234, v231, v235
	v_div_scale_f32 v235, s[22:23], v234, v234, 1.0
	v_rcp_f32_e32 v179, v235
	v_div_scale_f32 v196, vcc, 1.0, v234, 1.0
	v_fma_f32 v197, -v235, v179, 1.0
	v_fmac_f32_e32 v179, v197, v179
	v_mul_f32_e32 v197, v196, v179
	v_fma_f32 v199, -v235, v197, v196
	v_fmac_f32_e32 v197, v199, v179
	v_fma_f32 v235, -v235, v197, v196
	v_div_fmas_f32 v235, v235, v179, v197
	v_div_fixup_f32 v234, v235, v234, 1.0
	s_nop 15
	v_mul_f32_e32 v2, v2, v234
	v_mul_f32_e32 v3, v3, v234
	v_mul_f32_e32 v4, v4, v234
	v_mul_f32_e32 v5, v5, v234
	v_mul_f32_e32 v6, v6, v234
	v_mul_f32_e32 v7, v7, v234
	v_mul_f32_e32 v8, v8, v234
	v_mul_f32_e32 v9, v9, v234
	v_mul_f32_e32 v10, v10, v234
	v_mul_f32_e32 v11, v11, v234
	v_mul_f32_e32 v12, v12, v234
	v_mul_f32_e32 v13, v13, v234
	v_mul_f32_e32 v14, v14, v234
	v_mul_f32_e32 v15, v15, v234
	v_mul_f32_e32 v16, v16, v234
	v_mul_f32_e32 v17, v17, v234
	v_mul_f32_e32 v18, v18, v234
	v_mul_f32_e32 v19, v19, v234
	v_mul_f32_e32 v20, v20, v234
	v_mul_f32_e32 v21, v21, v234
	v_mul_f32_e32 v22, v22, v234
	v_mul_f32_e32 v23, v23, v234
	v_mul_f32_e32 v24, v24, v234
	v_mul_f32_e32 v25, v25, v234
	v_mul_f32_e32 v26, v26, v234
	v_mul_f32_e32 v27, v27, v234
	v_mul_f32_e32 v28, v28, v234
	v_mul_f32_e32 v29, v29, v234
	v_mul_f32_e32 v30, v30, v234
	v_mul_f32_e32 v31, v31, v234
	v_mul_f32_e32 v32, v32, v234
	v_mul_f32_e32 v33, v33, v234
	s_waitcnt vmcnt(0)
	v_lshlrev_b32_e32 v179, 16, v200
	v_and_b32_e32 v196, 0xffff0000, v200
	v_lshlrev_b32_e32 v197, 16, v201
	v_and_b32_e32 v199, 0xffff0000, v201
	v_mul_f32_e32 v2, v2, v179
	v_mul_f32_e32 v3, v3, v196
	v_mul_f32_e32 v4, v4, v197
	v_mul_f32_e32 v5, v5, v199
	v_cvt_pk_bf16_f32 v200, v2, v3
	v_cvt_pk_bf16_f32 v201, v4, v5
	global_store_dwordx2 v236, v[200:201], s[14:15] offset:0
	v_lshlrev_b32_e32 v179, 16, v202
	v_and_b32_e32 v196, 0xffff0000, v202
	v_lshlrev_b32_e32 v197, 16, v203
	v_and_b32_e32 v199, 0xffff0000, v203
	v_mul_f32_e32 v6, v6, v179
	v_mul_f32_e32 v7, v7, v196
	v_mul_f32_e32 v8, v8, v197
	v_mul_f32_e32 v9, v9, v199
	v_cvt_pk_bf16_f32 v202, v6, v7
	v_cvt_pk_bf16_f32 v203, v8, v9
	global_store_dwordx2 v236, v[202:203], s[14:15] offset:16
	v_lshlrev_b32_e32 v179, 16, v204
	v_and_b32_e32 v196, 0xffff0000, v204
	v_lshlrev_b32_e32 v197, 16, v205
	v_and_b32_e32 v199, 0xffff0000, v205
	v_mul_f32_e32 v10, v10, v179
	v_mul_f32_e32 v11, v11, v196
	v_mul_f32_e32 v12, v12, v197
	v_mul_f32_e32 v13, v13, v199
	v_cvt_pk_bf16_f32 v204, v10, v11
	v_cvt_pk_bf16_f32 v205, v12, v13
	global_store_dwordx2 v236, v[204:205], s[14:15] offset:32
	v_lshlrev_b32_e32 v179, 16, v206
	v_and_b32_e32 v196, 0xffff0000, v206
	v_lshlrev_b32_e32 v197, 16, v207
	v_and_b32_e32 v199, 0xffff0000, v207
	v_mul_f32_e32 v14, v14, v179
	v_mul_f32_e32 v15, v15, v196
	v_mul_f32_e32 v16, v16, v197
	v_mul_f32_e32 v17, v17, v199
	v_cvt_pk_bf16_f32 v206, v14, v15
	v_cvt_pk_bf16_f32 v207, v16, v17
	global_store_dwordx2 v236, v[206:207], s[14:15] offset:48
	v_lshlrev_b32_e32 v179, 16, v208
	v_and_b32_e32 v196, 0xffff0000, v208
	v_lshlrev_b32_e32 v197, 16, v209
	v_and_b32_e32 v199, 0xffff0000, v209
	v_mul_f32_e32 v18, v18, v179
	v_mul_f32_e32 v19, v19, v196
	v_mul_f32_e32 v20, v20, v197
	v_mul_f32_e32 v21, v21, v199
	v_cvt_pk_bf16_f32 v208, v18, v19
	v_cvt_pk_bf16_f32 v209, v20, v21
	global_store_dwordx2 v236, v[208:209], s[14:15] offset:64
	v_lshlrev_b32_e32 v179, 16, v210
	v_and_b32_e32 v196, 0xffff0000, v210
	v_lshlrev_b32_e32 v197, 16, v211
	v_and_b32_e32 v199, 0xffff0000, v211
	v_mul_f32_e32 v22, v22, v179
	v_mul_f32_e32 v23, v23, v196
	v_mul_f32_e32 v24, v24, v197
	v_mul_f32_e32 v25, v25, v199
	v_cvt_pk_bf16_f32 v210, v22, v23
	v_cvt_pk_bf16_f32 v211, v24, v25
	global_store_dwordx2 v236, v[210:211], s[14:15] offset:80
	v_lshlrev_b32_e32 v179, 16, v212
	v_and_b32_e32 v196, 0xffff0000, v212
	v_lshlrev_b32_e32 v197, 16, v213
	v_and_b32_e32 v199, 0xffff0000, v213
	v_mul_f32_e32 v26, v26, v179
	v_mul_f32_e32 v27, v27, v196
	v_mul_f32_e32 v28, v28, v197
	v_mul_f32_e32 v29, v29, v199
	v_cvt_pk_bf16_f32 v212, v26, v27
	v_cvt_pk_bf16_f32 v213, v28, v29
	global_store_dwordx2 v236, v[212:213], s[14:15] offset:96
	v_lshlrev_b32_e32 v179, 16, v214
	v_and_b32_e32 v196, 0xffff0000, v214
	v_lshlrev_b32_e32 v197, 16, v215
	v_and_b32_e32 v199, 0xffff0000, v215
	v_mul_f32_e32 v30, v30, v179
	v_mul_f32_e32 v31, v31, v196
	v_mul_f32_e32 v32, v32, v197
	v_mul_f32_e32 v33, v33, v199
	v_cvt_pk_bf16_f32 v214, v30, v31
	v_cvt_pk_bf16_f32 v215, v32, v33
	global_store_dwordx2 v236, v[214:215], s[14:15] offset:112
	s_add_i32 s2, s2, s88
	s_cmpk_lt_i32 s2, 0x200
	s_cbranch_scc1 .Lmla_restart
